# MFMA snake order over merged 32-MFMA sub-phase blocks (every consecutive MFMA shares accumulator or an operand), mid-block setprio toggle removed
# speedup vs baseline: 1.0145x; 1.0051x over previous
.LBB0_142:
	ds_read_b128 v[168:171], v165
	ds_read_b128 v[172:175], v165 offset:1024
	ds_read_b128 v[176:179], v165 offset:2048
	ds_read_b128 v[180:183], v165 offset:3072
	ds_read_b128 v[184:187], v166
	ds_read_b128 v[188:191], v166 offset:1024
	ds_read_b128 v[192:195], v166 offset:2048
	ds_read_b128 v[196:199], v166 offset:3072
	s_add_i32 s54, s22, 2
	s_add_u32 s55, s20, 0x80
	s_addc_u32 s23, s21, 0
	s_cmp_eq_u32 s42, s22
	s_cselect_b32 s22, s4, s55
	s_cselect_b32 s23, s5, s23
	s_cselect_b32 s61, s19, s53
	s_cselect_b32 s60, s18, s52
	v_lshl_add_u64 v[234:235], s[20:21], 0, v[154:155]
	s_add_i32 m0, s31, 0xc000
	ds_read_b128 v[200:203], v167
	ds_read_b128 v[204:207], v167 offset:1024
	ds_read_b128 v[208:211], v167 offset:2048
	ds_read_b128 v[212:215], v167 offset:3072
	ds_read_b128 v[216:219], v167 offset:4096
	ds_read_b128 v[222:225], v167 offset:5120
	ds_read_b128 v[226:229], v167 offset:6144
	ds_read_b128 v[230:233], v167 offset:7168
	global_load_lds_dwordx4 v[234:235], off
	v_lshl_add_u64 v[234:235], s[20:21], 0, v[156:157]
	s_add_i32 m0, s31, 0xe000
	s_nop 0
	global_load_lds_dwordx4 v[234:235], off
	s_waitcnt vmcnt(8)
	s_waitcnt lgkmcnt(0)
	s_barrier
	s_setprio 1
	s_waitcnt lgkmcnt(0)
	v_mfma_f32_16x16x32_bf16 v[120:123], v[168:171], v[200:203], v[120:123]
	v_mfma_f32_16x16x32_bf16 v[120:123], v[172:175], v[204:207], v[120:123]
	v_mfma_f32_16x16x32_bf16 v[116:119], v[180:183], v[204:207], v[116:119]
	v_mfma_f32_16x16x32_bf16 v[116:119], v[176:179], v[200:203], v[116:119]
	v_mfma_f32_16x16x32_bf16 v[124:127], v[184:187], v[200:203], v[124:127]
	v_mfma_f32_16x16x32_bf16 v[124:127], v[188:191], v[204:207], v[124:127]
	v_mfma_f32_16x16x32_bf16 v[112:115], v[196:199], v[204:207], v[112:115]
	v_mfma_f32_16x16x32_bf16 v[112:115], v[192:195], v[200:203], v[112:115]
	v_mfma_f32_16x16x32_bf16 v[96:99], v[192:195], v[208:211], v[96:99]
	v_mfma_f32_16x16x32_bf16 v[96:99], v[196:199], v[212:215], v[96:99]
	v_mfma_f32_16x16x32_bf16 v[104:107], v[188:191], v[212:215], v[104:107]
	v_mfma_f32_16x16x32_bf16 v[104:107], v[184:187], v[208:211], v[104:107]
	v_mfma_f32_16x16x32_bf16 v[100:103], v[176:179], v[208:211], v[100:103]
	v_mfma_f32_16x16x32_bf16 v[100:103], v[180:183], v[212:215], v[100:103]
	v_mfma_f32_16x16x32_bf16 v[108:111], v[172:175], v[212:215], v[108:111]
	v_mfma_f32_16x16x32_bf16 v[108:111], v[168:171], v[208:211], v[108:111]
	v_mfma_f32_16x16x32_bf16 v[92:95], v[168:171], v[216:219], v[92:95]
	v_mfma_f32_16x16x32_bf16 v[92:95], v[172:175], v[222:225], v[92:95]
	v_mfma_f32_16x16x32_bf16 v[84:87], v[180:183], v[222:225], v[84:87]
	v_mfma_f32_16x16x32_bf16 v[84:87], v[176:179], v[216:219], v[84:87]
	v_mfma_f32_16x16x32_bf16 v[88:91], v[184:187], v[216:219], v[88:91]
	v_mfma_f32_16x16x32_bf16 v[88:91], v[188:191], v[222:225], v[88:91]
	v_mfma_f32_16x16x32_bf16 v[80:83], v[196:199], v[222:225], v[80:83]
	v_mfma_f32_16x16x32_bf16 v[80:83], v[192:195], v[216:219], v[80:83]
	v_mfma_f32_16x16x32_bf16 v[64:67], v[192:195], v[226:229], v[64:67]
	v_mfma_f32_16x16x32_bf16 v[64:67], v[196:199], v[230:233], v[64:67]
	v_mfma_f32_16x16x32_bf16 v[72:75], v[188:191], v[230:233], v[72:75]
	v_mfma_f32_16x16x32_bf16 v[72:75], v[184:187], v[226:229], v[72:75]
	v_mfma_f32_16x16x32_bf16 v[68:71], v[176:179], v[226:229], v[68:71]
	v_mfma_f32_16x16x32_bf16 v[68:71], v[180:183], v[230:233], v[68:71]
	v_mfma_f32_16x16x32_bf16 v[76:79], v[172:175], v[230:233], v[76:79]
	v_mfma_f32_16x16x32_bf16 v[76:79], v[168:171], v[226:229], v[76:79]
	s_setprio 0
	s_barrier
	s_add_i32 s55, s46, s28
	v_lshl_add_u64 v[234:235], s[60:61], 0, v[132:133]
	s_mov_b32 m0, s55
	ds_read_b128 v[200:203], v167 offset:16384
	ds_read_b128 v[204:207], v167 offset:17408
	ds_read_b128 v[208:211], v167 offset:18432
	ds_read_b128 v[212:215], v167 offset:19456
	ds_read_b128 v[216:219], v167 offset:20480
	ds_read_b128 v[222:225], v167 offset:21504
	ds_read_b128 v[226:229], v167 offset:22528
	ds_read_b128 v[230:233], v167 offset:23552
	global_load_lds_dwordx4 v[234:235], off
	s_add_i32 m0, s55, 0x2000
	v_lshl_add_u64 v[236:237], s[60:61], 0, v[128:129]
	s_add_u32 s60, s60, s10
	s_addc_u32 s61, s61, s11
	s_add_i32 s55, s47, s28
	global_load_lds_dwordx4 v[236:237], off
	v_lshl_add_u64 v[238:239], s[60:61], 0, v[132:133]
	s_mov_b32 m0, s55
	v_lshl_add_u64 v[240:241], s[60:61], 0, v[128:129]
	global_load_lds_dwordx4 v[238:239], off
	s_add_i32 m0, s55, 0x2000
	v_lshl_add_u64 v[242:243], s[22:23], 0, v[134:135]
	global_load_lds_dwordx4 v[240:241], off
	s_mov_b32 m0, s31
	v_lshl_add_u64 v[244:245], s[22:23], 0, v[130:131]
	global_load_lds_dwordx4 v[242:243], off
	s_mov_b32 m0, s33
	s_nop 0
	global_load_lds_dwordx4 v[244:245], off
	s_waitcnt vmcnt(8)
	s_waitcnt lgkmcnt(0)
	s_barrier
	s_setprio 1
	s_waitcnt lgkmcnt(0)
	v_mfma_f32_16x16x32_bf16 v[60:63], v[168:171], v[200:203], v[60:63]
	v_mfma_f32_16x16x32_bf16 v[60:63], v[172:175], v[204:207], v[60:63]
	v_mfma_f32_16x16x32_bf16 v[52:55], v[180:183], v[204:207], v[52:55]
	v_mfma_f32_16x16x32_bf16 v[52:55], v[176:179], v[200:203], v[52:55]
	v_mfma_f32_16x16x32_bf16 v[56:59], v[184:187], v[200:203], v[56:59]
	v_mfma_f32_16x16x32_bf16 v[56:59], v[188:191], v[204:207], v[56:59]
	v_mfma_f32_16x16x32_bf16 v[48:51], v[196:199], v[204:207], v[48:51]
	v_mfma_f32_16x16x32_bf16 v[48:51], v[192:195], v[200:203], v[48:51]
	v_mfma_f32_16x16x32_bf16 v[32:35], v[192:195], v[208:211], v[32:35]
	v_mfma_f32_16x16x32_bf16 v[32:35], v[196:199], v[212:215], v[32:35]
	v_mfma_f32_16x16x32_bf16 v[40:43], v[188:191], v[212:215], v[40:43]
	v_mfma_f32_16x16x32_bf16 v[40:43], v[184:187], v[208:211], v[40:43]
	v_mfma_f32_16x16x32_bf16 v[36:39], v[176:179], v[208:211], v[36:39]
	v_mfma_f32_16x16x32_bf16 v[36:39], v[180:183], v[212:215], v[36:39]
	v_mfma_f32_16x16x32_bf16 v[44:47], v[172:175], v[212:215], v[44:47]
	v_mfma_f32_16x16x32_bf16 v[44:47], v[168:171], v[208:211], v[44:47]
	v_mfma_f32_16x16x32_bf16 v[28:31], v[168:171], v[216:219], v[28:31]
	v_mfma_f32_16x16x32_bf16 v[28:31], v[172:175], v[222:225], v[28:31]
	v_mfma_f32_16x16x32_bf16 v[20:23], v[180:183], v[222:225], v[20:23]
	v_mfma_f32_16x16x32_bf16 v[20:23], v[176:179], v[216:219], v[20:23]
	v_mfma_f32_16x16x32_bf16 v[24:27], v[184:187], v[216:219], v[24:27]
	v_mfma_f32_16x16x32_bf16 v[24:27], v[188:191], v[222:225], v[24:27]
	v_mfma_f32_16x16x32_bf16 v[16:19], v[196:199], v[222:225], v[16:19]
	v_mfma_f32_16x16x32_bf16 v[16:19], v[192:195], v[216:219], v[16:19]
	v_mfma_f32_16x16x32_bf16 v[0:3], v[192:195], v[226:229], v[0:3]
	v_mfma_f32_16x16x32_bf16 v[0:3], v[196:199], v[230:233], v[0:3]
	v_mfma_f32_16x16x32_bf16 v[8:11], v[188:191], v[230:233], v[8:11]
	v_mfma_f32_16x16x32_bf16 v[8:11], v[184:187], v[226:229], v[8:11]
	v_mfma_f32_16x16x32_bf16 v[4:7], v[176:179], v[226:229], v[4:7]
	v_mfma_f32_16x16x32_bf16 v[4:7], v[180:183], v[230:233], v[4:7]
	v_mfma_f32_16x16x32_bf16 v[12:15], v[172:175], v[230:233], v[12:15]
	v_mfma_f32_16x16x32_bf16 v[12:15], v[168:171], v[226:229], v[12:15]
	s_setprio 0
	s_barrier
	s_add_i32 s55, 0, 0x18000
	s_add_i32 s60, 0, 0x1c000
	v_add_u32_e32 v180, s55, v164
	v_add_u32_e32 v196, s60, v164
	ds_read_b128 v[168:171], v180
	ds_read_b128 v[172:175], v180 offset:1024
	ds_read_b128 v[176:179], v180 offset:2048
	ds_read_b128 v[180:183], v180 offset:3072
	ds_read_b128 v[184:187], v196
	ds_read_b128 v[188:191], v196 offset:1024
	ds_read_b128 v[192:195], v196 offset:2048
	ds_read_b128 v[196:199], v196 offset:3072
	s_add_u32 s22, s22, s10
	s_addc_u32 s23, s23, s11
	s_mov_b32 m0, s34
	v_lshl_add_u64 v[246:247], s[22:23], 0, v[134:135]
	ds_read_b128 v[200:203], v167 offset:32768
	ds_read_b128 v[204:207], v167 offset:33792
	ds_read_b128 v[208:211], v167 offset:34816
	ds_read_b128 v[212:215], v167 offset:35840
	ds_read_b128 v[216:219], v167 offset:36864
	ds_read_b128 v[222:225], v167 offset:37888
	ds_read_b128 v[226:229], v167 offset:38912
	ds_read_b128 v[230:233], v167 offset:39936
	global_load_lds_dwordx4 v[246:247], off
	v_lshl_add_u64 v[246:247], s[22:23], 0, v[130:131]
	s_mov_b32 m0, s35
	s_nop 0
	global_load_lds_dwordx4 v[246:247], off
	s_waitcnt vmcnt(8)
	s_waitcnt lgkmcnt(0)
	s_barrier
	s_setprio 1
	s_waitcnt lgkmcnt(0)
	v_mfma_f32_16x16x32_bf16 v[120:123], v[168:171], v[200:203], v[120:123]
	v_mfma_f32_16x16x32_bf16 v[120:123], v[172:175], v[204:207], v[120:123]
	v_mfma_f32_16x16x32_bf16 v[116:119], v[180:183], v[204:207], v[116:119]
	v_mfma_f32_16x16x32_bf16 v[116:119], v[176:179], v[200:203], v[116:119]
	v_mfma_f32_16x16x32_bf16 v[124:127], v[184:187], v[200:203], v[124:127]
	v_mfma_f32_16x16x32_bf16 v[124:127], v[188:191], v[204:207], v[124:127]
	v_mfma_f32_16x16x32_bf16 v[112:115], v[196:199], v[204:207], v[112:115]
	v_mfma_f32_16x16x32_bf16 v[112:115], v[192:195], v[200:203], v[112:115]
	v_mfma_f32_16x16x32_bf16 v[96:99], v[192:195], v[208:211], v[96:99]
	v_mfma_f32_16x16x32_bf16 v[96:99], v[196:199], v[212:215], v[96:99]
	v_mfma_f32_16x16x32_bf16 v[104:107], v[188:191], v[212:215], v[104:107]
	v_mfma_f32_16x16x32_bf16 v[104:107], v[184:187], v[208:211], v[104:107]
	v_mfma_f32_16x16x32_bf16 v[100:103], v[176:179], v[208:211], v[100:103]
	v_mfma_f32_16x16x32_bf16 v[100:103], v[180:183], v[212:215], v[100:103]
	v_mfma_f32_16x16x32_bf16 v[108:111], v[172:175], v[212:215], v[108:111]
	v_mfma_f32_16x16x32_bf16 v[108:111], v[168:171], v[208:211], v[108:111]
	v_mfma_f32_16x16x32_bf16 v[92:95], v[168:171], v[216:219], v[92:95]
	v_mfma_f32_16x16x32_bf16 v[92:95], v[172:175], v[222:225], v[92:95]
	v_mfma_f32_16x16x32_bf16 v[84:87], v[180:183], v[222:225], v[84:87]
	v_mfma_f32_16x16x32_bf16 v[84:87], v[176:179], v[216:219], v[84:87]
	v_mfma_f32_16x16x32_bf16 v[88:91], v[184:187], v[216:219], v[88:91]
	v_mfma_f32_16x16x32_bf16 v[88:91], v[188:191], v[222:225], v[88:91]
	v_mfma_f32_16x16x32_bf16 v[80:83], v[196:199], v[222:225], v[80:83]
	v_mfma_f32_16x16x32_bf16 v[80:83], v[192:195], v[216:219], v[80:83]
	v_mfma_f32_16x16x32_bf16 v[64:67], v[192:195], v[226:229], v[64:67]
	v_mfma_f32_16x16x32_bf16 v[64:67], v[196:199], v[230:233], v[64:67]
	v_mfma_f32_16x16x32_bf16 v[72:75], v[188:191], v[230:233], v[72:75]
	v_mfma_f32_16x16x32_bf16 v[72:75], v[184:187], v[226:229], v[72:75]
	v_mfma_f32_16x16x32_bf16 v[68:71], v[176:179], v[226:229], v[68:71]
	v_mfma_f32_16x16x32_bf16 v[68:71], v[180:183], v[230:233], v[68:71]
	v_mfma_f32_16x16x32_bf16 v[76:79], v[172:175], v[230:233], v[76:79]
	v_mfma_f32_16x16x32_bf16 v[76:79], v[168:171], v[226:229], v[76:79]
	s_setprio 0
	s_barrier
	s_add_i32 s22, s55, s28
	v_lshl_add_u64 v[234:235], v[234:235], 0, s[14:15]
	s_mov_b32 m0, s22
	ds_read_b128 v[200:203], v167 offset:49152
	ds_read_b128 v[204:207], v167 offset:50176
	ds_read_b128 v[208:211], v167 offset:51200
	ds_read_b128 v[212:215], v167 offset:52224
	ds_read_b128 v[216:219], v167 offset:53248
	ds_read_b128 v[222:225], v167 offset:54272
	ds_read_b128 v[226:229], v167 offset:55296
	ds_read_b128 v[230:233], v167 offset:56320
	global_load_lds_dwordx4 v[234:235], off
	v_lshl_add_u64 v[234:235], v[236:237], 0, s[14:15]
	s_add_i32 m0, s22, 0x2000
	s_add_i32 s22, s60, s28
	global_load_lds_dwordx4 v[234:235], off
	v_lshl_add_u64 v[234:235], v[238:239], 0, s[14:15]
	s_mov_b32 m0, s22
	s_nop 0
	global_load_lds_dwordx4 v[234:235], off
	v_lshl_add_u64 v[234:235], v[240:241], 0, s[14:15]
	s_add_i32 m0, s22, 0x2000
	s_nop 0
	global_load_lds_dwordx4 v[234:235], off
	v_lshl_add_u64 v[234:235], v[242:243], 0, s[14:15]
	s_mov_b32 m0, s39
	s_nop 0
	global_load_lds_dwordx4 v[234:235], off
	v_lshl_add_u64 v[234:235], v[244:245], 0, s[14:15]
	s_mov_b32 m0, s40
	s_nop 0
	global_load_lds_dwordx4 v[234:235], off
	s_waitcnt vmcnt(8)
	s_waitcnt lgkmcnt(0)
	s_barrier
	s_setprio 1
	s_waitcnt lgkmcnt(0)
	v_mfma_f32_16x16x32_bf16 v[60:63], v[168:171], v[200:203], v[60:63]
	v_mfma_f32_16x16x32_bf16 v[60:63], v[172:175], v[204:207], v[60:63]
	v_mfma_f32_16x16x32_bf16 v[52:55], v[180:183], v[204:207], v[52:55]
	v_mfma_f32_16x16x32_bf16 v[52:55], v[176:179], v[200:203], v[52:55]
	v_mfma_f32_16x16x32_bf16 v[56:59], v[184:187], v[200:203], v[56:59]
	v_mfma_f32_16x16x32_bf16 v[56:59], v[188:191], v[204:207], v[56:59]
	v_mfma_f32_16x16x32_bf16 v[48:51], v[196:199], v[204:207], v[48:51]
	v_mfma_f32_16x16x32_bf16 v[48:51], v[192:195], v[200:203], v[48:51]
	v_mfma_f32_16x16x32_bf16 v[32:35], v[192:195], v[208:211], v[32:35]
	v_mfma_f32_16x16x32_bf16 v[32:35], v[196:199], v[212:215], v[32:35]
	v_mfma_f32_16x16x32_bf16 v[40:43], v[188:191], v[212:215], v[40:43]
	v_mfma_f32_16x16x32_bf16 v[40:43], v[184:187], v[208:211], v[40:43]
	v_mfma_f32_16x16x32_bf16 v[36:39], v[176:179], v[208:211], v[36:39]
	v_mfma_f32_16x16x32_bf16 v[36:39], v[180:183], v[212:215], v[36:39]
	v_mfma_f32_16x16x32_bf16 v[44:47], v[172:175], v[212:215], v[44:47]
	v_mfma_f32_16x16x32_bf16 v[44:47], v[168:171], v[208:211], v[44:47]
	v_mfma_f32_16x16x32_bf16 v[28:31], v[168:171], v[216:219], v[28:31]
	v_mfma_f32_16x16x32_bf16 v[28:31], v[172:175], v[222:225], v[28:31]
	v_mfma_f32_16x16x32_bf16 v[20:23], v[180:183], v[222:225], v[20:23]
	v_mfma_f32_16x16x32_bf16 v[20:23], v[176:179], v[216:219], v[20:23]
	v_mfma_f32_16x16x32_bf16 v[24:27], v[184:187], v[216:219], v[24:27]
	v_mfma_f32_16x16x32_bf16 v[24:27], v[188:191], v[222:225], v[24:27]
	v_mfma_f32_16x16x32_bf16 v[16:19], v[196:199], v[222:225], v[16:19]
	v_mfma_f32_16x16x32_bf16 v[16:19], v[192:195], v[216:219], v[16:19]
	v_mfma_f32_16x16x32_bf16 v[0:3], v[192:195], v[226:229], v[0:3]
	v_mfma_f32_16x16x32_bf16 v[0:3], v[196:199], v[230:233], v[0:3]
	v_mfma_f32_16x16x32_bf16 v[8:11], v[188:191], v[230:233], v[8:11]
	v_mfma_f32_16x16x32_bf16 v[8:11], v[184:187], v[226:229], v[8:11]
	v_mfma_f32_16x16x32_bf16 v[4:7], v[176:179], v[226:229], v[4:7]
	v_mfma_f32_16x16x32_bf16 v[4:7], v[180:183], v[230:233], v[4:7]
	v_mfma_f32_16x16x32_bf16 v[12:15], v[172:175], v[230:233], v[12:15]
	v_mfma_f32_16x16x32_bf16 v[12:15], v[168:171], v[226:229], v[12:15]
	s_setprio 0
	s_barrier
	s_add_u32 s20, s20, 0x100
	s_addc_u32 s21, s21, 0
	s_add_u32 s52, s52, 0x100
	s_addc_u32 s53, s53, 0
	s_cmp_ge_i32 s54, s41
	s_mov_b32 s22, s54
	s_cbranch_scc0 .LBB0_142

.LBB0_228:
	ds_read_b128 v[140:143], v219
	ds_read_b128 v[144:147], v219 offset:1024
	ds_read_b128 v[148:151], v219 offset:2048
	ds_read_b128 v[152:155], v219 offset:3072
	ds_read_b128 v[156:159], v221
	ds_read_b128 v[164:167], v221 offset:1024
	ds_read_b128 v[168:171], v221 offset:2048
	ds_read_b128 v[172:175], v221 offset:3072
	s_add_i32 s62, s26, 2
	s_add_u32 s27, s24, 0x4000
	s_addc_u32 s28, s25, 0
	s_cmp_eq_u32 s46, s26
	s_cselect_b32 s30, s0, s27
	s_cselect_b32 s31, s1, s28
	s_cselect_b32 s28, s22, s60
	s_cselect_b32 s29, s23, s61
	s_add_u32 s26, s30, 0x8000
	s_addc_u32 s27, s31, 0
	v_lshl_add_u64 v[160:161], s[24:25], 0, v[132:133]
	s_add_i32 m0, s38, 0xc000
	ds_read_b128 v[176:179], v222
	ds_read_b128 v[180:183], v222 offset:1024
	ds_read_b128 v[184:187], v222 offset:2048
	ds_read_b128 v[188:191], v222 offset:3072
	ds_read_b128 v[192:195], v222 offset:4096
	ds_read_b128 v[196:199], v222 offset:5120
	ds_read_b128 v[200:203], v222 offset:6144
	ds_read_b128 v[204:207], v222 offset:7168
	global_load_lds_dwordx4 v[160:161], off
	v_lshl_add_u64 v[160:161], s[24:25], 0, v[134:135]
	s_add_i32 m0, s38, 0xe000
	s_nop 0
	global_load_lds_dwordx4 v[160:161], off
	s_waitcnt vmcnt(8)
	s_waitcnt lgkmcnt(0)
	s_barrier
	s_setprio 1
	s_waitcnt lgkmcnt(0)
	v_mfma_f32_16x16x32_bf16 v[124:127], v[140:143], v[176:179], v[124:127]
	v_mfma_f32_16x16x32_bf16 v[124:127], v[144:147], v[180:183], v[124:127]
	v_mfma_f32_16x16x32_bf16 v[120:123], v[152:155], v[180:183], v[120:123]
	v_mfma_f32_16x16x32_bf16 v[120:123], v[148:151], v[176:179], v[120:123]
	v_mfma_f32_16x16x32_bf16 v[108:111], v[156:159], v[176:179], v[108:111]
	v_mfma_f32_16x16x32_bf16 v[108:111], v[164:167], v[180:183], v[108:111]
	v_mfma_f32_16x16x32_bf16 v[100:103], v[172:175], v[180:183], v[100:103]
	v_mfma_f32_16x16x32_bf16 v[100:103], v[168:171], v[176:179], v[100:103]
	v_mfma_f32_16x16x32_bf16 v[84:87], v[168:171], v[184:187], v[84:87]
	v_mfma_f32_16x16x32_bf16 v[84:87], v[172:175], v[188:191], v[84:87]
	v_mfma_f32_16x16x32_bf16 v[92:95], v[164:167], v[188:191], v[92:95]
	v_mfma_f32_16x16x32_bf16 v[92:95], v[156:159], v[184:187], v[92:95]
	v_mfma_f32_16x16x32_bf16 v[112:115], v[148:151], v[184:187], v[112:115]
	v_mfma_f32_16x16x32_bf16 v[112:115], v[152:155], v[188:191], v[112:115]
	v_mfma_f32_16x16x32_bf16 v[116:119], v[144:147], v[188:191], v[116:119]
	v_mfma_f32_16x16x32_bf16 v[116:119], v[140:143], v[184:187], v[116:119]
	v_mfma_f32_16x16x32_bf16 v[104:107], v[140:143], v[192:195], v[104:107]
	v_mfma_f32_16x16x32_bf16 v[104:107], v[144:147], v[196:199], v[104:107]
	v_mfma_f32_16x16x32_bf16 v[96:99], v[152:155], v[196:199], v[96:99]
	v_mfma_f32_16x16x32_bf16 v[96:99], v[148:151], v[192:195], v[96:99]
	v_mfma_f32_16x16x32_bf16 v[76:79], v[156:159], v[192:195], v[76:79]
	v_mfma_f32_16x16x32_bf16 v[76:79], v[164:167], v[196:199], v[76:79]
	v_mfma_f32_16x16x32_bf16 v[72:75], v[172:175], v[196:199], v[72:75]
	v_mfma_f32_16x16x32_bf16 v[72:75], v[168:171], v[192:195], v[72:75]
	v_mfma_f32_16x16x32_bf16 v[64:67], v[168:171], v[200:203], v[64:67]
	v_mfma_f32_16x16x32_bf16 v[64:67], v[172:175], v[204:207], v[64:67]
	v_mfma_f32_16x16x32_bf16 v[68:71], v[164:167], v[204:207], v[68:71]
	v_mfma_f32_16x16x32_bf16 v[68:71], v[156:159], v[200:203], v[68:71]
	v_mfma_f32_16x16x32_bf16 v[80:83], v[148:151], v[200:203], v[80:83]
	v_mfma_f32_16x16x32_bf16 v[80:83], v[152:155], v[204:207], v[80:83]
	v_mfma_f32_16x16x32_bf16 v[88:91], v[144:147], v[204:207], v[88:91]
	v_mfma_f32_16x16x32_bf16 v[88:91], v[140:143], v[200:203], v[88:91]
	s_setprio 0
	s_barrier
	s_add_i32 s63, s50, s37
	v_lshl_add_u64 v[160:161], s[28:29], 0, v[128:129]
	s_mov_b32 m0, s63
	ds_read_b128 v[176:179], v222 offset:16384
	ds_read_b128 v[180:183], v222 offset:17408
	ds_read_b128 v[184:187], v222 offset:18432
	ds_read_b128 v[188:191], v222 offset:19456
	ds_read_b128 v[192:195], v222 offset:20480
	ds_read_b128 v[196:199], v222 offset:21504
	ds_read_b128 v[200:203], v222 offset:22528
	ds_read_b128 v[204:207], v222 offset:23552
	global_load_lds_dwordx4 v[160:161], off
	s_add_i32 m0, s63, 0x2000
	s_add_u32 s64, s28, 0x4000
	v_lshl_add_u64 v[160:161], s[28:29], 0, v[130:131]
	s_addc_u32 s65, s29, 0
	s_add_i32 s63, s51, s37
	global_load_lds_dwordx4 v[160:161], off
	v_lshl_add_u64 v[160:161], s[64:65], 0, v[128:129]
	s_mov_b32 m0, s63
	s_nop 0
	global_load_lds_dwordx4 v[160:161], off
	v_lshl_add_u64 v[160:161], s[64:65], 0, v[130:131]
	s_add_i32 m0, s63, 0x2000
	s_nop 0
	global_load_lds_dwordx4 v[160:161], off
	v_lshl_add_u64 v[160:161], s[30:31], 0, v[128:129]
	s_mov_b32 m0, s38
	s_nop 0
	global_load_lds_dwordx4 v[160:161], off
	v_lshl_add_u64 v[160:161], s[30:31], 0, v[130:131]
	s_mov_b32 m0, s39
	s_nop 0
	global_load_lds_dwordx4 v[160:161], off
	s_waitcnt vmcnt(8)
	s_waitcnt lgkmcnt(0)
	s_barrier
	s_setprio 1
	s_waitcnt lgkmcnt(0)
	v_mfma_f32_16x16x32_bf16 v[60:63], v[140:143], v[176:179], v[60:63]
	v_mfma_f32_16x16x32_bf16 v[60:63], v[144:147], v[180:183], v[60:63]
	v_mfma_f32_16x16x32_bf16 v[56:59], v[152:155], v[180:183], v[56:59]
	v_mfma_f32_16x16x32_bf16 v[56:59], v[148:151], v[176:179], v[56:59]
	v_mfma_f32_16x16x32_bf16 v[44:47], v[156:159], v[176:179], v[44:47]
	v_mfma_f32_16x16x32_bf16 v[44:47], v[164:167], v[180:183], v[44:47]
	v_mfma_f32_16x16x32_bf16 v[36:39], v[172:175], v[180:183], v[36:39]
	v_mfma_f32_16x16x32_bf16 v[36:39], v[168:171], v[176:179], v[36:39]
	v_mfma_f32_16x16x32_bf16 v[20:23], v[168:171], v[184:187], v[20:23]
	v_mfma_f32_16x16x32_bf16 v[20:23], v[172:175], v[188:191], v[20:23]
	v_mfma_f32_16x16x32_bf16 v[28:31], v[164:167], v[188:191], v[28:31]
	v_mfma_f32_16x16x32_bf16 v[28:31], v[156:159], v[184:187], v[28:31]
	v_mfma_f32_16x16x32_bf16 v[48:51], v[148:151], v[184:187], v[48:51]
	v_mfma_f32_16x16x32_bf16 v[48:51], v[152:155], v[188:191], v[48:51]
	v_mfma_f32_16x16x32_bf16 v[52:55], v[144:147], v[188:191], v[52:55]
	v_mfma_f32_16x16x32_bf16 v[52:55], v[140:143], v[184:187], v[52:55]
	v_mfma_f32_16x16x32_bf16 v[40:43], v[140:143], v[192:195], v[40:43]
	v_mfma_f32_16x16x32_bf16 v[40:43], v[144:147], v[196:199], v[40:43]
	v_mfma_f32_16x16x32_bf16 v[32:35], v[152:155], v[196:199], v[32:35]
	v_mfma_f32_16x16x32_bf16 v[32:35], v[148:151], v[192:195], v[32:35]
	v_mfma_f32_16x16x32_bf16 v[12:15], v[156:159], v[192:195], v[12:15]
	v_mfma_f32_16x16x32_bf16 v[12:15], v[164:167], v[196:199], v[12:15]
	v_mfma_f32_16x16x32_bf16 v[8:11], v[172:175], v[196:199], v[8:11]
	v_mfma_f32_16x16x32_bf16 v[8:11], v[168:171], v[192:195], v[8:11]
	v_mfma_f32_16x16x32_bf16 v[0:3], v[168:171], v[200:203], v[0:3]
	v_mfma_f32_16x16x32_bf16 v[0:3], v[172:175], v[204:207], v[0:3]
	v_mfma_f32_16x16x32_bf16 v[4:7], v[164:167], v[204:207], v[4:7]
	v_mfma_f32_16x16x32_bf16 v[4:7], v[156:159], v[200:203], v[4:7]
	v_mfma_f32_16x16x32_bf16 v[16:19], v[148:151], v[200:203], v[16:19]
	v_mfma_f32_16x16x32_bf16 v[16:19], v[152:155], v[204:207], v[16:19]
	v_mfma_f32_16x16x32_bf16 v[24:27], v[144:147], v[204:207], v[24:27]
	v_mfma_f32_16x16x32_bf16 v[24:27], v[140:143], v[200:203], v[24:27]
	s_setprio 0
	s_barrier
	s_add_i32 s63, 0, 0x18000
	s_add_i32 s64, 0, 0x1c000
	v_add_u32_e32 v152, s63, v217
	v_add_u32_e32 v160, s64, v217
	ds_read_b128 v[140:143], v152
	ds_read_b128 v[144:147], v152 offset:1024
	ds_read_b128 v[148:151], v152 offset:2048
	ds_read_b128 v[152:155], v152 offset:3072
	ds_read_b128 v[156:159], v160
	ds_read_b128 v[164:167], v160 offset:1024
	ds_read_b128 v[168:171], v160 offset:2048
	ds_read_b128 v[172:175], v160 offset:3072
	s_add_u32 s30, s30, 0x4000
	s_addc_u32 s31, s31, 0
	s_mov_b32 m0, s40
	v_lshl_add_u64 v[160:161], s[30:31], 0, v[128:129]
	ds_read_b128 v[176:179], v222 offset:32768
	ds_read_b128 v[180:183], v222 offset:33792
	ds_read_b128 v[184:187], v222 offset:34816
	ds_read_b128 v[188:191], v222 offset:35840
	ds_read_b128 v[192:195], v222 offset:36864
	ds_read_b128 v[196:199], v222 offset:37888
	ds_read_b128 v[200:203], v222 offset:38912
	ds_read_b128 v[204:207], v222 offset:39936
	global_load_lds_dwordx4 v[160:161], off
	v_lshl_add_u64 v[160:161], s[30:31], 0, v[130:131]
	s_mov_b32 m0, s41
	s_nop 0
	global_load_lds_dwordx4 v[160:161], off
	s_waitcnt vmcnt(8)
	s_waitcnt lgkmcnt(0)
	s_barrier
	s_setprio 1
	s_waitcnt lgkmcnt(0)
	v_mfma_f32_16x16x32_bf16 v[124:127], v[140:143], v[176:179], v[124:127]
	v_mfma_f32_16x16x32_bf16 v[124:127], v[144:147], v[180:183], v[124:127]
	v_mfma_f32_16x16x32_bf16 v[120:123], v[152:155], v[180:183], v[120:123]
	v_mfma_f32_16x16x32_bf16 v[120:123], v[148:151], v[176:179], v[120:123]
	v_mfma_f32_16x16x32_bf16 v[108:111], v[156:159], v[176:179], v[108:111]
	v_mfma_f32_16x16x32_bf16 v[108:111], v[164:167], v[180:183], v[108:111]
	v_mfma_f32_16x16x32_bf16 v[100:103], v[172:175], v[180:183], v[100:103]
	v_mfma_f32_16x16x32_bf16 v[100:103], v[168:171], v[176:179], v[100:103]
	v_mfma_f32_16x16x32_bf16 v[84:87], v[168:171], v[184:187], v[84:87]
	v_mfma_f32_16x16x32_bf16 v[84:87], v[172:175], v[188:191], v[84:87]
	v_mfma_f32_16x16x32_bf16 v[92:95], v[164:167], v[188:191], v[92:95]
	v_mfma_f32_16x16x32_bf16 v[92:95], v[156:159], v[184:187], v[92:95]
	v_mfma_f32_16x16x32_bf16 v[112:115], v[148:151], v[184:187], v[112:115]
	v_mfma_f32_16x16x32_bf16 v[112:115], v[152:155], v[188:191], v[112:115]
	v_mfma_f32_16x16x32_bf16 v[116:119], v[144:147], v[188:191], v[116:119]
	v_mfma_f32_16x16x32_bf16 v[116:119], v[140:143], v[184:187], v[116:119]
	v_mfma_f32_16x16x32_bf16 v[104:107], v[140:143], v[192:195], v[104:107]
	v_mfma_f32_16x16x32_bf16 v[104:107], v[144:147], v[196:199], v[104:107]
	v_mfma_f32_16x16x32_bf16 v[96:99], v[152:155], v[196:199], v[96:99]
	v_mfma_f32_16x16x32_bf16 v[96:99], v[148:151], v[192:195], v[96:99]
	v_mfma_f32_16x16x32_bf16 v[76:79], v[156:159], v[192:195], v[76:79]
	v_mfma_f32_16x16x32_bf16 v[76:79], v[164:167], v[196:199], v[76:79]
	v_mfma_f32_16x16x32_bf16 v[72:75], v[172:175], v[196:199], v[72:75]
	v_mfma_f32_16x16x32_bf16 v[72:75], v[168:171], v[192:195], v[72:75]
	v_mfma_f32_16x16x32_bf16 v[64:67], v[168:171], v[200:203], v[64:67]
	v_mfma_f32_16x16x32_bf16 v[64:67], v[172:175], v[204:207], v[64:67]
	v_mfma_f32_16x16x32_bf16 v[68:71], v[164:167], v[204:207], v[68:71]
	v_mfma_f32_16x16x32_bf16 v[68:71], v[156:159], v[200:203], v[68:71]
	v_mfma_f32_16x16x32_bf16 v[80:83], v[148:151], v[200:203], v[80:83]
	v_mfma_f32_16x16x32_bf16 v[80:83], v[152:155], v[204:207], v[80:83]
	v_mfma_f32_16x16x32_bf16 v[88:91], v[144:147], v[204:207], v[88:91]
	v_mfma_f32_16x16x32_bf16 v[88:91], v[140:143], v[200:203], v[88:91]
	s_setprio 0
	s_barrier
	s_add_u32 s30, s28, 0x8000
	s_addc_u32 s31, s29, 0
	s_add_i32 s63, s63, s37
	v_lshl_add_u64 v[160:161], s[30:31], 0, v[128:129]
	s_mov_b32 m0, s63
	ds_read_b128 v[176:179], v222 offset:49152
	ds_read_b128 v[180:183], v222 offset:50176
	ds_read_b128 v[184:187], v222 offset:51200
	ds_read_b128 v[188:191], v222 offset:52224
	ds_read_b128 v[192:195], v222 offset:53248
	ds_read_b128 v[196:199], v222 offset:54272
	ds_read_b128 v[200:203], v222 offset:55296
	ds_read_b128 v[204:207], v222 offset:56320
	global_load_lds_dwordx4 v[160:161], off
	s_add_i32 m0, s63, 0x2000
	s_add_u32 s28, s28, 0xc000
	v_lshl_add_u64 v[160:161], s[30:31], 0, v[130:131]
	s_addc_u32 s29, s29, 0
	s_add_i32 s30, s64, s37
	global_load_lds_dwordx4 v[160:161], off
	v_lshl_add_u64 v[160:161], s[28:29], 0, v[128:129]
	s_mov_b32 m0, s30
	s_nop 0
	global_load_lds_dwordx4 v[160:161], off
	v_lshl_add_u64 v[160:161], s[28:29], 0, v[130:131]
	s_add_i32 m0, s30, 0x2000
	s_nop 0
	global_load_lds_dwordx4 v[160:161], off
	v_lshl_add_u64 v[160:161], s[26:27], 0, v[128:129]
	s_mov_b32 m0, s44
	s_nop 0
	global_load_lds_dwordx4 v[160:161], off
	v_lshl_add_u64 v[160:161], s[26:27], 0, v[130:131]
	s_mov_b32 m0, s45
	s_nop 0
	global_load_lds_dwordx4 v[160:161], off
	s_waitcnt vmcnt(8)
	s_waitcnt lgkmcnt(0)
	s_barrier
	s_setprio 1
	s_waitcnt lgkmcnt(0)
	v_mfma_f32_16x16x32_bf16 v[60:63], v[140:143], v[176:179], v[60:63]
	v_mfma_f32_16x16x32_bf16 v[60:63], v[144:147], v[180:183], v[60:63]
	v_mfma_f32_16x16x32_bf16 v[56:59], v[152:155], v[180:183], v[56:59]
	v_mfma_f32_16x16x32_bf16 v[56:59], v[148:151], v[176:179], v[56:59]
	v_mfma_f32_16x16x32_bf16 v[44:47], v[156:159], v[176:179], v[44:47]
	v_mfma_f32_16x16x32_bf16 v[44:47], v[164:167], v[180:183], v[44:47]
	v_mfma_f32_16x16x32_bf16 v[36:39], v[172:175], v[180:183], v[36:39]
	v_mfma_f32_16x16x32_bf16 v[36:39], v[168:171], v[176:179], v[36:39]
	v_mfma_f32_16x16x32_bf16 v[20:23], v[168:171], v[184:187], v[20:23]
	v_mfma_f32_16x16x32_bf16 v[20:23], v[172:175], v[188:191], v[20:23]
	v_mfma_f32_16x16x32_bf16 v[28:31], v[164:167], v[188:191], v[28:31]
	v_mfma_f32_16x16x32_bf16 v[28:31], v[156:159], v[184:187], v[28:31]
	v_mfma_f32_16x16x32_bf16 v[48:51], v[148:151], v[184:187], v[48:51]
	v_mfma_f32_16x16x32_bf16 v[48:51], v[152:155], v[188:191], v[48:51]
	v_mfma_f32_16x16x32_bf16 v[52:55], v[144:147], v[188:191], v[52:55]
	v_mfma_f32_16x16x32_bf16 v[52:55], v[140:143], v[184:187], v[52:55]
	v_mfma_f32_16x16x32_bf16 v[40:43], v[140:143], v[192:195], v[40:43]
	v_mfma_f32_16x16x32_bf16 v[40:43], v[144:147], v[196:199], v[40:43]
	v_mfma_f32_16x16x32_bf16 v[32:35], v[152:155], v[196:199], v[32:35]
	v_mfma_f32_16x16x32_bf16 v[32:35], v[148:151], v[192:195], v[32:35]
	v_mfma_f32_16x16x32_bf16 v[12:15], v[156:159], v[192:195], v[12:15]
	v_mfma_f32_16x16x32_bf16 v[12:15], v[164:167], v[196:199], v[12:15]
	v_mfma_f32_16x16x32_bf16 v[8:11], v[172:175], v[196:199], v[8:11]
	v_mfma_f32_16x16x32_bf16 v[8:11], v[168:171], v[192:195], v[8:11]
	v_mfma_f32_16x16x32_bf16 v[0:3], v[168:171], v[200:203], v[0:3]
	v_mfma_f32_16x16x32_bf16 v[0:3], v[172:175], v[204:207], v[0:3]
	v_mfma_f32_16x16x32_bf16 v[4:7], v[164:167], v[204:207], v[4:7]
	v_mfma_f32_16x16x32_bf16 v[4:7], v[156:159], v[200:203], v[4:7]
	v_mfma_f32_16x16x32_bf16 v[16:19], v[148:151], v[200:203], v[16:19]
	v_mfma_f32_16x16x32_bf16 v[16:19], v[152:155], v[204:207], v[16:19]
	v_mfma_f32_16x16x32_bf16 v[24:27], v[144:147], v[204:207], v[24:27]
	v_mfma_f32_16x16x32_bf16 v[24:27], v[140:143], v[200:203], v[24:27]
	s_setprio 0
	s_barrier
	s_add_u32 s24, s24, 0x10000
	s_addc_u32 s25, s25, 0
	s_add_u32 s60, s60, 0x10000
	s_addc_u32 s61, s61, 0
	s_cmp_ge_i32 s62, s43
	s_mov_b32 s26, s62
	s_cbranch_scc0 .LBB0_228
	v_pk_mul_f32 v[200:201], v[126:127], 0.5 op_sel_hi:[1,0]
	v_pk_mul_f32 v[202:203], v[124:125], 0.5 op_sel_hi:[1,0]
	v_pk_mul_f32 v[204:205], v[122:123], 0.5 op_sel_hi:[1,0]
	v_pk_mul_f32 v[206:207], v[120:121], 0.5 op_sel_hi:[1,0]
	v_pk_mul_f32 v[210:211], v[110:111], 0.5 op_sel_hi:[1,0]
	v_pk_mul_f32 v[208:209], v[108:109], 0.5 op_sel_hi:[1,0]
	v_pk_mul_f32 v[198:199], v[102:103], 0.5 op_sel_hi:[1,0]
	v_pk_mul_f32 v[196:197], v[100:101], 0.5 op_sel_hi:[1,0]
	v_pk_mul_f32 v[194:195], v[118:119], 0.5 op_sel_hi:[1,0]
	v_pk_mul_f32 v[192:193], v[116:117], 0.5 op_sel_hi:[1,0]
	v_pk_mul_f32 v[190:191], v[114:115], 0.5 op_sel_hi:[1,0]
	v_pk_mul_f32 v[188:189], v[112:113], 0.5 op_sel_hi:[1,0]
	v_pk_mul_f32 v[186:187], v[94:95], 0.5 op_sel_hi:[1,0]
	v_pk_mul_f32 v[184:185], v[92:93], 0.5 op_sel_hi:[1,0]
	v_pk_mul_f32 v[182:183], v[86:87], 0.5 op_sel_hi:[1,0]
	v_pk_mul_f32 v[180:181], v[84:85], 0.5 op_sel_hi:[1,0]
	v_pk_mul_f32 v[178:179], v[106:107], 0.5 op_sel_hi:[1,0]
	v_pk_mul_f32 v[176:177], v[104:105], 0.5 op_sel_hi:[1,0]
	v_pk_mul_f32 v[174:175], v[98:99], 0.5 op_sel_hi:[1,0]
	v_pk_mul_f32 v[172:173], v[96:97], 0.5 op_sel_hi:[1,0]
	v_pk_mul_f32 v[170:171], v[78:79], 0.5 op_sel_hi:[1,0]
	v_pk_mul_f32 v[168:169], v[76:77], 0.5 op_sel_hi:[1,0]
	v_pk_mul_f32 v[166:167], v[74:75], 0.5 op_sel_hi:[1,0]
	v_pk_mul_f32 v[164:165], v[72:73], 0.5 op_sel_hi:[1,0]
	v_pk_mul_f32 v[160:161], v[90:91], 0.5 op_sel_hi:[1,0]
	v_pk_mul_f32 v[158:159], v[88:89], 0.5 op_sel_hi:[1,0]
	v_pk_mul_f32 v[156:157], v[82:83], 0.5 op_sel_hi:[1,0]
	v_pk_mul_f32 v[154:155], v[80:81], 0.5 op_sel_hi:[1,0]
	v_pk_mul_f32 v[152:153], v[70:71], 0.5 op_sel_hi:[1,0]
	v_pk_mul_f32 v[150:151], v[68:69], 0.5 op_sel_hi:[1,0]
	v_pk_mul_f32 v[148:149], v[66:67], 0.5 op_sel_hi:[1,0]
	v_pk_mul_f32 v[146:147], v[64:65], 0.5 op_sel_hi:[1,0]
	v_pk_mul_f32 v[144:145], v[62:63], 0.5 op_sel_hi:[1,0]
	v_pk_mul_f32 v[142:143], v[60:61], 0.5 op_sel_hi:[1,0]
	v_pk_mul_f32 v[126:127], v[58:59], 0.5 op_sel_hi:[1,0]
	v_pk_mul_f32 v[124:125], v[56:57], 0.5 op_sel_hi:[1,0]
	v_pk_mul_f32 v[122:123], v[46:47], 0.5 op_sel_hi:[1,0]
	v_pk_mul_f32 v[120:121], v[44:45], 0.5 op_sel_hi:[1,0]
	v_pk_mul_f32 v[118:119], v[38:39], 0.5 op_sel_hi:[1,0]
	v_pk_mul_f32 v[116:117], v[36:37], 0.5 op_sel_hi:[1,0]
	v_pk_mul_f32 v[114:115], v[54:55], 0.5 op_sel_hi:[1,0]
	v_pk_mul_f32 v[112:113], v[52:53], 0.5 op_sel_hi:[1,0]
	v_pk_mul_f32 v[110:111], v[50:51], 0.5 op_sel_hi:[1,0]
	v_pk_mul_f32 v[108:109], v[48:49], 0.5 op_sel_hi:[1,0]
	v_pk_mul_f32 v[106:107], v[30:31], 0.5 op_sel_hi:[1,0]
	v_pk_mul_f32 v[104:105], v[28:29], 0.5 op_sel_hi:[1,0]
	v_pk_mul_f32 v[102:103], v[22:23], 0.5 op_sel_hi:[1,0]
	v_pk_mul_f32 v[100:101], v[20:21], 0.5 op_sel_hi:[1,0]
	v_pk_mul_f32 v[98:99], v[42:43], 0.5 op_sel_hi:[1,0]
	v_pk_mul_f32 v[96:97], v[40:41], 0.5 op_sel_hi:[1,0]
	v_pk_mul_f32 v[94:95], v[34:35], 0.5 op_sel_hi:[1,0]
	v_pk_mul_f32 v[92:93], v[32:33], 0.5 op_sel_hi:[1,0]
	v_pk_mul_f32 v[90:91], v[14:15], 0.5 op_sel_hi:[1,0]
	v_pk_mul_f32 v[88:89], v[12:13], 0.5 op_sel_hi:[1,0]
	v_pk_mul_f32 v[86:87], v[10:11], 0.5 op_sel_hi:[1,0]
	v_pk_mul_f32 v[84:85], v[8:9], 0.5 op_sel_hi:[1,0]
	v_pk_mul_f32 v[82:83], v[26:27], 0.5 op_sel_hi:[1,0]
	v_pk_mul_f32 v[80:81], v[24:25], 0.5 op_sel_hi:[1,0]
	v_pk_mul_f32 v[78:79], v[18:19], 0.5 op_sel_hi:[1,0]
	v_pk_mul_f32 v[76:77], v[16:17], 0.5 op_sel_hi:[1,0]
	v_pk_mul_f32 v[74:75], v[6:7], 0.5 op_sel_hi:[1,0]
	v_pk_mul_f32 v[72:73], v[4:5], 0.5 op_sel_hi:[1,0]
	v_pk_mul_f32 v[70:71], v[2:3], 0.5 op_sel_hi:[1,0]
	v_pk_mul_f32 v[68:69], v[0:1], 0.5 op_sel_hi:[1,0]

.LBB0_323:
	ds_read_b128 v[128:131], v222
	ds_read_b128 v[132:135], v222 offset:1024
	ds_read_b128 v[136:139], v222 offset:2048
	ds_read_b128 v[140:143], v222 offset:3072
	ds_read_b128 v[144:147], v223
	ds_read_b128 v[148:151], v223 offset:1024
	ds_read_b128 v[152:155], v223 offset:2048
	ds_read_b128 v[156:159], v223 offset:3072
	s_add_i32 s53, s50, 2
	s_add_u32 s54, s0, 0x80
	s_addc_u32 s51, s1, 0
	s_cmp_eq_u32 s78, s50
	s_cselect_b32 s50, s46, s54
	s_cselect_b32 s51, s47, s51
	s_cselect_b32 s55, s49, s52
	s_cselect_b32 s54, s48, s33
	v_lshl_add_u64 v[160:161], s[0:1], 0, v[176:177]
	s_add_i32 m0, s71, 0xc000
	ds_read_b128 v[184:187], v224
	ds_read_b128 v[188:191], v224 offset:1024
	ds_read_b128 v[192:195], v224 offset:2048
	ds_read_b128 v[196:199], v224 offset:3072
	ds_read_b128 v[200:203], v224 offset:4096
	ds_read_b128 v[204:207], v224 offset:5120
	ds_read_b128 v[208:211], v224 offset:6144
	ds_read_b128 v[212:215], v224 offset:7168
	global_load_lds_dwordx4 v[160:161], off
	v_lshl_add_u64 v[160:161], s[0:1], 0, v[178:179]
	s_add_i32 m0, s71, 0xe000
	s_nop 0
	global_load_lds_dwordx4 v[160:161], off
	s_waitcnt vmcnt(8)
	s_waitcnt lgkmcnt(0)
	s_barrier
	s_setprio 1
	s_waitcnt lgkmcnt(0)
	v_mfma_f32_16x16x32_bf16 v[124:127], v[128:131], v[184:187], v[124:127]
	v_mfma_f32_16x16x32_bf16 v[124:127], v[132:135], v[188:191], v[124:127]
	v_mfma_f32_16x16x32_bf16 v[120:123], v[140:143], v[188:191], v[120:123]
	v_mfma_f32_16x16x32_bf16 v[120:123], v[136:139], v[184:187], v[120:123]
	v_mfma_f32_16x16x32_bf16 v[116:119], v[144:147], v[184:187], v[116:119]
	v_mfma_f32_16x16x32_bf16 v[116:119], v[148:151], v[188:191], v[116:119]
	v_mfma_f32_16x16x32_bf16 v[112:115], v[156:159], v[188:191], v[112:115]
	v_mfma_f32_16x16x32_bf16 v[112:115], v[152:155], v[184:187], v[112:115]
	v_mfma_f32_16x16x32_bf16 v[96:99], v[152:155], v[192:195], v[96:99]
	v_mfma_f32_16x16x32_bf16 v[96:99], v[156:159], v[196:199], v[96:99]
	v_mfma_f32_16x16x32_bf16 v[100:103], v[148:151], v[196:199], v[100:103]
	v_mfma_f32_16x16x32_bf16 v[100:103], v[144:147], v[192:195], v[100:103]
	v_mfma_f32_16x16x32_bf16 v[104:107], v[136:139], v[192:195], v[104:107]
	v_mfma_f32_16x16x32_bf16 v[104:107], v[140:143], v[196:199], v[104:107]
	v_mfma_f32_16x16x32_bf16 v[108:111], v[132:135], v[196:199], v[108:111]
	v_mfma_f32_16x16x32_bf16 v[108:111], v[128:131], v[192:195], v[108:111]
	v_mfma_f32_16x16x32_bf16 v[92:95], v[128:131], v[200:203], v[92:95]
	v_mfma_f32_16x16x32_bf16 v[92:95], v[132:135], v[204:207], v[92:95]
	v_mfma_f32_16x16x32_bf16 v[88:91], v[140:143], v[204:207], v[88:91]
	v_mfma_f32_16x16x32_bf16 v[88:91], v[136:139], v[200:203], v[88:91]
	v_mfma_f32_16x16x32_bf16 v[84:87], v[144:147], v[200:203], v[84:87]
	v_mfma_f32_16x16x32_bf16 v[84:87], v[148:151], v[204:207], v[84:87]
	v_mfma_f32_16x16x32_bf16 v[80:83], v[156:159], v[204:207], v[80:83]
	v_mfma_f32_16x16x32_bf16 v[80:83], v[152:155], v[200:203], v[80:83]
	v_mfma_f32_16x16x32_bf16 v[64:67], v[152:155], v[208:211], v[64:67]
	v_mfma_f32_16x16x32_bf16 v[64:67], v[156:159], v[212:215], v[64:67]
	v_mfma_f32_16x16x32_bf16 v[68:71], v[148:151], v[212:215], v[68:71]
	v_mfma_f32_16x16x32_bf16 v[68:71], v[144:147], v[208:211], v[68:71]
	v_mfma_f32_16x16x32_bf16 v[72:75], v[136:139], v[208:211], v[72:75]
	v_mfma_f32_16x16x32_bf16 v[72:75], v[140:143], v[212:215], v[72:75]
	v_mfma_f32_16x16x32_bf16 v[76:79], v[132:135], v[212:215], v[76:79]
	v_mfma_f32_16x16x32_bf16 v[76:79], v[128:131], v[208:211], v[76:79]
	s_setprio 0
	s_barrier
	s_add_i32 s60, s82, s70
	v_lshl_add_u64 v[160:161], s[54:55], 0, v[166:167]
	s_mov_b32 m0, s60
	ds_read_b128 v[184:187], v224 offset:16384
	ds_read_b128 v[188:191], v224 offset:17408
	ds_read_b128 v[192:195], v224 offset:18432
	ds_read_b128 v[196:199], v224 offset:19456
	ds_read_b128 v[200:203], v224 offset:20480
	ds_read_b128 v[204:207], v224 offset:21504
	ds_read_b128 v[208:211], v224 offset:22528
	ds_read_b128 v[212:215], v224 offset:23552
	global_load_lds_dwordx4 v[160:161], off
	s_add_i32 m0, s60, 0x2000
	v_lshl_add_u64 v[216:217], s[54:55], 0, v[170:171]
	s_add_u32 s54, s54, s10
	s_addc_u32 s55, s55, s11
	s_add_i32 s60, s83, s70
	global_load_lds_dwordx4 v[216:217], off
	v_lshl_add_u64 v[218:219], s[54:55], 0, v[166:167]
	s_mov_b32 m0, s60
	v_lshl_add_u64 v[230:231], s[54:55], 0, v[170:171]
	global_load_lds_dwordx4 v[218:219], off
	s_add_i32 m0, s60, 0x2000
	v_lshl_add_u64 v[232:233], s[50:51], 0, v[164:165]
	global_load_lds_dwordx4 v[230:231], off
	s_mov_b32 m0, s71
	v_lshl_add_u64 v[234:235], s[50:51], 0, v[168:169]
	global_load_lds_dwordx4 v[232:233], off
	s_mov_b32 m0, s72
	s_nop 0
	global_load_lds_dwordx4 v[234:235], off
	s_waitcnt vmcnt(8)
	s_waitcnt lgkmcnt(0)
	s_barrier
	s_setprio 1
	s_waitcnt lgkmcnt(0)
	v_mfma_f32_16x16x32_bf16 v[60:63], v[128:131], v[184:187], v[60:63]
	v_mfma_f32_16x16x32_bf16 v[60:63], v[132:135], v[188:191], v[60:63]
	v_mfma_f32_16x16x32_bf16 v[56:59], v[140:143], v[188:191], v[56:59]
	v_mfma_f32_16x16x32_bf16 v[56:59], v[136:139], v[184:187], v[56:59]
	v_mfma_f32_16x16x32_bf16 v[52:55], v[144:147], v[184:187], v[52:55]
	v_mfma_f32_16x16x32_bf16 v[52:55], v[148:151], v[188:191], v[52:55]
	v_mfma_f32_16x16x32_bf16 v[48:51], v[156:159], v[188:191], v[48:51]
	v_mfma_f32_16x16x32_bf16 v[48:51], v[152:155], v[184:187], v[48:51]
	v_mfma_f32_16x16x32_bf16 v[32:35], v[152:155], v[192:195], v[32:35]
	v_mfma_f32_16x16x32_bf16 v[32:35], v[156:159], v[196:199], v[32:35]
	v_mfma_f32_16x16x32_bf16 v[36:39], v[148:151], v[196:199], v[36:39]
	v_mfma_f32_16x16x32_bf16 v[36:39], v[144:147], v[192:195], v[36:39]
	v_mfma_f32_16x16x32_bf16 v[40:43], v[136:139], v[192:195], v[40:43]
	v_mfma_f32_16x16x32_bf16 v[40:43], v[140:143], v[196:199], v[40:43]
	v_mfma_f32_16x16x32_bf16 v[44:47], v[132:135], v[196:199], v[44:47]
	v_mfma_f32_16x16x32_bf16 v[44:47], v[128:131], v[192:195], v[44:47]
	v_mfma_f32_16x16x32_bf16 v[28:31], v[128:131], v[200:203], v[28:31]
	v_mfma_f32_16x16x32_bf16 v[28:31], v[132:135], v[204:207], v[28:31]
	v_mfma_f32_16x16x32_bf16 v[24:27], v[140:143], v[204:207], v[24:27]
	v_mfma_f32_16x16x32_bf16 v[24:27], v[136:139], v[200:203], v[24:27]
	v_mfma_f32_16x16x32_bf16 v[20:23], v[144:147], v[200:203], v[20:23]
	v_mfma_f32_16x16x32_bf16 v[20:23], v[148:151], v[204:207], v[20:23]
	v_mfma_f32_16x16x32_bf16 v[16:19], v[156:159], v[204:207], v[16:19]
	v_mfma_f32_16x16x32_bf16 v[16:19], v[152:155], v[200:203], v[16:19]
	v_mfma_f32_16x16x32_bf16 v[0:3], v[152:155], v[208:211], v[0:3]
	v_mfma_f32_16x16x32_bf16 v[0:3], v[156:159], v[212:215], v[0:3]
	v_mfma_f32_16x16x32_bf16 v[4:7], v[148:151], v[212:215], v[4:7]
	v_mfma_f32_16x16x32_bf16 v[4:7], v[144:147], v[208:211], v[4:7]
	v_mfma_f32_16x16x32_bf16 v[8:11], v[136:139], v[208:211], v[8:11]
	v_mfma_f32_16x16x32_bf16 v[8:11], v[140:143], v[212:215], v[8:11]
	v_mfma_f32_16x16x32_bf16 v[12:15], v[132:135], v[212:215], v[12:15]
	v_mfma_f32_16x16x32_bf16 v[12:15], v[128:131], v[208:211], v[12:15]
	s_setprio 0
	s_barrier
	s_add_i32 s54, 0, 0x18000
	s_add_i32 s55, 0, 0x1c000
	v_add_u32_e32 v140, s54, v221
	v_add_u32_e32 v156, s55, v221
	ds_read_b128 v[128:131], v140
	ds_read_b128 v[132:135], v140 offset:1024
	ds_read_b128 v[136:139], v140 offset:2048
	ds_read_b128 v[140:143], v140 offset:3072
	ds_read_b128 v[144:147], v156
	ds_read_b128 v[148:151], v156 offset:1024
	ds_read_b128 v[152:155], v156 offset:2048
	ds_read_b128 v[156:159], v156 offset:3072
	s_add_u32 s50, s50, s10
	s_addc_u32 s51, s51, s11
	s_mov_b32 m0, s73
	v_lshl_add_u64 v[236:237], s[50:51], 0, v[164:165]
	ds_read_b128 v[184:187], v224 offset:32768
	ds_read_b128 v[188:191], v224 offset:33792
	ds_read_b128 v[192:195], v224 offset:34816
	ds_read_b128 v[196:199], v224 offset:35840
	ds_read_b128 v[200:203], v224 offset:36864
	ds_read_b128 v[204:207], v224 offset:37888
	ds_read_b128 v[208:211], v224 offset:38912
	ds_read_b128 v[212:215], v224 offset:39936
	global_load_lds_dwordx4 v[236:237], off
	v_lshl_add_u64 v[236:237], s[50:51], 0, v[168:169]
	s_mov_b32 m0, s74
	s_nop 0
	global_load_lds_dwordx4 v[236:237], off
	s_waitcnt vmcnt(8)
	s_waitcnt lgkmcnt(0)
	s_barrier
	s_setprio 1
	s_waitcnt lgkmcnt(0)
	v_mfma_f32_16x16x32_bf16 v[124:127], v[128:131], v[184:187], v[124:127]
	v_mfma_f32_16x16x32_bf16 v[124:127], v[132:135], v[188:191], v[124:127]
	v_mfma_f32_16x16x32_bf16 v[120:123], v[140:143], v[188:191], v[120:123]
	v_mfma_f32_16x16x32_bf16 v[120:123], v[136:139], v[184:187], v[120:123]
	v_mfma_f32_16x16x32_bf16 v[116:119], v[144:147], v[184:187], v[116:119]
	v_mfma_f32_16x16x32_bf16 v[116:119], v[148:151], v[188:191], v[116:119]
	v_mfma_f32_16x16x32_bf16 v[112:115], v[156:159], v[188:191], v[112:115]
	v_mfma_f32_16x16x32_bf16 v[112:115], v[152:155], v[184:187], v[112:115]
	v_mfma_f32_16x16x32_bf16 v[96:99], v[152:155], v[192:195], v[96:99]
	v_mfma_f32_16x16x32_bf16 v[96:99], v[156:159], v[196:199], v[96:99]
	v_mfma_f32_16x16x32_bf16 v[100:103], v[148:151], v[196:199], v[100:103]
	v_mfma_f32_16x16x32_bf16 v[100:103], v[144:147], v[192:195], v[100:103]
	v_mfma_f32_16x16x32_bf16 v[104:107], v[136:139], v[192:195], v[104:107]
	v_mfma_f32_16x16x32_bf16 v[104:107], v[140:143], v[196:199], v[104:107]
	v_mfma_f32_16x16x32_bf16 v[108:111], v[132:135], v[196:199], v[108:111]
	v_mfma_f32_16x16x32_bf16 v[108:111], v[128:131], v[192:195], v[108:111]
	v_mfma_f32_16x16x32_bf16 v[92:95], v[128:131], v[200:203], v[92:95]
	v_mfma_f32_16x16x32_bf16 v[92:95], v[132:135], v[204:207], v[92:95]
	v_mfma_f32_16x16x32_bf16 v[88:91], v[140:143], v[204:207], v[88:91]
	v_mfma_f32_16x16x32_bf16 v[88:91], v[136:139], v[200:203], v[88:91]
	v_mfma_f32_16x16x32_bf16 v[84:87], v[144:147], v[200:203], v[84:87]
	v_mfma_f32_16x16x32_bf16 v[84:87], v[148:151], v[204:207], v[84:87]
	v_mfma_f32_16x16x32_bf16 v[80:83], v[156:159], v[204:207], v[80:83]
	v_mfma_f32_16x16x32_bf16 v[80:83], v[152:155], v[200:203], v[80:83]
	v_mfma_f32_16x16x32_bf16 v[64:67], v[152:155], v[208:211], v[64:67]
	v_mfma_f32_16x16x32_bf16 v[64:67], v[156:159], v[212:215], v[64:67]
	v_mfma_f32_16x16x32_bf16 v[68:71], v[148:151], v[212:215], v[68:71]
	v_mfma_f32_16x16x32_bf16 v[68:71], v[144:147], v[208:211], v[68:71]
	v_mfma_f32_16x16x32_bf16 v[72:75], v[136:139], v[208:211], v[72:75]
	v_mfma_f32_16x16x32_bf16 v[72:75], v[140:143], v[212:215], v[72:75]
	v_mfma_f32_16x16x32_bf16 v[76:79], v[132:135], v[212:215], v[76:79]
	v_mfma_f32_16x16x32_bf16 v[76:79], v[128:131], v[208:211], v[76:79]
	s_setprio 0
	s_barrier
	s_add_i32 s50, s54, s70
	v_lshl_add_u64 v[160:161], v[160:161], 0, s[36:37]
	s_mov_b32 m0, s50
	ds_read_b128 v[184:187], v224 offset:49152
	ds_read_b128 v[188:191], v224 offset:50176
	ds_read_b128 v[192:195], v224 offset:51200
	ds_read_b128 v[196:199], v224 offset:52224
	ds_read_b128 v[200:203], v224 offset:53248
	ds_read_b128 v[204:207], v224 offset:54272
	ds_read_b128 v[208:211], v224 offset:55296
	ds_read_b128 v[212:215], v224 offset:56320
	global_load_lds_dwordx4 v[160:161], off
	v_lshl_add_u64 v[160:161], v[216:217], 0, s[36:37]
	s_add_i32 m0, s50, 0x2000
	s_add_i32 s50, s55, s70
	global_load_lds_dwordx4 v[160:161], off
	v_lshl_add_u64 v[160:161], v[218:219], 0, s[36:37]
	s_mov_b32 m0, s50
	s_nop 0
	global_load_lds_dwordx4 v[160:161], off
	v_lshl_add_u64 v[160:161], v[230:231], 0, s[36:37]
	s_add_i32 m0, s50, 0x2000
	s_nop 0
	global_load_lds_dwordx4 v[160:161], off
	v_lshl_add_u64 v[160:161], v[232:233], 0, s[36:37]
	s_mov_b32 m0, s76
	s_nop 0
	global_load_lds_dwordx4 v[160:161], off
	v_lshl_add_u64 v[160:161], v[234:235], 0, s[36:37]
	s_mov_b32 m0, s77
	s_nop 0
	global_load_lds_dwordx4 v[160:161], off
	s_waitcnt vmcnt(8)
	s_waitcnt lgkmcnt(0)
	s_barrier
	s_setprio 1
	s_waitcnt lgkmcnt(0)
	v_mfma_f32_16x16x32_bf16 v[60:63], v[128:131], v[184:187], v[60:63]
	v_mfma_f32_16x16x32_bf16 v[60:63], v[132:135], v[188:191], v[60:63]
	v_mfma_f32_16x16x32_bf16 v[56:59], v[140:143], v[188:191], v[56:59]
	v_mfma_f32_16x16x32_bf16 v[56:59], v[136:139], v[184:187], v[56:59]
	v_mfma_f32_16x16x32_bf16 v[52:55], v[144:147], v[184:187], v[52:55]
	v_mfma_f32_16x16x32_bf16 v[52:55], v[148:151], v[188:191], v[52:55]
	v_mfma_f32_16x16x32_bf16 v[48:51], v[156:159], v[188:191], v[48:51]
	v_mfma_f32_16x16x32_bf16 v[48:51], v[152:155], v[184:187], v[48:51]
	v_mfma_f32_16x16x32_bf16 v[32:35], v[152:155], v[192:195], v[32:35]
	v_mfma_f32_16x16x32_bf16 v[32:35], v[156:159], v[196:199], v[32:35]
	v_mfma_f32_16x16x32_bf16 v[36:39], v[148:151], v[196:199], v[36:39]
	v_mfma_f32_16x16x32_bf16 v[36:39], v[144:147], v[192:195], v[36:39]
	v_mfma_f32_16x16x32_bf16 v[40:43], v[136:139], v[192:195], v[40:43]
	v_mfma_f32_16x16x32_bf16 v[40:43], v[140:143], v[196:199], v[40:43]
	v_mfma_f32_16x16x32_bf16 v[44:47], v[132:135], v[196:199], v[44:47]
	v_mfma_f32_16x16x32_bf16 v[44:47], v[128:131], v[192:195], v[44:47]
	v_mfma_f32_16x16x32_bf16 v[28:31], v[128:131], v[200:203], v[28:31]
	v_mfma_f32_16x16x32_bf16 v[28:31], v[132:135], v[204:207], v[28:31]
	v_mfma_f32_16x16x32_bf16 v[24:27], v[140:143], v[204:207], v[24:27]
	v_mfma_f32_16x16x32_bf16 v[24:27], v[136:139], v[200:203], v[24:27]
	v_mfma_f32_16x16x32_bf16 v[20:23], v[144:147], v[200:203], v[20:23]
	v_mfma_f32_16x16x32_bf16 v[20:23], v[148:151], v[204:207], v[20:23]
	v_mfma_f32_16x16x32_bf16 v[16:19], v[156:159], v[204:207], v[16:19]
	v_mfma_f32_16x16x32_bf16 v[16:19], v[152:155], v[200:203], v[16:19]
	v_mfma_f32_16x16x32_bf16 v[0:3], v[152:155], v[208:211], v[0:3]
	v_mfma_f32_16x16x32_bf16 v[0:3], v[156:159], v[212:215], v[0:3]
	v_mfma_f32_16x16x32_bf16 v[4:7], v[148:151], v[212:215], v[4:7]
	v_mfma_f32_16x16x32_bf16 v[4:7], v[144:147], v[208:211], v[4:7]
	v_mfma_f32_16x16x32_bf16 v[8:11], v[136:139], v[208:211], v[8:11]
	v_mfma_f32_16x16x32_bf16 v[8:11], v[140:143], v[212:215], v[8:11]
	v_mfma_f32_16x16x32_bf16 v[12:15], v[132:135], v[212:215], v[12:15]
	v_mfma_f32_16x16x32_bf16 v[12:15], v[128:131], v[208:211], v[12:15]
	s_setprio 0
	s_barrier
	s_add_u32 s0, s0, 0x100
	s_addc_u32 s1, s1, 0
	s_add_u32 s33, s33, 0x100
	s_addc_u32 s52, s52, 0
	s_cmp_ge_i32 s53, s75
	s_mov_b32 s50, s53
	s_cbranch_scc0 .LBB0_323

.LBB0_592:
	ds_read_b128 v[144:147], v157
	ds_read_b128 v[148:151], v157 offset:1024
	ds_read_b128 v[164:167], v157 offset:2048
	ds_read_b128 v[168:171], v157 offset:3072
	ds_read_b128 v[172:175], v158
	ds_read_b128 v[176:179], v158 offset:1024
	ds_read_b128 v[180:183], v158 offset:2048
	ds_read_b128 v[184:187], v158 offset:3072
	s_add_i32 s64, s34, 2
	s_add_u32 s65, s30, 0x80
	s_addc_u32 s35, s31, 0
	s_cmp_eq_u32 s49, s34
	s_cselect_b32 s34, s2, s65
	s_cselect_b32 s35, s3, s35
	s_cselect_b32 s67, s29, s63
	s_cselect_b32 s66, s28, s62
	v_lshl_add_u64 v[152:153], s[30:31], 0, v[136:137]
	s_add_i32 m0, s41, 0xc000
	ds_read_b128 v[188:191], v159
	ds_read_b128 v[192:195], v159 offset:1024
	ds_read_b128 v[196:199], v159 offset:2048
	ds_read_b128 v[200:203], v159 offset:3072
	ds_read_b128 v[204:207], v159 offset:4096
	ds_read_b128 v[208:211], v159 offset:5120
	ds_read_b128 v[212:215], v159 offset:6144
	ds_read_b128 v[216:219], v159 offset:7168
	global_load_lds_dwordx4 v[152:153], off
	v_lshl_add_u64 v[152:153], s[30:31], 0, v[138:139]
	s_add_i32 m0, s41, 0xe000
	s_nop 0
	global_load_lds_dwordx4 v[152:153], off
	s_waitcnt vmcnt(8)
	s_waitcnt lgkmcnt(0)
	s_barrier
	s_setprio 1
	s_waitcnt lgkmcnt(0)
	v_mfma_f32_16x16x32_bf16 v[120:123], v[144:147], v[188:191], v[120:123]
	v_mfma_f32_16x16x32_bf16 v[120:123], v[148:151], v[192:195], v[120:123]
	v_mfma_f32_16x16x32_bf16 v[124:127], v[168:171], v[192:195], v[124:127]
	v_mfma_f32_16x16x32_bf16 v[124:127], v[164:167], v[188:191], v[124:127]
	v_mfma_f32_16x16x32_bf16 v[116:119], v[172:175], v[188:191], v[116:119]
	v_mfma_f32_16x16x32_bf16 v[116:119], v[176:179], v[192:195], v[116:119]
	v_mfma_f32_16x16x32_bf16 v[112:115], v[184:187], v[192:195], v[112:115]
	v_mfma_f32_16x16x32_bf16 v[112:115], v[180:183], v[188:191], v[112:115]
	v_mfma_f32_16x16x32_bf16 v[96:99], v[180:183], v[196:199], v[96:99]
	v_mfma_f32_16x16x32_bf16 v[96:99], v[184:187], v[200:203], v[96:99]
	v_mfma_f32_16x16x32_bf16 v[100:103], v[176:179], v[200:203], v[100:103]
	v_mfma_f32_16x16x32_bf16 v[100:103], v[172:175], v[196:199], v[100:103]
	v_mfma_f32_16x16x32_bf16 v[104:107], v[164:167], v[196:199], v[104:107]
	v_mfma_f32_16x16x32_bf16 v[104:107], v[168:171], v[200:203], v[104:107]
	v_mfma_f32_16x16x32_bf16 v[108:111], v[148:151], v[200:203], v[108:111]
	v_mfma_f32_16x16x32_bf16 v[108:111], v[144:147], v[196:199], v[108:111]
	v_mfma_f32_16x16x32_bf16 v[92:95], v[144:147], v[204:207], v[92:95]
	v_mfma_f32_16x16x32_bf16 v[92:95], v[148:151], v[208:211], v[92:95]
	v_mfma_f32_16x16x32_bf16 v[88:91], v[168:171], v[208:211], v[88:91]
	v_mfma_f32_16x16x32_bf16 v[88:91], v[164:167], v[204:207], v[88:91]
	v_mfma_f32_16x16x32_bf16 v[84:87], v[172:175], v[204:207], v[84:87]
	v_mfma_f32_16x16x32_bf16 v[84:87], v[176:179], v[208:211], v[84:87]
	v_mfma_f32_16x16x32_bf16 v[80:83], v[184:187], v[208:211], v[80:83]
	v_mfma_f32_16x16x32_bf16 v[80:83], v[180:183], v[204:207], v[80:83]
	v_mfma_f32_16x16x32_bf16 v[64:67], v[180:183], v[212:215], v[64:67]
	v_mfma_f32_16x16x32_bf16 v[64:67], v[184:187], v[216:219], v[64:67]
	v_mfma_f32_16x16x32_bf16 v[68:71], v[176:179], v[216:219], v[68:71]
	v_mfma_f32_16x16x32_bf16 v[68:71], v[172:175], v[212:215], v[68:71]
	v_mfma_f32_16x16x32_bf16 v[72:75], v[164:167], v[212:215], v[72:75]
	v_mfma_f32_16x16x32_bf16 v[72:75], v[168:171], v[216:219], v[72:75]
	v_mfma_f32_16x16x32_bf16 v[76:79], v[148:151], v[216:219], v[76:79]
	v_mfma_f32_16x16x32_bf16 v[76:79], v[144:147], v[212:215], v[76:79]
	s_setprio 0
	s_barrier
	s_add_i32 s65, s52, s40
	v_lshl_add_u64 v[152:153], s[66:67], 0, v[130:131]
	s_mov_b32 m0, s65
	ds_read_b128 v[188:191], v159 offset:16384
	ds_read_b128 v[192:195], v159 offset:17408
	ds_read_b128 v[196:199], v159 offset:18432
	ds_read_b128 v[200:203], v159 offset:19456
	ds_read_b128 v[204:207], v159 offset:20480
	ds_read_b128 v[208:211], v159 offset:21504
	ds_read_b128 v[212:215], v159 offset:22528
	ds_read_b128 v[216:219], v159 offset:23552
	global_load_lds_dwordx4 v[152:153], off
	s_add_i32 m0, s65, 0x2000
	v_lshl_add_u64 v[160:161], s[66:67], 0, v[134:135]
	s_add_u32 s66, s66, s8
	s_addc_u32 s67, s67, s9
	s_add_i32 s65, s53, s40
	global_load_lds_dwordx4 v[160:161], off
	v_lshl_add_u64 v[222:223], s[66:67], 0, v[130:131]
	s_mov_b32 m0, s65
	v_lshl_add_u64 v[224:225], s[66:67], 0, v[134:135]
	global_load_lds_dwordx4 v[222:223], off
	s_add_i32 m0, s65, 0x2000
	v_lshl_add_u64 v[226:227], s[34:35], 0, v[128:129]
	global_load_lds_dwordx4 v[224:225], off
	s_mov_b32 m0, s41
	v_lshl_add_u64 v[228:229], s[34:35], 0, v[132:133]
	global_load_lds_dwordx4 v[226:227], off
	s_mov_b32 m0, s42
	s_nop 0
	global_load_lds_dwordx4 v[228:229], off
	s_waitcnt vmcnt(8)
	s_waitcnt lgkmcnt(0)
	s_barrier
	s_setprio 1
	s_waitcnt lgkmcnt(0)
	v_mfma_f32_16x16x32_bf16 v[60:63], v[144:147], v[188:191], v[60:63]
	v_mfma_f32_16x16x32_bf16 v[60:63], v[148:151], v[192:195], v[60:63]
	v_mfma_f32_16x16x32_bf16 v[56:59], v[168:171], v[192:195], v[56:59]
	v_mfma_f32_16x16x32_bf16 v[56:59], v[164:167], v[188:191], v[56:59]
	v_mfma_f32_16x16x32_bf16 v[52:55], v[172:175], v[188:191], v[52:55]
	v_mfma_f32_16x16x32_bf16 v[52:55], v[176:179], v[192:195], v[52:55]
	v_mfma_f32_16x16x32_bf16 v[48:51], v[184:187], v[192:195], v[48:51]
	v_mfma_f32_16x16x32_bf16 v[48:51], v[180:183], v[188:191], v[48:51]
	v_mfma_f32_16x16x32_bf16 v[32:35], v[180:183], v[196:199], v[32:35]
	v_mfma_f32_16x16x32_bf16 v[32:35], v[184:187], v[200:203], v[32:35]
	v_mfma_f32_16x16x32_bf16 v[36:39], v[176:179], v[200:203], v[36:39]
	v_mfma_f32_16x16x32_bf16 v[36:39], v[172:175], v[196:199], v[36:39]
	v_mfma_f32_16x16x32_bf16 v[40:43], v[164:167], v[196:199], v[40:43]
	v_mfma_f32_16x16x32_bf16 v[40:43], v[168:171], v[200:203], v[40:43]
	v_mfma_f32_16x16x32_bf16 v[44:47], v[148:151], v[200:203], v[44:47]
	v_mfma_f32_16x16x32_bf16 v[44:47], v[144:147], v[196:199], v[44:47]
	v_mfma_f32_16x16x32_bf16 v[28:31], v[144:147], v[204:207], v[28:31]
	v_mfma_f32_16x16x32_bf16 v[28:31], v[148:151], v[208:211], v[28:31]
	v_mfma_f32_16x16x32_bf16 v[24:27], v[168:171], v[208:211], v[24:27]
	v_mfma_f32_16x16x32_bf16 v[24:27], v[164:167], v[204:207], v[24:27]
	v_mfma_f32_16x16x32_bf16 v[20:23], v[172:175], v[204:207], v[20:23]
	v_mfma_f32_16x16x32_bf16 v[20:23], v[176:179], v[208:211], v[20:23]
	v_mfma_f32_16x16x32_bf16 v[16:19], v[184:187], v[208:211], v[16:19]
	v_mfma_f32_16x16x32_bf16 v[16:19], v[180:183], v[204:207], v[16:19]
	v_mfma_f32_16x16x32_bf16 v[0:3], v[180:183], v[212:215], v[0:3]
	v_mfma_f32_16x16x32_bf16 v[0:3], v[184:187], v[216:219], v[0:3]
	v_mfma_f32_16x16x32_bf16 v[4:7], v[176:179], v[216:219], v[4:7]
	v_mfma_f32_16x16x32_bf16 v[4:7], v[172:175], v[212:215], v[4:7]
	v_mfma_f32_16x16x32_bf16 v[8:11], v[164:167], v[212:215], v[8:11]
	v_mfma_f32_16x16x32_bf16 v[8:11], v[168:171], v[216:219], v[8:11]
	v_mfma_f32_16x16x32_bf16 v[12:15], v[148:151], v[216:219], v[12:15]
	v_mfma_f32_16x16x32_bf16 v[12:15], v[144:147], v[212:215], v[12:15]
	s_setprio 0
	s_barrier
	s_add_i32 s65, 0, 0x18000
	s_add_i32 s66, 0, 0x1c000
	v_add_u32_e32 v168, s65, v155
	v_add_u32_e32 v184, s66, v155
	ds_read_b128 v[144:147], v168
	ds_read_b128 v[148:151], v168 offset:1024
	ds_read_b128 v[164:167], v168 offset:2048
	ds_read_b128 v[168:171], v168 offset:3072
	ds_read_b128 v[172:175], v184
	ds_read_b128 v[176:179], v184 offset:1024
	ds_read_b128 v[180:183], v184 offset:2048
	ds_read_b128 v[184:187], v184 offset:3072
	s_add_u32 s34, s34, s8
	s_addc_u32 s35, s35, s9
	s_mov_b32 m0, s43
	v_lshl_add_u64 v[230:231], s[34:35], 0, v[128:129]
	ds_read_b128 v[188:191], v159 offset:32768
	ds_read_b128 v[192:195], v159 offset:33792
	ds_read_b128 v[196:199], v159 offset:34816
	ds_read_b128 v[200:203], v159 offset:35840
	ds_read_b128 v[204:207], v159 offset:36864
	ds_read_b128 v[208:211], v159 offset:37888
	ds_read_b128 v[212:215], v159 offset:38912
	ds_read_b128 v[216:219], v159 offset:39936
	global_load_lds_dwordx4 v[230:231], off
	v_lshl_add_u64 v[230:231], s[34:35], 0, v[132:133]
	s_mov_b32 m0, s44
	s_nop 0
	global_load_lds_dwordx4 v[230:231], off
	s_waitcnt vmcnt(8)
	s_waitcnt lgkmcnt(0)
	s_barrier
	s_setprio 1
	s_waitcnt lgkmcnt(0)
	v_mfma_f32_16x16x32_bf16 v[120:123], v[144:147], v[188:191], v[120:123]
	v_mfma_f32_16x16x32_bf16 v[120:123], v[148:151], v[192:195], v[120:123]
	v_mfma_f32_16x16x32_bf16 v[124:127], v[168:171], v[192:195], v[124:127]
	v_mfma_f32_16x16x32_bf16 v[124:127], v[164:167], v[188:191], v[124:127]
	v_mfma_f32_16x16x32_bf16 v[116:119], v[172:175], v[188:191], v[116:119]
	v_mfma_f32_16x16x32_bf16 v[116:119], v[176:179], v[192:195], v[116:119]
	v_mfma_f32_16x16x32_bf16 v[112:115], v[184:187], v[192:195], v[112:115]
	v_mfma_f32_16x16x32_bf16 v[112:115], v[180:183], v[188:191], v[112:115]
	v_mfma_f32_16x16x32_bf16 v[96:99], v[180:183], v[196:199], v[96:99]
	v_mfma_f32_16x16x32_bf16 v[96:99], v[184:187], v[200:203], v[96:99]
	v_mfma_f32_16x16x32_bf16 v[100:103], v[176:179], v[200:203], v[100:103]
	v_mfma_f32_16x16x32_bf16 v[100:103], v[172:175], v[196:199], v[100:103]
	v_mfma_f32_16x16x32_bf16 v[104:107], v[164:167], v[196:199], v[104:107]
	v_mfma_f32_16x16x32_bf16 v[104:107], v[168:171], v[200:203], v[104:107]
	v_mfma_f32_16x16x32_bf16 v[108:111], v[148:151], v[200:203], v[108:111]
	v_mfma_f32_16x16x32_bf16 v[108:111], v[144:147], v[196:199], v[108:111]
	v_mfma_f32_16x16x32_bf16 v[92:95], v[144:147], v[204:207], v[92:95]
	v_mfma_f32_16x16x32_bf16 v[92:95], v[148:151], v[208:211], v[92:95]
	v_mfma_f32_16x16x32_bf16 v[88:91], v[168:171], v[208:211], v[88:91]
	v_mfma_f32_16x16x32_bf16 v[88:91], v[164:167], v[204:207], v[88:91]
	v_mfma_f32_16x16x32_bf16 v[84:87], v[172:175], v[204:207], v[84:87]
	v_mfma_f32_16x16x32_bf16 v[84:87], v[176:179], v[208:211], v[84:87]
	v_mfma_f32_16x16x32_bf16 v[80:83], v[184:187], v[208:211], v[80:83]
	v_mfma_f32_16x16x32_bf16 v[80:83], v[180:183], v[204:207], v[80:83]
	v_mfma_f32_16x16x32_bf16 v[64:67], v[180:183], v[212:215], v[64:67]
	v_mfma_f32_16x16x32_bf16 v[64:67], v[184:187], v[216:219], v[64:67]
	v_mfma_f32_16x16x32_bf16 v[68:71], v[176:179], v[216:219], v[68:71]
	v_mfma_f32_16x16x32_bf16 v[68:71], v[172:175], v[212:215], v[68:71]
	v_mfma_f32_16x16x32_bf16 v[72:75], v[164:167], v[212:215], v[72:75]
	v_mfma_f32_16x16x32_bf16 v[72:75], v[168:171], v[216:219], v[72:75]
	v_mfma_f32_16x16x32_bf16 v[76:79], v[148:151], v[216:219], v[76:79]
	v_mfma_f32_16x16x32_bf16 v[76:79], v[144:147], v[212:215], v[76:79]
	s_setprio 0
	s_barrier
	s_add_i32 s34, s65, s40
	v_lshl_add_u64 v[152:153], v[152:153], 0, s[14:15]
	s_mov_b32 m0, s34
	ds_read_b128 v[188:191], v159 offset:49152
	ds_read_b128 v[192:195], v159 offset:50176
	ds_read_b128 v[196:199], v159 offset:51200
	ds_read_b128 v[200:203], v159 offset:52224
	ds_read_b128 v[204:207], v159 offset:53248
	ds_read_b128 v[208:211], v159 offset:54272
	ds_read_b128 v[212:215], v159 offset:55296
	ds_read_b128 v[216:219], v159 offset:56320
	global_load_lds_dwordx4 v[152:153], off
	v_lshl_add_u64 v[152:153], v[160:161], 0, s[14:15]
	s_add_i32 m0, s34, 0x2000
	s_add_i32 s34, s66, s40
	global_load_lds_dwordx4 v[152:153], off
	v_lshl_add_u64 v[152:153], v[222:223], 0, s[14:15]
	s_mov_b32 m0, s34
	s_nop 0
	global_load_lds_dwordx4 v[152:153], off
	v_lshl_add_u64 v[152:153], v[224:225], 0, s[14:15]
	s_add_i32 m0, s34, 0x2000
	s_nop 0
	global_load_lds_dwordx4 v[152:153], off
	v_lshl_add_u64 v[152:153], v[226:227], 0, s[14:15]
	s_mov_b32 m0, s46
	s_nop 0
	global_load_lds_dwordx4 v[152:153], off
	v_lshl_add_u64 v[152:153], v[228:229], 0, s[14:15]
	s_mov_b32 m0, s47
	s_nop 0
	global_load_lds_dwordx4 v[152:153], off
	s_waitcnt vmcnt(8)
	s_waitcnt lgkmcnt(0)
	s_barrier
	s_setprio 1
	s_waitcnt lgkmcnt(0)
	v_mfma_f32_16x16x32_bf16 v[60:63], v[144:147], v[188:191], v[60:63]
	v_mfma_f32_16x16x32_bf16 v[60:63], v[148:151], v[192:195], v[60:63]
	v_mfma_f32_16x16x32_bf16 v[56:59], v[168:171], v[192:195], v[56:59]
	v_mfma_f32_16x16x32_bf16 v[56:59], v[164:167], v[188:191], v[56:59]
	v_mfma_f32_16x16x32_bf16 v[52:55], v[172:175], v[188:191], v[52:55]
	v_mfma_f32_16x16x32_bf16 v[52:55], v[176:179], v[192:195], v[52:55]
	v_mfma_f32_16x16x32_bf16 v[48:51], v[184:187], v[192:195], v[48:51]
	v_mfma_f32_16x16x32_bf16 v[48:51], v[180:183], v[188:191], v[48:51]
	v_mfma_f32_16x16x32_bf16 v[32:35], v[180:183], v[196:199], v[32:35]
	v_mfma_f32_16x16x32_bf16 v[32:35], v[184:187], v[200:203], v[32:35]
	v_mfma_f32_16x16x32_bf16 v[36:39], v[176:179], v[200:203], v[36:39]
	v_mfma_f32_16x16x32_bf16 v[36:39], v[172:175], v[196:199], v[36:39]
	v_mfma_f32_16x16x32_bf16 v[40:43], v[164:167], v[196:199], v[40:43]
	v_mfma_f32_16x16x32_bf16 v[40:43], v[168:171], v[200:203], v[40:43]
	v_mfma_f32_16x16x32_bf16 v[44:47], v[148:151], v[200:203], v[44:47]
	v_mfma_f32_16x16x32_bf16 v[44:47], v[144:147], v[196:199], v[44:47]
	v_mfma_f32_16x16x32_bf16 v[28:31], v[144:147], v[204:207], v[28:31]
	v_mfma_f32_16x16x32_bf16 v[28:31], v[148:151], v[208:211], v[28:31]
	v_mfma_f32_16x16x32_bf16 v[24:27], v[168:171], v[208:211], v[24:27]
	v_mfma_f32_16x16x32_bf16 v[24:27], v[164:167], v[204:207], v[24:27]
	v_mfma_f32_16x16x32_bf16 v[20:23], v[172:175], v[204:207], v[20:23]
	v_mfma_f32_16x16x32_bf16 v[20:23], v[176:179], v[208:211], v[20:23]
	v_mfma_f32_16x16x32_bf16 v[16:19], v[184:187], v[208:211], v[16:19]
	v_mfma_f32_16x16x32_bf16 v[16:19], v[180:183], v[204:207], v[16:19]
	v_mfma_f32_16x16x32_bf16 v[0:3], v[180:183], v[212:215], v[0:3]
	v_mfma_f32_16x16x32_bf16 v[0:3], v[184:187], v[216:219], v[0:3]
	v_mfma_f32_16x16x32_bf16 v[4:7], v[176:179], v[216:219], v[4:7]
	v_mfma_f32_16x16x32_bf16 v[4:7], v[172:175], v[212:215], v[4:7]
	v_mfma_f32_16x16x32_bf16 v[8:11], v[164:167], v[212:215], v[8:11]
	v_mfma_f32_16x16x32_bf16 v[8:11], v[168:171], v[216:219], v[8:11]
	v_mfma_f32_16x16x32_bf16 v[12:15], v[148:151], v[216:219], v[12:15]
	v_mfma_f32_16x16x32_bf16 v[12:15], v[144:147], v[212:215], v[12:15]
	s_setprio 0
	s_barrier
	s_add_u32 s30, s30, 0x100
	s_addc_u32 s31, s31, 0
	s_add_u32 s62, s62, 0x100
	s_addc_u32 s63, s63, 0
	s_cmp_ge_i32 s64, s48
	s_mov_b32 s34, s64
	s_cbranch_scc0 .LBB0_592

.LBB0_763:
	ds_read_b128 v[128:131], v181
	ds_read_b128 v[132:135], v181 offset:1024
	ds_read_b128 v[136:139], v181 offset:2048
	ds_read_b128 v[140:143], v181 offset:3072
	ds_read_b128 v[144:147], v182
	ds_read_b128 v[148:151], v182 offset:1024
	ds_read_b128 v[168:171], v182 offset:2048
	ds_read_b128 v[172:175], v182 offset:3072
	s_add_i32 s54, s26, 2
	s_add_u32 s55, s24, 0x80
	s_addc_u32 s27, s25, 0
	s_cmp_eq_u32 s43, s26
	s_cselect_b32 s26, s2, s55
	s_cselect_b32 s27, s3, s27
	s_cselect_b32 s61, s23, s53
	s_cselect_b32 s60, s22, s52
	v_lshl_add_u64 v[176:177], s[24:25], 0, v[160:161]
	s_add_i32 m0, s35, 0xc000
	ds_read_b128 v[184:187], v183
	ds_read_b128 v[188:191], v183 offset:1024
	ds_read_b128 v[192:195], v183 offset:2048
	ds_read_b128 v[196:199], v183 offset:3072
	ds_read_b128 v[200:203], v183 offset:4096
	ds_read_b128 v[204:207], v183 offset:5120
	ds_read_b128 v[208:211], v183 offset:6144
	ds_read_b128 v[212:215], v183 offset:7168
	global_load_lds_dwordx4 v[176:177], off
	v_lshl_add_u64 v[176:177], s[24:25], 0, v[162:163]
	s_add_i32 m0, s35, 0xe000
	s_nop 0
	global_load_lds_dwordx4 v[176:177], off
	s_waitcnt vmcnt(8)
	s_waitcnt lgkmcnt(0)
	s_barrier
	s_setprio 1
	s_waitcnt lgkmcnt(0)
	v_mfma_f32_16x16x32_bf16 v[120:123], v[128:131], v[184:187], v[120:123]
	v_mfma_f32_16x16x32_bf16 v[120:123], v[132:135], v[188:191], v[120:123]
	v_mfma_f32_16x16x32_bf16 v[124:127], v[140:143], v[188:191], v[124:127]
	v_mfma_f32_16x16x32_bf16 v[124:127], v[136:139], v[184:187], v[124:127]
	v_mfma_f32_16x16x32_bf16 v[116:119], v[144:147], v[184:187], v[116:119]
	v_mfma_f32_16x16x32_bf16 v[116:119], v[148:151], v[188:191], v[116:119]
	v_mfma_f32_16x16x32_bf16 v[112:115], v[172:175], v[188:191], v[112:115]
	v_mfma_f32_16x16x32_bf16 v[112:115], v[168:171], v[184:187], v[112:115]
	v_mfma_f32_16x16x32_bf16 v[96:99], v[168:171], v[192:195], v[96:99]
	v_mfma_f32_16x16x32_bf16 v[96:99], v[172:175], v[196:199], v[96:99]
	v_mfma_f32_16x16x32_bf16 v[100:103], v[148:151], v[196:199], v[100:103]
	v_mfma_f32_16x16x32_bf16 v[100:103], v[144:147], v[192:195], v[100:103]
	v_mfma_f32_16x16x32_bf16 v[104:107], v[136:139], v[192:195], v[104:107]
	v_mfma_f32_16x16x32_bf16 v[104:107], v[140:143], v[196:199], v[104:107]
	v_mfma_f32_16x16x32_bf16 v[108:111], v[132:135], v[196:199], v[108:111]
	v_mfma_f32_16x16x32_bf16 v[108:111], v[128:131], v[192:195], v[108:111]
	v_mfma_f32_16x16x32_bf16 v[92:95], v[128:131], v[200:203], v[92:95]
	v_mfma_f32_16x16x32_bf16 v[92:95], v[132:135], v[204:207], v[92:95]
	v_mfma_f32_16x16x32_bf16 v[88:91], v[140:143], v[204:207], v[88:91]
	v_mfma_f32_16x16x32_bf16 v[88:91], v[136:139], v[200:203], v[88:91]
	v_mfma_f32_16x16x32_bf16 v[84:87], v[144:147], v[200:203], v[84:87]
	v_mfma_f32_16x16x32_bf16 v[84:87], v[148:151], v[204:207], v[84:87]
	v_mfma_f32_16x16x32_bf16 v[80:83], v[172:175], v[204:207], v[80:83]
	v_mfma_f32_16x16x32_bf16 v[80:83], v[168:171], v[200:203], v[80:83]
	v_mfma_f32_16x16x32_bf16 v[64:67], v[168:171], v[208:211], v[64:67]
	v_mfma_f32_16x16x32_bf16 v[64:67], v[172:175], v[212:215], v[64:67]
	v_mfma_f32_16x16x32_bf16 v[68:71], v[148:151], v[212:215], v[68:71]
	v_mfma_f32_16x16x32_bf16 v[68:71], v[144:147], v[208:211], v[68:71]
	v_mfma_f32_16x16x32_bf16 v[72:75], v[136:139], v[208:211], v[72:75]
	v_mfma_f32_16x16x32_bf16 v[72:75], v[140:143], v[212:215], v[72:75]
	v_mfma_f32_16x16x32_bf16 v[76:79], v[132:135], v[212:215], v[76:79]
	v_mfma_f32_16x16x32_bf16 v[76:79], v[128:131], v[208:211], v[76:79]
	s_setprio 0
	s_barrier
	s_add_i32 s55, s46, s34
	v_lshl_add_u64 v[176:177], s[60:61], 0, v[154:155]
	s_mov_b32 m0, s55
	ds_read_b128 v[184:187], v183 offset:16384
	ds_read_b128 v[188:191], v183 offset:17408
	ds_read_b128 v[192:195], v183 offset:18432
	ds_read_b128 v[196:199], v183 offset:19456
	ds_read_b128 v[200:203], v183 offset:20480
	ds_read_b128 v[204:207], v183 offset:21504
	ds_read_b128 v[208:211], v183 offset:22528
	ds_read_b128 v[212:215], v183 offset:23552
	global_load_lds_dwordx4 v[176:177], off
	s_add_i32 m0, s55, 0x2000
	v_lshl_add_u64 v[216:217], s[60:61], 0, v[158:159]
	s_add_u32 s60, s60, s8
	s_addc_u32 s61, s61, s9
	s_add_i32 s55, s47, s34
	global_load_lds_dwordx4 v[216:217], off
	v_lshl_add_u64 v[218:219], s[60:61], 0, v[154:155]
	s_mov_b32 m0, s55
	v_lshl_add_u64 v[222:223], s[60:61], 0, v[158:159]
	global_load_lds_dwordx4 v[218:219], off
	s_add_i32 m0, s55, 0x2000
	v_lshl_add_u64 v[224:225], s[26:27], 0, v[152:153]
	global_load_lds_dwordx4 v[222:223], off
	s_mov_b32 m0, s35
	v_lshl_add_u64 v[226:227], s[26:27], 0, v[156:157]
	global_load_lds_dwordx4 v[224:225], off
	s_mov_b32 m0, s36
	s_nop 0
	global_load_lds_dwordx4 v[226:227], off
	s_waitcnt vmcnt(8)
	s_waitcnt lgkmcnt(0)
	s_barrier
	s_setprio 1
	s_waitcnt lgkmcnt(0)
	v_mfma_f32_16x16x32_bf16 v[60:63], v[128:131], v[184:187], v[60:63]
	v_mfma_f32_16x16x32_bf16 v[60:63], v[132:135], v[188:191], v[60:63]
	v_mfma_f32_16x16x32_bf16 v[56:59], v[140:143], v[188:191], v[56:59]
	v_mfma_f32_16x16x32_bf16 v[56:59], v[136:139], v[184:187], v[56:59]
	v_mfma_f32_16x16x32_bf16 v[52:55], v[144:147], v[184:187], v[52:55]
	v_mfma_f32_16x16x32_bf16 v[52:55], v[148:151], v[188:191], v[52:55]
	v_mfma_f32_16x16x32_bf16 v[48:51], v[172:175], v[188:191], v[48:51]
	v_mfma_f32_16x16x32_bf16 v[48:51], v[168:171], v[184:187], v[48:51]
	v_mfma_f32_16x16x32_bf16 v[32:35], v[168:171], v[192:195], v[32:35]
	v_mfma_f32_16x16x32_bf16 v[32:35], v[172:175], v[196:199], v[32:35]
	v_mfma_f32_16x16x32_bf16 v[36:39], v[148:151], v[196:199], v[36:39]
	v_mfma_f32_16x16x32_bf16 v[36:39], v[144:147], v[192:195], v[36:39]
	v_mfma_f32_16x16x32_bf16 v[40:43], v[136:139], v[192:195], v[40:43]
	v_mfma_f32_16x16x32_bf16 v[40:43], v[140:143], v[196:199], v[40:43]
	v_mfma_f32_16x16x32_bf16 v[44:47], v[132:135], v[196:199], v[44:47]
	v_mfma_f32_16x16x32_bf16 v[44:47], v[128:131], v[192:195], v[44:47]
	v_mfma_f32_16x16x32_bf16 v[28:31], v[128:131], v[200:203], v[28:31]
	v_mfma_f32_16x16x32_bf16 v[28:31], v[132:135], v[204:207], v[28:31]
	v_mfma_f32_16x16x32_bf16 v[24:27], v[140:143], v[204:207], v[24:27]
	v_mfma_f32_16x16x32_bf16 v[24:27], v[136:139], v[200:203], v[24:27]
	v_mfma_f32_16x16x32_bf16 v[20:23], v[144:147], v[200:203], v[20:23]
	v_mfma_f32_16x16x32_bf16 v[20:23], v[148:151], v[204:207], v[20:23]
	v_mfma_f32_16x16x32_bf16 v[16:19], v[172:175], v[204:207], v[16:19]
	v_mfma_f32_16x16x32_bf16 v[16:19], v[168:171], v[200:203], v[16:19]
	v_mfma_f32_16x16x32_bf16 v[0:3], v[168:171], v[208:211], v[0:3]
	v_mfma_f32_16x16x32_bf16 v[0:3], v[172:175], v[212:215], v[0:3]
	v_mfma_f32_16x16x32_bf16 v[4:7], v[148:151], v[212:215], v[4:7]
	v_mfma_f32_16x16x32_bf16 v[4:7], v[144:147], v[208:211], v[4:7]
	v_mfma_f32_16x16x32_bf16 v[8:11], v[136:139], v[208:211], v[8:11]
	v_mfma_f32_16x16x32_bf16 v[8:11], v[140:143], v[212:215], v[8:11]
	v_mfma_f32_16x16x32_bf16 v[12:15], v[132:135], v[212:215], v[12:15]
	v_mfma_f32_16x16x32_bf16 v[12:15], v[128:131], v[208:211], v[12:15]
	s_setprio 0
	s_barrier
	s_add_i32 s55, 0, 0x18000
	s_add_i32 s60, 0, 0x1c000
	v_add_u32_e32 v140, s55, v179
	v_add_u32_e32 v172, s60, v179
	ds_read_b128 v[128:131], v140
	ds_read_b128 v[132:135], v140 offset:1024
	ds_read_b128 v[136:139], v140 offset:2048
	ds_read_b128 v[140:143], v140 offset:3072
	ds_read_b128 v[144:147], v172
	ds_read_b128 v[148:151], v172 offset:1024
	ds_read_b128 v[168:171], v172 offset:2048
	ds_read_b128 v[172:175], v172 offset:3072
	s_add_u32 s26, s26, s8
	s_addc_u32 s27, s27, s9
	s_mov_b32 m0, s37
	v_lshl_add_u64 v[228:229], s[26:27], 0, v[152:153]
	ds_read_b128 v[184:187], v183 offset:32768
	ds_read_b128 v[188:191], v183 offset:33792
	ds_read_b128 v[192:195], v183 offset:34816
	ds_read_b128 v[196:199], v183 offset:35840
	ds_read_b128 v[200:203], v183 offset:36864
	ds_read_b128 v[204:207], v183 offset:37888
	ds_read_b128 v[208:211], v183 offset:38912
	ds_read_b128 v[212:215], v183 offset:39936
	global_load_lds_dwordx4 v[228:229], off
	v_lshl_add_u64 v[228:229], s[26:27], 0, v[156:157]
	s_mov_b32 m0, s38
	s_nop 0
	global_load_lds_dwordx4 v[228:229], off
	s_waitcnt vmcnt(8)
	s_waitcnt lgkmcnt(0)
	s_barrier
	s_setprio 1
	s_waitcnt lgkmcnt(0)
	v_mfma_f32_16x16x32_bf16 v[120:123], v[128:131], v[184:187], v[120:123]
	v_mfma_f32_16x16x32_bf16 v[120:123], v[132:135], v[188:191], v[120:123]
	v_mfma_f32_16x16x32_bf16 v[124:127], v[140:143], v[188:191], v[124:127]
	v_mfma_f32_16x16x32_bf16 v[124:127], v[136:139], v[184:187], v[124:127]
	v_mfma_f32_16x16x32_bf16 v[116:119], v[144:147], v[184:187], v[116:119]
	v_mfma_f32_16x16x32_bf16 v[116:119], v[148:151], v[188:191], v[116:119]
	v_mfma_f32_16x16x32_bf16 v[112:115], v[172:175], v[188:191], v[112:115]
	v_mfma_f32_16x16x32_bf16 v[112:115], v[168:171], v[184:187], v[112:115]
	v_mfma_f32_16x16x32_bf16 v[96:99], v[168:171], v[192:195], v[96:99]
	v_mfma_f32_16x16x32_bf16 v[96:99], v[172:175], v[196:199], v[96:99]
	v_mfma_f32_16x16x32_bf16 v[100:103], v[148:151], v[196:199], v[100:103]
	v_mfma_f32_16x16x32_bf16 v[100:103], v[144:147], v[192:195], v[100:103]
	v_mfma_f32_16x16x32_bf16 v[104:107], v[136:139], v[192:195], v[104:107]
	v_mfma_f32_16x16x32_bf16 v[104:107], v[140:143], v[196:199], v[104:107]
	v_mfma_f32_16x16x32_bf16 v[108:111], v[132:135], v[196:199], v[108:111]
	v_mfma_f32_16x16x32_bf16 v[108:111], v[128:131], v[192:195], v[108:111]
	v_mfma_f32_16x16x32_bf16 v[92:95], v[128:131], v[200:203], v[92:95]
	v_mfma_f32_16x16x32_bf16 v[92:95], v[132:135], v[204:207], v[92:95]
	v_mfma_f32_16x16x32_bf16 v[88:91], v[140:143], v[204:207], v[88:91]
	v_mfma_f32_16x16x32_bf16 v[88:91], v[136:139], v[200:203], v[88:91]
	v_mfma_f32_16x16x32_bf16 v[84:87], v[144:147], v[200:203], v[84:87]
	v_mfma_f32_16x16x32_bf16 v[84:87], v[148:151], v[204:207], v[84:87]
	v_mfma_f32_16x16x32_bf16 v[80:83], v[172:175], v[204:207], v[80:83]
	v_mfma_f32_16x16x32_bf16 v[80:83], v[168:171], v[200:203], v[80:83]
	v_mfma_f32_16x16x32_bf16 v[64:67], v[168:171], v[208:211], v[64:67]
	v_mfma_f32_16x16x32_bf16 v[64:67], v[172:175], v[212:215], v[64:67]
	v_mfma_f32_16x16x32_bf16 v[68:71], v[148:151], v[212:215], v[68:71]
	v_mfma_f32_16x16x32_bf16 v[68:71], v[144:147], v[208:211], v[68:71]
	v_mfma_f32_16x16x32_bf16 v[72:75], v[136:139], v[208:211], v[72:75]
	v_mfma_f32_16x16x32_bf16 v[72:75], v[140:143], v[212:215], v[72:75]
	v_mfma_f32_16x16x32_bf16 v[76:79], v[132:135], v[212:215], v[76:79]
	v_mfma_f32_16x16x32_bf16 v[76:79], v[128:131], v[208:211], v[76:79]
	s_setprio 0
	s_barrier
	s_add_i32 s26, s55, s34
	v_lshl_add_u64 v[176:177], v[176:177], 0, s[16:17]
	s_mov_b32 m0, s26
	ds_read_b128 v[184:187], v183 offset:49152
	ds_read_b128 v[188:191], v183 offset:50176
	ds_read_b128 v[192:195], v183 offset:51200
	ds_read_b128 v[196:199], v183 offset:52224
	ds_read_b128 v[200:203], v183 offset:53248
	ds_read_b128 v[204:207], v183 offset:54272
	ds_read_b128 v[208:211], v183 offset:55296
	ds_read_b128 v[212:215], v183 offset:56320
	global_load_lds_dwordx4 v[176:177], off
	v_lshl_add_u64 v[176:177], v[216:217], 0, s[16:17]
	s_add_i32 m0, s26, 0x2000
	s_add_i32 s26, s60, s34
	global_load_lds_dwordx4 v[176:177], off
	v_lshl_add_u64 v[176:177], v[218:219], 0, s[16:17]
	s_mov_b32 m0, s26
	s_nop 0
	global_load_lds_dwordx4 v[176:177], off
	v_lshl_add_u64 v[176:177], v[222:223], 0, s[16:17]
	s_add_i32 m0, s26, 0x2000
	s_nop 0
	global_load_lds_dwordx4 v[176:177], off
	v_lshl_add_u64 v[176:177], v[224:225], 0, s[16:17]
	s_mov_b32 m0, s40
	s_nop 0
	global_load_lds_dwordx4 v[176:177], off
	v_lshl_add_u64 v[176:177], v[226:227], 0, s[16:17]
	s_mov_b32 m0, s41
	s_nop 0
	global_load_lds_dwordx4 v[176:177], off
	s_waitcnt vmcnt(8)
	s_waitcnt lgkmcnt(0)
	s_barrier
	s_setprio 1
	s_waitcnt lgkmcnt(0)
	v_mfma_f32_16x16x32_bf16 v[60:63], v[128:131], v[184:187], v[60:63]
	v_mfma_f32_16x16x32_bf16 v[60:63], v[132:135], v[188:191], v[60:63]
	v_mfma_f32_16x16x32_bf16 v[56:59], v[140:143], v[188:191], v[56:59]
	v_mfma_f32_16x16x32_bf16 v[56:59], v[136:139], v[184:187], v[56:59]
	v_mfma_f32_16x16x32_bf16 v[52:55], v[144:147], v[184:187], v[52:55]
	v_mfma_f32_16x16x32_bf16 v[52:55], v[148:151], v[188:191], v[52:55]
	v_mfma_f32_16x16x32_bf16 v[48:51], v[172:175], v[188:191], v[48:51]
	v_mfma_f32_16x16x32_bf16 v[48:51], v[168:171], v[184:187], v[48:51]
	v_mfma_f32_16x16x32_bf16 v[32:35], v[168:171], v[192:195], v[32:35]
	v_mfma_f32_16x16x32_bf16 v[32:35], v[172:175], v[196:199], v[32:35]
	v_mfma_f32_16x16x32_bf16 v[36:39], v[148:151], v[196:199], v[36:39]
	v_mfma_f32_16x16x32_bf16 v[36:39], v[144:147], v[192:195], v[36:39]
	v_mfma_f32_16x16x32_bf16 v[40:43], v[136:139], v[192:195], v[40:43]
	v_mfma_f32_16x16x32_bf16 v[40:43], v[140:143], v[196:199], v[40:43]
	v_mfma_f32_16x16x32_bf16 v[44:47], v[132:135], v[196:199], v[44:47]
	v_mfma_f32_16x16x32_bf16 v[44:47], v[128:131], v[192:195], v[44:47]
	v_mfma_f32_16x16x32_bf16 v[28:31], v[128:131], v[200:203], v[28:31]
	v_mfma_f32_16x16x32_bf16 v[28:31], v[132:135], v[204:207], v[28:31]
	v_mfma_f32_16x16x32_bf16 v[24:27], v[140:143], v[204:207], v[24:27]
	v_mfma_f32_16x16x32_bf16 v[24:27], v[136:139], v[200:203], v[24:27]
	v_mfma_f32_16x16x32_bf16 v[20:23], v[144:147], v[200:203], v[20:23]
	v_mfma_f32_16x16x32_bf16 v[20:23], v[148:151], v[204:207], v[20:23]
	v_mfma_f32_16x16x32_bf16 v[16:19], v[172:175], v[204:207], v[16:19]
	v_mfma_f32_16x16x32_bf16 v[16:19], v[168:171], v[200:203], v[16:19]
	v_mfma_f32_16x16x32_bf16 v[0:3], v[168:171], v[208:211], v[0:3]
	v_mfma_f32_16x16x32_bf16 v[0:3], v[172:175], v[212:215], v[0:3]
	v_mfma_f32_16x16x32_bf16 v[4:7], v[148:151], v[212:215], v[4:7]
	v_mfma_f32_16x16x32_bf16 v[4:7], v[144:147], v[208:211], v[4:7]
	v_mfma_f32_16x16x32_bf16 v[8:11], v[136:139], v[208:211], v[8:11]
	v_mfma_f32_16x16x32_bf16 v[8:11], v[140:143], v[212:215], v[8:11]
	v_mfma_f32_16x16x32_bf16 v[12:15], v[132:135], v[212:215], v[12:15]
	v_mfma_f32_16x16x32_bf16 v[12:15], v[128:131], v[208:211], v[12:15]
	s_setprio 0
	s_barrier
	s_add_u32 s24, s24, 0x100
	s_addc_u32 s25, s25, 0
	s_add_u32 s52, s52, 0x100
	s_addc_u32 s53, s53, 0
	s_cmp_ge_i32 s54, s42
	s_mov_b32 s26, s54
	s_cbranch_scc0 .LBB0_763

.LBB0_849:
	ds_read_b128 v[112:115], v209
	ds_read_b128 v[116:119], v209 offset:1024
	ds_read_b128 v[120:123], v209 offset:2048
	ds_read_b128 v[128:131], v209 offset:3072
	ds_read_b128 v[144:147], v210
	ds_read_b128 v[148:151], v210 offset:1024
	ds_read_b128 v[152:155], v210 offset:2048
	ds_read_b128 v[156:159], v210 offset:3072
	s_add_i32 s62, s30, 2
	s_add_u32 s63, s28, 0x80
	s_addc_u32 s31, s29, 0
	s_cmp_eq_u32 s46, s30
	s_cselect_b32 s30, s4, s63
	s_cselect_b32 s31, s5, s31
	s_cselect_b32 s65, s27, s61
	s_cselect_b32 s64, s26, s60
	v_lshl_add_u64 v[204:205], s[28:29], 0, v[180:181]
	s_add_i32 m0, s38, 0xc000
	ds_read_b128 v[160:163], v211
	ds_read_b128 v[164:167], v211 offset:1024
	ds_read_b128 v[168:171], v211 offset:2048
	ds_read_b128 v[172:175], v211 offset:3072
	ds_read_b128 v[188:191], v211 offset:4096
	ds_read_b128 v[192:195], v211 offset:5120
	ds_read_b128 v[196:199], v211 offset:6144
	ds_read_b128 v[200:203], v211 offset:7168
	global_load_lds_dwordx4 v[204:205], off
	v_lshl_add_u64 v[204:205], s[28:29], 0, v[182:183]
	s_add_i32 m0, s38, 0xe000
	s_nop 0
	global_load_lds_dwordx4 v[204:205], off
	s_waitcnt vmcnt(8)
	s_waitcnt lgkmcnt(0)
	s_barrier
	s_setprio 1
	s_waitcnt lgkmcnt(0)
	v_mfma_f32_16x16x32_bf16 v[136:139], v[112:115], v[160:163], v[136:139]
	v_mfma_f32_16x16x32_bf16 v[136:139], v[116:119], v[164:167], v[136:139]
	v_mfma_f32_16x16x32_bf16 v[140:143], v[128:131], v[164:167], v[140:143]
	v_mfma_f32_16x16x32_bf16 v[140:143], v[120:123], v[160:163], v[140:143]
	v_mfma_f32_16x16x32_bf16 v[132:135], v[144:147], v[160:163], v[132:135]
	v_mfma_f32_16x16x32_bf16 v[132:135], v[148:151], v[164:167], v[132:135]
	v_mfma_f32_16x16x32_bf16 v[124:127], v[156:159], v[164:167], v[124:127]
	v_mfma_f32_16x16x32_bf16 v[124:127], v[152:155], v[160:163], v[124:127]
	v_mfma_f32_16x16x32_bf16 v[96:99], v[152:155], v[168:171], v[96:99]
	v_mfma_f32_16x16x32_bf16 v[96:99], v[156:159], v[172:175], v[96:99]
	v_mfma_f32_16x16x32_bf16 v[100:103], v[148:151], v[172:175], v[100:103]
	v_mfma_f32_16x16x32_bf16 v[100:103], v[144:147], v[168:171], v[100:103]
	v_mfma_f32_16x16x32_bf16 v[104:107], v[120:123], v[168:171], v[104:107]
	v_mfma_f32_16x16x32_bf16 v[104:107], v[128:131], v[172:175], v[104:107]
	v_mfma_f32_16x16x32_bf16 v[108:111], v[116:119], v[172:175], v[108:111]
	v_mfma_f32_16x16x32_bf16 v[108:111], v[112:115], v[168:171], v[108:111]
	v_mfma_f32_16x16x32_bf16 v[92:95], v[112:115], v[188:191], v[92:95]
	v_mfma_f32_16x16x32_bf16 v[92:95], v[116:119], v[192:195], v[92:95]
	v_mfma_f32_16x16x32_bf16 v[88:91], v[128:131], v[192:195], v[88:91]
	v_mfma_f32_16x16x32_bf16 v[88:91], v[120:123], v[188:191], v[88:91]
	v_mfma_f32_16x16x32_bf16 v[84:87], v[144:147], v[188:191], v[84:87]
	v_mfma_f32_16x16x32_bf16 v[84:87], v[148:151], v[192:195], v[84:87]
	v_mfma_f32_16x16x32_bf16 v[80:83], v[156:159], v[192:195], v[80:83]
	v_mfma_f32_16x16x32_bf16 v[80:83], v[152:155], v[188:191], v[80:83]
	v_mfma_f32_16x16x32_bf16 v[64:67], v[152:155], v[196:199], v[64:67]
	v_mfma_f32_16x16x32_bf16 v[64:67], v[156:159], v[200:203], v[64:67]
	v_mfma_f32_16x16x32_bf16 v[68:71], v[148:151], v[200:203], v[68:71]
	v_mfma_f32_16x16x32_bf16 v[68:71], v[144:147], v[196:199], v[68:71]
	v_mfma_f32_16x16x32_bf16 v[72:75], v[120:123], v[196:199], v[72:75]
	v_mfma_f32_16x16x32_bf16 v[72:75], v[128:131], v[200:203], v[72:75]
	v_mfma_f32_16x16x32_bf16 v[76:79], v[116:119], v[200:203], v[76:79]
	v_mfma_f32_16x16x32_bf16 v[76:79], v[112:115], v[196:199], v[76:79]
	s_setprio 0
	s_barrier
	s_add_i32 s63, s50, s37
	v_lshl_add_u64 v[204:205], s[64:65], 0, v[176:177]
	s_mov_b32 m0, s63
	ds_read_b128 v[160:163], v211 offset:16384
	ds_read_b128 v[164:167], v211 offset:17408
	ds_read_b128 v[168:171], v211 offset:18432
	ds_read_b128 v[172:175], v211 offset:19456
	ds_read_b128 v[188:191], v211 offset:20480
	ds_read_b128 v[192:195], v211 offset:21504
	ds_read_b128 v[196:199], v211 offset:22528
	ds_read_b128 v[200:203], v211 offset:23552
	global_load_lds_dwordx4 v[204:205], off
	s_add_i32 m0, s63, 0x2000
	v_lshl_add_u64 v[214:215], s[64:65], 0, v[178:179]
	s_add_u32 s64, s64, s10
	s_addc_u32 s65, s65, s11
	s_add_i32 s63, s51, s37
	global_load_lds_dwordx4 v[214:215], off
	v_lshl_add_u64 v[216:217], s[64:65], 0, v[176:177]
	s_mov_b32 m0, s63
	v_lshl_add_u64 v[218:219], s[64:65], 0, v[178:179]
	global_load_lds_dwordx4 v[216:217], off
	s_add_i32 m0, s63, 0x2000
	v_lshl_add_u64 v[222:223], s[30:31], 0, v[176:177]
	global_load_lds_dwordx4 v[218:219], off
	s_mov_b32 m0, s38
	v_lshl_add_u64 v[224:225], s[30:31], 0, v[178:179]
	global_load_lds_dwordx4 v[222:223], off
	s_mov_b32 m0, s39
	s_nop 0
	global_load_lds_dwordx4 v[224:225], off
	s_waitcnt vmcnt(8)
	s_waitcnt lgkmcnt(0)
	s_barrier
	s_setprio 1
	s_waitcnt lgkmcnt(0)
	v_mfma_f32_16x16x32_bf16 v[60:63], v[112:115], v[160:163], v[60:63]
	v_mfma_f32_16x16x32_bf16 v[60:63], v[116:119], v[164:167], v[60:63]
	v_mfma_f32_16x16x32_bf16 v[56:59], v[128:131], v[164:167], v[56:59]
	v_mfma_f32_16x16x32_bf16 v[56:59], v[120:123], v[160:163], v[56:59]
	v_mfma_f32_16x16x32_bf16 v[52:55], v[144:147], v[160:163], v[52:55]
	v_mfma_f32_16x16x32_bf16 v[52:55], v[148:151], v[164:167], v[52:55]
	v_mfma_f32_16x16x32_bf16 v[48:51], v[156:159], v[164:167], v[48:51]
	v_mfma_f32_16x16x32_bf16 v[48:51], v[152:155], v[160:163], v[48:51]
	v_mfma_f32_16x16x32_bf16 v[32:35], v[152:155], v[168:171], v[32:35]
	v_mfma_f32_16x16x32_bf16 v[32:35], v[156:159], v[172:175], v[32:35]
	v_mfma_f32_16x16x32_bf16 v[36:39], v[148:151], v[172:175], v[36:39]
	v_mfma_f32_16x16x32_bf16 v[36:39], v[144:147], v[168:171], v[36:39]
	v_mfma_f32_16x16x32_bf16 v[40:43], v[120:123], v[168:171], v[40:43]
	v_mfma_f32_16x16x32_bf16 v[40:43], v[128:131], v[172:175], v[40:43]
	v_mfma_f32_16x16x32_bf16 v[44:47], v[116:119], v[172:175], v[44:47]
	v_mfma_f32_16x16x32_bf16 v[44:47], v[112:115], v[168:171], v[44:47]
	v_mfma_f32_16x16x32_bf16 v[28:31], v[112:115], v[188:191], v[28:31]
	v_mfma_f32_16x16x32_bf16 v[28:31], v[116:119], v[192:195], v[28:31]
	v_mfma_f32_16x16x32_bf16 v[24:27], v[128:131], v[192:195], v[24:27]
	v_mfma_f32_16x16x32_bf16 v[24:27], v[120:123], v[188:191], v[24:27]
	v_mfma_f32_16x16x32_bf16 v[20:23], v[144:147], v[188:191], v[20:23]
	v_mfma_f32_16x16x32_bf16 v[20:23], v[148:151], v[192:195], v[20:23]
	v_mfma_f32_16x16x32_bf16 v[16:19], v[156:159], v[192:195], v[16:19]
	v_mfma_f32_16x16x32_bf16 v[16:19], v[152:155], v[188:191], v[16:19]
	v_mfma_f32_16x16x32_bf16 v[0:3], v[152:155], v[196:199], v[0:3]
	v_mfma_f32_16x16x32_bf16 v[0:3], v[156:159], v[200:203], v[0:3]
	v_mfma_f32_16x16x32_bf16 v[4:7], v[148:151], v[200:203], v[4:7]
	v_mfma_f32_16x16x32_bf16 v[4:7], v[144:147], v[196:199], v[4:7]
	v_mfma_f32_16x16x32_bf16 v[8:11], v[120:123], v[196:199], v[8:11]
	v_mfma_f32_16x16x32_bf16 v[8:11], v[128:131], v[200:203], v[8:11]
	v_mfma_f32_16x16x32_bf16 v[12:15], v[116:119], v[200:203], v[12:15]
	v_mfma_f32_16x16x32_bf16 v[12:15], v[112:115], v[196:199], v[12:15]
	s_setprio 0
	s_barrier
	s_add_i32 s63, 0, 0x18000
	s_add_i32 s64, 0, 0x1c000
	v_add_u32_e32 v128, s63, v207
	v_add_u32_e32 v156, s64, v207
	ds_read_b128 v[112:115], v128
	ds_read_b128 v[116:119], v128 offset:1024
	ds_read_b128 v[120:123], v128 offset:2048
	ds_read_b128 v[128:131], v128 offset:3072
	ds_read_b128 v[144:147], v156
	ds_read_b128 v[148:151], v156 offset:1024
	ds_read_b128 v[152:155], v156 offset:2048
	ds_read_b128 v[156:159], v156 offset:3072
	s_add_u32 s30, s30, s10
	s_addc_u32 s31, s31, s11
	s_mov_b32 m0, s40
	v_lshl_add_u64 v[226:227], s[30:31], 0, v[176:177]
	ds_read_b128 v[160:163], v211 offset:32768
	ds_read_b128 v[164:167], v211 offset:33792
	ds_read_b128 v[168:171], v211 offset:34816
	ds_read_b128 v[172:175], v211 offset:35840
	ds_read_b128 v[188:191], v211 offset:36864
	ds_read_b128 v[192:195], v211 offset:37888
	ds_read_b128 v[196:199], v211 offset:38912
	ds_read_b128 v[200:203], v211 offset:39936
	global_load_lds_dwordx4 v[226:227], off
	v_lshl_add_u64 v[226:227], s[30:31], 0, v[178:179]
	s_mov_b32 m0, s41
	s_nop 0
	global_load_lds_dwordx4 v[226:227], off
	s_waitcnt vmcnt(8)
	s_waitcnt lgkmcnt(0)
	s_barrier
	s_setprio 1
	s_waitcnt lgkmcnt(0)
	v_mfma_f32_16x16x32_bf16 v[136:139], v[112:115], v[160:163], v[136:139]
	v_mfma_f32_16x16x32_bf16 v[136:139], v[116:119], v[164:167], v[136:139]
	v_mfma_f32_16x16x32_bf16 v[140:143], v[128:131], v[164:167], v[140:143]
	v_mfma_f32_16x16x32_bf16 v[140:143], v[120:123], v[160:163], v[140:143]
	v_mfma_f32_16x16x32_bf16 v[132:135], v[144:147], v[160:163], v[132:135]
	v_mfma_f32_16x16x32_bf16 v[132:135], v[148:151], v[164:167], v[132:135]
	v_mfma_f32_16x16x32_bf16 v[124:127], v[156:159], v[164:167], v[124:127]
	v_mfma_f32_16x16x32_bf16 v[124:127], v[152:155], v[160:163], v[124:127]
	v_mfma_f32_16x16x32_bf16 v[96:99], v[152:155], v[168:171], v[96:99]
	v_mfma_f32_16x16x32_bf16 v[96:99], v[156:159], v[172:175], v[96:99]
	v_mfma_f32_16x16x32_bf16 v[100:103], v[148:151], v[172:175], v[100:103]
	v_mfma_f32_16x16x32_bf16 v[100:103], v[144:147], v[168:171], v[100:103]
	v_mfma_f32_16x16x32_bf16 v[104:107], v[120:123], v[168:171], v[104:107]
	v_mfma_f32_16x16x32_bf16 v[104:107], v[128:131], v[172:175], v[104:107]
	v_mfma_f32_16x16x32_bf16 v[108:111], v[116:119], v[172:175], v[108:111]
	v_mfma_f32_16x16x32_bf16 v[108:111], v[112:115], v[168:171], v[108:111]
	v_mfma_f32_16x16x32_bf16 v[92:95], v[112:115], v[188:191], v[92:95]
	v_mfma_f32_16x16x32_bf16 v[92:95], v[116:119], v[192:195], v[92:95]
	v_mfma_f32_16x16x32_bf16 v[88:91], v[128:131], v[192:195], v[88:91]
	v_mfma_f32_16x16x32_bf16 v[88:91], v[120:123], v[188:191], v[88:91]
	v_mfma_f32_16x16x32_bf16 v[84:87], v[144:147], v[188:191], v[84:87]
	v_mfma_f32_16x16x32_bf16 v[84:87], v[148:151], v[192:195], v[84:87]
	v_mfma_f32_16x16x32_bf16 v[80:83], v[156:159], v[192:195], v[80:83]
	v_mfma_f32_16x16x32_bf16 v[80:83], v[152:155], v[188:191], v[80:83]
	v_mfma_f32_16x16x32_bf16 v[64:67], v[152:155], v[196:199], v[64:67]
	v_mfma_f32_16x16x32_bf16 v[64:67], v[156:159], v[200:203], v[64:67]
	v_mfma_f32_16x16x32_bf16 v[68:71], v[148:151], v[200:203], v[68:71]
	v_mfma_f32_16x16x32_bf16 v[68:71], v[144:147], v[196:199], v[68:71]
	v_mfma_f32_16x16x32_bf16 v[72:75], v[120:123], v[196:199], v[72:75]
	v_mfma_f32_16x16x32_bf16 v[72:75], v[128:131], v[200:203], v[72:75]
	v_mfma_f32_16x16x32_bf16 v[76:79], v[116:119], v[200:203], v[76:79]
	v_mfma_f32_16x16x32_bf16 v[76:79], v[112:115], v[196:199], v[76:79]
	s_setprio 0
	s_barrier
	s_add_i32 s30, s63, s37
	v_lshl_add_u64 v[204:205], v[204:205], 0, s[18:19]
	s_mov_b32 m0, s30
	ds_read_b128 v[160:163], v211 offset:49152
	ds_read_b128 v[164:167], v211 offset:50176
	ds_read_b128 v[168:171], v211 offset:51200
	ds_read_b128 v[172:175], v211 offset:52224
	ds_read_b128 v[188:191], v211 offset:53248
	ds_read_b128 v[192:195], v211 offset:54272
	ds_read_b128 v[196:199], v211 offset:55296
	ds_read_b128 v[200:203], v211 offset:56320
	global_load_lds_dwordx4 v[204:205], off
	v_lshl_add_u64 v[204:205], v[214:215], 0, s[18:19]
	s_add_i32 m0, s30, 0x2000
	s_add_i32 s30, s64, s37
	global_load_lds_dwordx4 v[204:205], off
	v_lshl_add_u64 v[204:205], v[216:217], 0, s[18:19]
	s_mov_b32 m0, s30
	s_nop 0
	global_load_lds_dwordx4 v[204:205], off
	v_lshl_add_u64 v[204:205], v[218:219], 0, s[18:19]
	s_add_i32 m0, s30, 0x2000
	s_nop 0
	global_load_lds_dwordx4 v[204:205], off
	v_lshl_add_u64 v[204:205], v[222:223], 0, s[18:19]
	s_mov_b32 m0, s43
	s_nop 0
	global_load_lds_dwordx4 v[204:205], off
	v_lshl_add_u64 v[204:205], v[224:225], 0, s[18:19]
	s_mov_b32 m0, s44
	s_nop 0
	global_load_lds_dwordx4 v[204:205], off
	s_waitcnt vmcnt(8)
	s_waitcnt lgkmcnt(0)
	s_barrier
	s_setprio 1
	s_waitcnt lgkmcnt(0)
	v_mfma_f32_16x16x32_bf16 v[60:63], v[112:115], v[160:163], v[60:63]
	v_mfma_f32_16x16x32_bf16 v[60:63], v[116:119], v[164:167], v[60:63]
	v_mfma_f32_16x16x32_bf16 v[56:59], v[128:131], v[164:167], v[56:59]
	v_mfma_f32_16x16x32_bf16 v[56:59], v[120:123], v[160:163], v[56:59]
	v_mfma_f32_16x16x32_bf16 v[52:55], v[144:147], v[160:163], v[52:55]
	v_mfma_f32_16x16x32_bf16 v[52:55], v[148:151], v[164:167], v[52:55]
	v_mfma_f32_16x16x32_bf16 v[48:51], v[156:159], v[164:167], v[48:51]
	v_mfma_f32_16x16x32_bf16 v[48:51], v[152:155], v[160:163], v[48:51]
	v_mfma_f32_16x16x32_bf16 v[32:35], v[152:155], v[168:171], v[32:35]
	v_mfma_f32_16x16x32_bf16 v[32:35], v[156:159], v[172:175], v[32:35]
	v_mfma_f32_16x16x32_bf16 v[36:39], v[148:151], v[172:175], v[36:39]
	v_mfma_f32_16x16x32_bf16 v[36:39], v[144:147], v[168:171], v[36:39]
	v_mfma_f32_16x16x32_bf16 v[40:43], v[120:123], v[168:171], v[40:43]
	v_mfma_f32_16x16x32_bf16 v[40:43], v[128:131], v[172:175], v[40:43]
	v_mfma_f32_16x16x32_bf16 v[44:47], v[116:119], v[172:175], v[44:47]
	v_mfma_f32_16x16x32_bf16 v[44:47], v[112:115], v[168:171], v[44:47]
	v_mfma_f32_16x16x32_bf16 v[28:31], v[112:115], v[188:191], v[28:31]
	v_mfma_f32_16x16x32_bf16 v[28:31], v[116:119], v[192:195], v[28:31]
	v_mfma_f32_16x16x32_bf16 v[24:27], v[128:131], v[192:195], v[24:27]
	v_mfma_f32_16x16x32_bf16 v[24:27], v[120:123], v[188:191], v[24:27]
	v_mfma_f32_16x16x32_bf16 v[20:23], v[144:147], v[188:191], v[20:23]
	v_mfma_f32_16x16x32_bf16 v[20:23], v[148:151], v[192:195], v[20:23]
	v_mfma_f32_16x16x32_bf16 v[16:19], v[156:159], v[192:195], v[16:19]
	v_mfma_f32_16x16x32_bf16 v[16:19], v[152:155], v[188:191], v[16:19]
	v_mfma_f32_16x16x32_bf16 v[0:3], v[152:155], v[196:199], v[0:3]
	v_mfma_f32_16x16x32_bf16 v[0:3], v[156:159], v[200:203], v[0:3]
	v_mfma_f32_16x16x32_bf16 v[4:7], v[148:151], v[200:203], v[4:7]
	v_mfma_f32_16x16x32_bf16 v[4:7], v[144:147], v[196:199], v[4:7]
	v_mfma_f32_16x16x32_bf16 v[8:11], v[120:123], v[196:199], v[8:11]
	v_mfma_f32_16x16x32_bf16 v[8:11], v[128:131], v[200:203], v[8:11]
	v_mfma_f32_16x16x32_bf16 v[12:15], v[116:119], v[200:203], v[12:15]
	v_mfma_f32_16x16x32_bf16 v[12:15], v[112:115], v[196:199], v[12:15]
	s_setprio 0
	s_barrier
	s_add_u32 s28, s28, 0x100
	s_addc_u32 s29, s29, 0
	s_add_u32 s60, s60, 0x100
	s_addc_u32 s61, s61, 0
	s_cmp_ge_i32 s62, s45
	s_mov_b32 s30, s62
	s_cbranch_scc0 .LBB0_849

.LBB0_949:
	ds_read_b128 v[164:167], v157
	ds_read_b128 v[168:171], v157 offset:1024
	ds_read_b128 v[172:175], v157 offset:2048
	ds_read_b128 v[176:179], v157 offset:3072
	ds_read_b128 v[180:183], v162
	ds_read_b128 v[184:187], v162 offset:1024
	ds_read_b128 v[188:191], v162 offset:2048
	ds_read_b128 v[192:195], v162 offset:3072
	s_add_i32 s68, s34, 2
	s_add_u32 s69, s30, 0x80
	s_addc_u32 s35, s31, 0
	s_cmp_eq_u32 s49, s34
	s_cselect_b32 s34, s2, s69
	s_cselect_b32 s35, s3, s35
	s_cselect_b32 s71, s29, s67
	s_cselect_b32 s70, s28, s66
	v_lshl_add_u64 v[230:231], s[30:31], 0, v[136:137]
	s_add_i32 m0, s41, 0xc000
	ds_read_b128 v[196:199], v163
	ds_read_b128 v[200:203], v163 offset:1024
	ds_read_b128 v[204:207], v163 offset:2048
	ds_read_b128 v[208:211], v163 offset:3072
	ds_read_b128 v[212:215], v163 offset:4096
	ds_read_b128 v[216:219], v163 offset:5120
	ds_read_b128 v[222:225], v163 offset:6144
	ds_read_b128 v[226:229], v163 offset:7168
	global_load_lds_dwordx4 v[230:231], off
	v_lshl_add_u64 v[230:231], s[30:31], 0, v[138:139]
	s_add_i32 m0, s41, 0xe000
	s_nop 0
	global_load_lds_dwordx4 v[230:231], off
	s_waitcnt vmcnt(8)
	s_waitcnt lgkmcnt(0)
	s_barrier
	s_setprio 1
	s_waitcnt lgkmcnt(0)
	v_mfma_f32_16x16x32_bf16 v[120:123], v[164:167], v[196:199], v[120:123]
	v_mfma_f32_16x16x32_bf16 v[120:123], v[168:171], v[200:203], v[120:123]
	v_mfma_f32_16x16x32_bf16 v[124:127], v[176:179], v[200:203], v[124:127]
	v_mfma_f32_16x16x32_bf16 v[124:127], v[172:175], v[196:199], v[124:127]
	v_mfma_f32_16x16x32_bf16 v[116:119], v[180:183], v[196:199], v[116:119]
	v_mfma_f32_16x16x32_bf16 v[116:119], v[184:187], v[200:203], v[116:119]
	v_mfma_f32_16x16x32_bf16 v[112:115], v[192:195], v[200:203], v[112:115]
	v_mfma_f32_16x16x32_bf16 v[112:115], v[188:191], v[196:199], v[112:115]
	v_mfma_f32_16x16x32_bf16 v[96:99], v[188:191], v[204:207], v[96:99]
	v_mfma_f32_16x16x32_bf16 v[96:99], v[192:195], v[208:211], v[96:99]
	v_mfma_f32_16x16x32_bf16 v[100:103], v[184:187], v[208:211], v[100:103]
	v_mfma_f32_16x16x32_bf16 v[100:103], v[180:183], v[204:207], v[100:103]
	v_mfma_f32_16x16x32_bf16 v[104:107], v[172:175], v[204:207], v[104:107]
	v_mfma_f32_16x16x32_bf16 v[104:107], v[176:179], v[208:211], v[104:107]
	v_mfma_f32_16x16x32_bf16 v[108:111], v[168:171], v[208:211], v[108:111]
	v_mfma_f32_16x16x32_bf16 v[108:111], v[164:167], v[204:207], v[108:111]
	v_mfma_f32_16x16x32_bf16 v[92:95], v[164:167], v[212:215], v[92:95]
	v_mfma_f32_16x16x32_bf16 v[92:95], v[168:171], v[216:219], v[92:95]
	v_mfma_f32_16x16x32_bf16 v[88:91], v[176:179], v[216:219], v[88:91]
	v_mfma_f32_16x16x32_bf16 v[88:91], v[172:175], v[212:215], v[88:91]
	v_mfma_f32_16x16x32_bf16 v[84:87], v[180:183], v[212:215], v[84:87]
	v_mfma_f32_16x16x32_bf16 v[84:87], v[184:187], v[216:219], v[84:87]
	v_mfma_f32_16x16x32_bf16 v[80:83], v[192:195], v[216:219], v[80:83]
	v_mfma_f32_16x16x32_bf16 v[80:83], v[188:191], v[212:215], v[80:83]
	v_mfma_f32_16x16x32_bf16 v[64:67], v[188:191], v[222:225], v[64:67]
	v_mfma_f32_16x16x32_bf16 v[64:67], v[192:195], v[226:229], v[64:67]
	v_mfma_f32_16x16x32_bf16 v[68:71], v[184:187], v[226:229], v[68:71]
	v_mfma_f32_16x16x32_bf16 v[68:71], v[180:183], v[222:225], v[68:71]
	v_mfma_f32_16x16x32_bf16 v[72:75], v[172:175], v[222:225], v[72:75]
	v_mfma_f32_16x16x32_bf16 v[72:75], v[176:179], v[226:229], v[72:75]
	v_mfma_f32_16x16x32_bf16 v[76:79], v[168:171], v[226:229], v[76:79]
	v_mfma_f32_16x16x32_bf16 v[76:79], v[164:167], v[222:225], v[76:79]
	s_setprio 0
	s_barrier
	s_add_i32 s69, s52, s40
	v_lshl_add_u64 v[230:231], s[70:71], 0, v[130:131]
	s_mov_b32 m0, s69
	ds_read_b128 v[196:199], v163 offset:16384
	ds_read_b128 v[200:203], v163 offset:17408
	ds_read_b128 v[204:207], v163 offset:18432
	ds_read_b128 v[208:211], v163 offset:19456
	ds_read_b128 v[212:215], v163 offset:20480
	ds_read_b128 v[216:219], v163 offset:21504
	ds_read_b128 v[222:225], v163 offset:22528
	ds_read_b128 v[226:229], v163 offset:23552
	global_load_lds_dwordx4 v[230:231], off
	s_add_i32 m0, s69, 0x2000
	v_lshl_add_u64 v[232:233], s[70:71], 0, v[134:135]
	s_add_u32 s70, s70, s6
	s_addc_u32 s71, s71, s7
	s_add_i32 s69, s53, s40
	global_load_lds_dwordx4 v[232:233], off
	v_lshl_add_u64 v[234:235], s[70:71], 0, v[130:131]
	s_mov_b32 m0, s69
	v_lshl_add_u64 v[236:237], s[70:71], 0, v[134:135]
	global_load_lds_dwordx4 v[234:235], off
	s_add_i32 m0, s69, 0x2000
	v_lshl_add_u64 v[238:239], s[34:35], 0, v[128:129]
	global_load_lds_dwordx4 v[236:237], off
	s_mov_b32 m0, s41
	v_lshl_add_u64 v[240:241], s[34:35], 0, v[132:133]
	global_load_lds_dwordx4 v[238:239], off
	s_mov_b32 m0, s42
	s_nop 0
	global_load_lds_dwordx4 v[240:241], off
	s_waitcnt vmcnt(8)
	s_waitcnt lgkmcnt(0)
	s_barrier
	s_setprio 1
	s_waitcnt lgkmcnt(0)
	v_mfma_f32_16x16x32_bf16 v[60:63], v[164:167], v[196:199], v[60:63]
	v_mfma_f32_16x16x32_bf16 v[60:63], v[168:171], v[200:203], v[60:63]
	v_mfma_f32_16x16x32_bf16 v[56:59], v[176:179], v[200:203], v[56:59]
	v_mfma_f32_16x16x32_bf16 v[56:59], v[172:175], v[196:199], v[56:59]
	v_mfma_f32_16x16x32_bf16 v[52:55], v[180:183], v[196:199], v[52:55]
	v_mfma_f32_16x16x32_bf16 v[52:55], v[184:187], v[200:203], v[52:55]
	v_mfma_f32_16x16x32_bf16 v[48:51], v[192:195], v[200:203], v[48:51]
	v_mfma_f32_16x16x32_bf16 v[48:51], v[188:191], v[196:199], v[48:51]
	v_mfma_f32_16x16x32_bf16 v[32:35], v[188:191], v[204:207], v[32:35]
	v_mfma_f32_16x16x32_bf16 v[32:35], v[192:195], v[208:211], v[32:35]
	v_mfma_f32_16x16x32_bf16 v[36:39], v[184:187], v[208:211], v[36:39]
	v_mfma_f32_16x16x32_bf16 v[36:39], v[180:183], v[204:207], v[36:39]
	v_mfma_f32_16x16x32_bf16 v[40:43], v[172:175], v[204:207], v[40:43]
	v_mfma_f32_16x16x32_bf16 v[40:43], v[176:179], v[208:211], v[40:43]
	v_mfma_f32_16x16x32_bf16 v[44:47], v[168:171], v[208:211], v[44:47]
	v_mfma_f32_16x16x32_bf16 v[44:47], v[164:167], v[204:207], v[44:47]
	v_mfma_f32_16x16x32_bf16 v[28:31], v[164:167], v[212:215], v[28:31]
	v_mfma_f32_16x16x32_bf16 v[28:31], v[168:171], v[216:219], v[28:31]
	v_mfma_f32_16x16x32_bf16 v[24:27], v[176:179], v[216:219], v[24:27]
	v_mfma_f32_16x16x32_bf16 v[24:27], v[172:175], v[212:215], v[24:27]
	v_mfma_f32_16x16x32_bf16 v[20:23], v[180:183], v[212:215], v[20:23]
	v_mfma_f32_16x16x32_bf16 v[20:23], v[184:187], v[216:219], v[20:23]
	v_mfma_f32_16x16x32_bf16 v[16:19], v[192:195], v[216:219], v[16:19]
	v_mfma_f32_16x16x32_bf16 v[16:19], v[188:191], v[212:215], v[16:19]
	v_mfma_f32_16x16x32_bf16 v[0:3], v[188:191], v[222:225], v[0:3]
	v_mfma_f32_16x16x32_bf16 v[0:3], v[192:195], v[226:229], v[0:3]
	v_mfma_f32_16x16x32_bf16 v[4:7], v[184:187], v[226:229], v[4:7]
	v_mfma_f32_16x16x32_bf16 v[4:7], v[180:183], v[222:225], v[4:7]
	v_mfma_f32_16x16x32_bf16 v[8:11], v[172:175], v[222:225], v[8:11]
	v_mfma_f32_16x16x32_bf16 v[8:11], v[176:179], v[226:229], v[8:11]
	v_mfma_f32_16x16x32_bf16 v[12:15], v[168:171], v[226:229], v[12:15]
	v_mfma_f32_16x16x32_bf16 v[12:15], v[164:167], v[222:225], v[12:15]
	s_setprio 0
	s_barrier
	s_add_i32 s69, 0, 0x18000
	s_add_i32 s70, 0, 0x1c000
	v_add_u32_e32 v176, s69, v154
	v_add_u32_e32 v192, s70, v154
	ds_read_b128 v[164:167], v176
	ds_read_b128 v[168:171], v176 offset:1024
	ds_read_b128 v[172:175], v176 offset:2048
	ds_read_b128 v[176:179], v176 offset:3072
	ds_read_b128 v[180:183], v192
	ds_read_b128 v[184:187], v192 offset:1024
	ds_read_b128 v[188:191], v192 offset:2048
	ds_read_b128 v[192:195], v192 offset:3072
	s_add_u32 s34, s34, s6
	s_addc_u32 s35, s35, s7
	s_mov_b32 m0, s43
	v_lshl_add_u64 v[242:243], s[34:35], 0, v[128:129]
	ds_read_b128 v[196:199], v163 offset:32768
	ds_read_b128 v[200:203], v163 offset:33792
	ds_read_b128 v[204:207], v163 offset:34816
	ds_read_b128 v[208:211], v163 offset:35840
	ds_read_b128 v[212:215], v163 offset:36864
	ds_read_b128 v[216:219], v163 offset:37888
	ds_read_b128 v[222:225], v163 offset:38912
	ds_read_b128 v[226:229], v163 offset:39936
	global_load_lds_dwordx4 v[242:243], off
	v_lshl_add_u64 v[242:243], s[34:35], 0, v[132:133]
	s_mov_b32 m0, s44
	s_nop 0
	global_load_lds_dwordx4 v[242:243], off
	s_waitcnt vmcnt(8)
	s_waitcnt lgkmcnt(0)
	s_barrier
	s_setprio 1
	s_waitcnt lgkmcnt(0)
	v_mfma_f32_16x16x32_bf16 v[120:123], v[164:167], v[196:199], v[120:123]
	v_mfma_f32_16x16x32_bf16 v[120:123], v[168:171], v[200:203], v[120:123]
	v_mfma_f32_16x16x32_bf16 v[124:127], v[176:179], v[200:203], v[124:127]
	v_mfma_f32_16x16x32_bf16 v[124:127], v[172:175], v[196:199], v[124:127]
	v_mfma_f32_16x16x32_bf16 v[116:119], v[180:183], v[196:199], v[116:119]
	v_mfma_f32_16x16x32_bf16 v[116:119], v[184:187], v[200:203], v[116:119]
	v_mfma_f32_16x16x32_bf16 v[112:115], v[192:195], v[200:203], v[112:115]
	v_mfma_f32_16x16x32_bf16 v[112:115], v[188:191], v[196:199], v[112:115]
	v_mfma_f32_16x16x32_bf16 v[96:99], v[188:191], v[204:207], v[96:99]
	v_mfma_f32_16x16x32_bf16 v[96:99], v[192:195], v[208:211], v[96:99]
	v_mfma_f32_16x16x32_bf16 v[100:103], v[184:187], v[208:211], v[100:103]
	v_mfma_f32_16x16x32_bf16 v[100:103], v[180:183], v[204:207], v[100:103]
	v_mfma_f32_16x16x32_bf16 v[104:107], v[172:175], v[204:207], v[104:107]
	v_mfma_f32_16x16x32_bf16 v[104:107], v[176:179], v[208:211], v[104:107]
	v_mfma_f32_16x16x32_bf16 v[108:111], v[168:171], v[208:211], v[108:111]
	v_mfma_f32_16x16x32_bf16 v[108:111], v[164:167], v[204:207], v[108:111]
	v_mfma_f32_16x16x32_bf16 v[92:95], v[164:167], v[212:215], v[92:95]
	v_mfma_f32_16x16x32_bf16 v[92:95], v[168:171], v[216:219], v[92:95]
	v_mfma_f32_16x16x32_bf16 v[88:91], v[176:179], v[216:219], v[88:91]
	v_mfma_f32_16x16x32_bf16 v[88:91], v[172:175], v[212:215], v[88:91]
	v_mfma_f32_16x16x32_bf16 v[84:87], v[180:183], v[212:215], v[84:87]
	v_mfma_f32_16x16x32_bf16 v[84:87], v[184:187], v[216:219], v[84:87]
	v_mfma_f32_16x16x32_bf16 v[80:83], v[192:195], v[216:219], v[80:83]
	v_mfma_f32_16x16x32_bf16 v[80:83], v[188:191], v[212:215], v[80:83]
	v_mfma_f32_16x16x32_bf16 v[64:67], v[188:191], v[222:225], v[64:67]
	v_mfma_f32_16x16x32_bf16 v[64:67], v[192:195], v[226:229], v[64:67]
	v_mfma_f32_16x16x32_bf16 v[68:71], v[184:187], v[226:229], v[68:71]
	v_mfma_f32_16x16x32_bf16 v[68:71], v[180:183], v[222:225], v[68:71]
	v_mfma_f32_16x16x32_bf16 v[72:75], v[172:175], v[222:225], v[72:75]
	v_mfma_f32_16x16x32_bf16 v[72:75], v[176:179], v[226:229], v[72:75]
	v_mfma_f32_16x16x32_bf16 v[76:79], v[168:171], v[226:229], v[76:79]
	v_mfma_f32_16x16x32_bf16 v[76:79], v[164:167], v[222:225], v[76:79]
	s_setprio 0
	s_barrier
	s_add_i32 s34, s69, s40
	v_lshl_add_u64 v[230:231], v[230:231], 0, s[12:13]
	s_mov_b32 m0, s34
	ds_read_b128 v[196:199], v163 offset:49152
	ds_read_b128 v[200:203], v163 offset:50176
	ds_read_b128 v[204:207], v163 offset:51200
	ds_read_b128 v[208:211], v163 offset:52224
	ds_read_b128 v[212:215], v163 offset:53248
	ds_read_b128 v[216:219], v163 offset:54272
	ds_read_b128 v[222:225], v163 offset:55296
	ds_read_b128 v[226:229], v163 offset:56320
	global_load_lds_dwordx4 v[230:231], off
	v_lshl_add_u64 v[230:231], v[232:233], 0, s[12:13]
	s_add_i32 m0, s34, 0x2000
	s_add_i32 s34, s70, s40
	global_load_lds_dwordx4 v[230:231], off
	v_lshl_add_u64 v[230:231], v[234:235], 0, s[12:13]
	s_mov_b32 m0, s34
	s_nop 0
	global_load_lds_dwordx4 v[230:231], off
	v_lshl_add_u64 v[230:231], v[236:237], 0, s[12:13]
	s_add_i32 m0, s34, 0x2000
	s_nop 0
	global_load_lds_dwordx4 v[230:231], off
	v_lshl_add_u64 v[230:231], v[238:239], 0, s[12:13]
	s_mov_b32 m0, s46
	s_nop 0
	global_load_lds_dwordx4 v[230:231], off
	v_lshl_add_u64 v[230:231], v[240:241], 0, s[12:13]
	s_mov_b32 m0, s47
	s_nop 0
	global_load_lds_dwordx4 v[230:231], off
	s_waitcnt vmcnt(8)
	s_waitcnt lgkmcnt(0)
	s_barrier
	s_setprio 1
	s_waitcnt lgkmcnt(0)
	v_mfma_f32_16x16x32_bf16 v[60:63], v[164:167], v[196:199], v[60:63]
	v_mfma_f32_16x16x32_bf16 v[60:63], v[168:171], v[200:203], v[60:63]
	v_mfma_f32_16x16x32_bf16 v[56:59], v[176:179], v[200:203], v[56:59]
	v_mfma_f32_16x16x32_bf16 v[56:59], v[172:175], v[196:199], v[56:59]
	v_mfma_f32_16x16x32_bf16 v[52:55], v[180:183], v[196:199], v[52:55]
	v_mfma_f32_16x16x32_bf16 v[52:55], v[184:187], v[200:203], v[52:55]
	v_mfma_f32_16x16x32_bf16 v[48:51], v[192:195], v[200:203], v[48:51]
	v_mfma_f32_16x16x32_bf16 v[48:51], v[188:191], v[196:199], v[48:51]
	v_mfma_f32_16x16x32_bf16 v[32:35], v[188:191], v[204:207], v[32:35]
	v_mfma_f32_16x16x32_bf16 v[32:35], v[192:195], v[208:211], v[32:35]
	v_mfma_f32_16x16x32_bf16 v[36:39], v[184:187], v[208:211], v[36:39]
	v_mfma_f32_16x16x32_bf16 v[36:39], v[180:183], v[204:207], v[36:39]
	v_mfma_f32_16x16x32_bf16 v[40:43], v[172:175], v[204:207], v[40:43]
	v_mfma_f32_16x16x32_bf16 v[40:43], v[176:179], v[208:211], v[40:43]
	v_mfma_f32_16x16x32_bf16 v[44:47], v[168:171], v[208:211], v[44:47]
	v_mfma_f32_16x16x32_bf16 v[44:47], v[164:167], v[204:207], v[44:47]
	v_mfma_f32_16x16x32_bf16 v[28:31], v[164:167], v[212:215], v[28:31]
	v_mfma_f32_16x16x32_bf16 v[28:31], v[168:171], v[216:219], v[28:31]
	v_mfma_f32_16x16x32_bf16 v[24:27], v[176:179], v[216:219], v[24:27]
	v_mfma_f32_16x16x32_bf16 v[24:27], v[172:175], v[212:215], v[24:27]
	v_mfma_f32_16x16x32_bf16 v[20:23], v[180:183], v[212:215], v[20:23]
	v_mfma_f32_16x16x32_bf16 v[20:23], v[184:187], v[216:219], v[20:23]
	v_mfma_f32_16x16x32_bf16 v[16:19], v[192:195], v[216:219], v[16:19]
	v_mfma_f32_16x16x32_bf16 v[16:19], v[188:191], v[212:215], v[16:19]
	v_mfma_f32_16x16x32_bf16 v[0:3], v[188:191], v[222:225], v[0:3]
	v_mfma_f32_16x16x32_bf16 v[0:3], v[192:195], v[226:229], v[0:3]
	v_mfma_f32_16x16x32_bf16 v[4:7], v[184:187], v[226:229], v[4:7]
	v_mfma_f32_16x16x32_bf16 v[4:7], v[180:183], v[222:225], v[4:7]
	v_mfma_f32_16x16x32_bf16 v[8:11], v[172:175], v[222:225], v[8:11]
	v_mfma_f32_16x16x32_bf16 v[8:11], v[176:179], v[226:229], v[8:11]
	v_mfma_f32_16x16x32_bf16 v[12:15], v[168:171], v[226:229], v[12:15]
	v_mfma_f32_16x16x32_bf16 v[12:15], v[164:167], v[222:225], v[12:15]
	s_setprio 0
	s_barrier
	s_add_u32 s30, s30, 0x100
	s_addc_u32 s31, s31, 0
	s_add_u32 s66, s66, 0x100
	s_addc_u32 s67, s67, 0
	s_cmp_ge_i32 s68, s48
	s_mov_b32 s34, s68
	s_cbranch_scc0 .LBB0_949

.LBB0_970:
	ds_read_b128 v[170:173], v139
	ds_read_b128 v[174:177], v139 offset:1024
	ds_read_b128 v[178:181], v139 offset:2048
	ds_read_b128 v[182:185], v139 offset:3072
	ds_read_b128 v[186:189], v165
	ds_read_b128 v[190:193], v165 offset:1024
	ds_read_b128 v[194:197], v165 offset:2048
	ds_read_b128 v[198:201], v165 offset:3072
	s_add_i32 s8, s4, 2
	s_add_u32 s9, s2, 0x80
	s_addc_u32 s5, s3, 0
	s_cmp_eq_u32 s52, s4
	s_cselect_b32 s4, s30, s9
	s_cselect_b32 s5, s31, s5
	s_cselect_b32 s11, s35, s7
	s_cselect_b32 s10, s34, s6
	v_lshl_add_u64 v[218:219], s[2:3], 0, v[156:157]
	s_add_i32 m0, s42, 0xc000
	ds_read_b128 v[202:205], v166
	ds_read_b128 v[206:209], v166 offset:1024
	ds_read_b128 v[210:213], v166 offset:2048
	ds_read_b128 v[214:217], v166 offset:3072
	ds_read_b128 v[222:225], v166 offset:4096
	ds_read_b128 v[226:229], v166 offset:5120
	ds_read_b128 v[230:233], v166 offset:6144
	ds_read_b128 v[234:237], v166 offset:7168
	global_load_lds_dwordx4 v[218:219], off
	v_lshl_add_u64 v[218:219], s[2:3], 0, v[158:159]
	s_add_i32 m0, s42, 0xe000
	s_nop 0
	global_load_lds_dwordx4 v[218:219], off
	s_waitcnt vmcnt(8)
	s_waitcnt lgkmcnt(0)
	s_barrier
	s_setprio 1
	s_waitcnt lgkmcnt(0)
	v_mfma_f32_16x16x32_bf16 v[124:127], v[170:173], v[202:205], v[124:127]
	v_mfma_f32_16x16x32_bf16 v[124:127], v[174:177], v[206:209], v[124:127]
	v_mfma_f32_16x16x32_bf16 v[120:123], v[182:185], v[206:209], v[120:123]
	v_mfma_f32_16x16x32_bf16 v[120:123], v[178:181], v[202:205], v[120:123]
	v_mfma_f32_16x16x32_bf16 v[116:119], v[186:189], v[202:205], v[116:119]
	v_mfma_f32_16x16x32_bf16 v[116:119], v[190:193], v[206:209], v[116:119]
	v_mfma_f32_16x16x32_bf16 v[112:115], v[198:201], v[206:209], v[112:115]
	v_mfma_f32_16x16x32_bf16 v[112:115], v[194:197], v[202:205], v[112:115]
	v_mfma_f32_16x16x32_bf16 v[96:99], v[194:197], v[210:213], v[96:99]
	v_mfma_f32_16x16x32_bf16 v[96:99], v[198:201], v[214:217], v[96:99]
	v_mfma_f32_16x16x32_bf16 v[100:103], v[190:193], v[214:217], v[100:103]
	v_mfma_f32_16x16x32_bf16 v[100:103], v[186:189], v[210:213], v[100:103]
	v_mfma_f32_16x16x32_bf16 v[104:107], v[178:181], v[210:213], v[104:107]
	v_mfma_f32_16x16x32_bf16 v[104:107], v[182:185], v[214:217], v[104:107]
	v_mfma_f32_16x16x32_bf16 v[108:111], v[174:177], v[214:217], v[108:111]
	v_mfma_f32_16x16x32_bf16 v[108:111], v[170:173], v[210:213], v[108:111]
	v_mfma_f32_16x16x32_bf16 v[92:95], v[170:173], v[222:225], v[92:95]
	v_mfma_f32_16x16x32_bf16 v[92:95], v[174:177], v[226:229], v[92:95]
	v_mfma_f32_16x16x32_bf16 v[88:91], v[182:185], v[226:229], v[88:91]
	v_mfma_f32_16x16x32_bf16 v[88:91], v[178:181], v[222:225], v[88:91]
	v_mfma_f32_16x16x32_bf16 v[84:87], v[186:189], v[222:225], v[84:87]
	v_mfma_f32_16x16x32_bf16 v[84:87], v[190:193], v[226:229], v[84:87]
	v_mfma_f32_16x16x32_bf16 v[80:83], v[198:201], v[226:229], v[80:83]
	v_mfma_f32_16x16x32_bf16 v[80:83], v[194:197], v[222:225], v[80:83]
	v_mfma_f32_16x16x32_bf16 v[64:67], v[194:197], v[230:233], v[64:67]
	v_mfma_f32_16x16x32_bf16 v[64:67], v[198:201], v[234:237], v[64:67]
	v_mfma_f32_16x16x32_bf16 v[68:71], v[190:193], v[234:237], v[68:71]
	v_mfma_f32_16x16x32_bf16 v[68:71], v[186:189], v[230:233], v[68:71]
	v_mfma_f32_16x16x32_bf16 v[72:75], v[178:181], v[230:233], v[72:75]
	v_mfma_f32_16x16x32_bf16 v[72:75], v[182:185], v[234:237], v[72:75]
	v_mfma_f32_16x16x32_bf16 v[76:79], v[174:177], v[234:237], v[76:79]
	v_mfma_f32_16x16x32_bf16 v[76:79], v[170:173], v[230:233], v[76:79]
	s_setprio 0
	s_barrier
	s_add_i32 s9, s60, s39
	v_lshl_add_u64 v[218:219], s[10:11], 0, v[132:133]
	s_mov_b32 m0, s9
	ds_read_b128 v[202:205], v166 offset:16384
	ds_read_b128 v[206:209], v166 offset:17408
	ds_read_b128 v[210:213], v166 offset:18432
	ds_read_b128 v[214:217], v166 offset:19456
	ds_read_b128 v[222:225], v166 offset:20480
	ds_read_b128 v[226:229], v166 offset:21504
	ds_read_b128 v[230:233], v166 offset:22528
	ds_read_b128 v[234:237], v166 offset:23552
	global_load_lds_dwordx4 v[218:219], off
	s_add_i32 m0, s9, 0x2000
	v_lshl_add_u64 v[238:239], s[10:11], 0, v[128:129]
	s_add_u32 s10, s10, s18
	s_addc_u32 s11, s11, s19
	s_add_i32 s9, s61, s39
	global_load_lds_dwordx4 v[238:239], off
	v_lshl_add_u64 v[240:241], s[10:11], 0, v[132:133]
	s_mov_b32 m0, s9
	v_lshl_add_u64 v[242:243], s[10:11], 0, v[128:129]
	global_load_lds_dwordx4 v[240:241], off
	s_add_i32 m0, s9, 0x2000
	v_lshl_add_u64 v[244:245], s[4:5], 0, v[134:135]
	global_load_lds_dwordx4 v[242:243], off
	s_mov_b32 m0, s42
	v_lshl_add_u64 v[246:247], s[4:5], 0, v[130:131]
	global_load_lds_dwordx4 v[244:245], off
	s_mov_b32 m0, s43
	s_nop 0
	global_load_lds_dwordx4 v[246:247], off
	s_waitcnt vmcnt(8)
	s_waitcnt lgkmcnt(0)
	s_barrier
	s_setprio 1
	s_waitcnt lgkmcnt(0)
	v_mfma_f32_16x16x32_bf16 v[60:63], v[170:173], v[202:205], v[60:63]
	v_mfma_f32_16x16x32_bf16 v[60:63], v[174:177], v[206:209], v[60:63]
	v_mfma_f32_16x16x32_bf16 v[56:59], v[182:185], v[206:209], v[56:59]
	v_mfma_f32_16x16x32_bf16 v[56:59], v[178:181], v[202:205], v[56:59]
	v_mfma_f32_16x16x32_bf16 v[52:55], v[186:189], v[202:205], v[52:55]
	v_mfma_f32_16x16x32_bf16 v[52:55], v[190:193], v[206:209], v[52:55]
	v_mfma_f32_16x16x32_bf16 v[48:51], v[198:201], v[206:209], v[48:51]
	v_mfma_f32_16x16x32_bf16 v[48:51], v[194:197], v[202:205], v[48:51]
	v_mfma_f32_16x16x32_bf16 v[32:35], v[194:197], v[210:213], v[32:35]
	v_mfma_f32_16x16x32_bf16 v[32:35], v[198:201], v[214:217], v[32:35]
	v_mfma_f32_16x16x32_bf16 v[36:39], v[190:193], v[214:217], v[36:39]
	v_mfma_f32_16x16x32_bf16 v[36:39], v[186:189], v[210:213], v[36:39]
	v_mfma_f32_16x16x32_bf16 v[40:43], v[178:181], v[210:213], v[40:43]
	v_mfma_f32_16x16x32_bf16 v[40:43], v[182:185], v[214:217], v[40:43]
	v_mfma_f32_16x16x32_bf16 v[44:47], v[174:177], v[214:217], v[44:47]
	v_mfma_f32_16x16x32_bf16 v[44:47], v[170:173], v[210:213], v[44:47]
	v_mfma_f32_16x16x32_bf16 v[28:31], v[170:173], v[222:225], v[28:31]
	v_mfma_f32_16x16x32_bf16 v[28:31], v[174:177], v[226:229], v[28:31]
	v_mfma_f32_16x16x32_bf16 v[24:27], v[182:185], v[226:229], v[24:27]
	v_mfma_f32_16x16x32_bf16 v[24:27], v[178:181], v[222:225], v[24:27]
	v_mfma_f32_16x16x32_bf16 v[20:23], v[186:189], v[222:225], v[20:23]
	v_mfma_f32_16x16x32_bf16 v[20:23], v[190:193], v[226:229], v[20:23]
	v_mfma_f32_16x16x32_bf16 v[16:19], v[198:201], v[226:229], v[16:19]
	v_mfma_f32_16x16x32_bf16 v[16:19], v[194:197], v[222:225], v[16:19]
	v_mfma_f32_16x16x32_bf16 v[0:3], v[194:197], v[230:233], v[0:3]
	v_mfma_f32_16x16x32_bf16 v[0:3], v[198:201], v[234:237], v[0:3]
	v_mfma_f32_16x16x32_bf16 v[4:7], v[190:193], v[234:237], v[4:7]
	v_mfma_f32_16x16x32_bf16 v[4:7], v[186:189], v[230:233], v[4:7]
	v_mfma_f32_16x16x32_bf16 v[8:11], v[178:181], v[230:233], v[8:11]
	v_mfma_f32_16x16x32_bf16 v[8:11], v[182:185], v[234:237], v[8:11]
	v_mfma_f32_16x16x32_bf16 v[12:15], v[174:177], v[234:237], v[12:15]
	v_mfma_f32_16x16x32_bf16 v[12:15], v[170:173], v[230:233], v[12:15]
	s_setprio 0
	s_barrier
	s_add_i32 s9, 0, 0x18000
	v_add_u32_e32 v169, s9, v164
	s_add_i32 s10, 0, 0x1c000
	ds_read_b128 v[170:173], v169
	ds_read_b128 v[174:177], v169 offset:1024
	ds_read_b128 v[178:181], v169 offset:2048
	ds_read_b128 v[182:185], v169 offset:3072
	v_add_u32_e32 v169, s10, v164
	ds_read_b128 v[186:189], v169
	ds_read_b128 v[190:193], v169 offset:1024
	ds_read_b128 v[194:197], v169 offset:2048
	ds_read_b128 v[198:201], v169 offset:3072
	s_add_u32 s4, s4, s18
	s_addc_u32 s5, s5, s19
	s_mov_b32 m0, s44
	v_lshl_add_u64 v[248:249], s[4:5], 0, v[134:135]
	ds_read_b128 v[202:205], v166 offset:32768
	ds_read_b128 v[206:209], v166 offset:33792
	ds_read_b128 v[210:213], v166 offset:34816
	ds_read_b128 v[214:217], v166 offset:35840
	ds_read_b128 v[222:225], v166 offset:36864
	ds_read_b128 v[226:229], v166 offset:37888
	ds_read_b128 v[230:233], v166 offset:38912
	ds_read_b128 v[234:237], v166 offset:39936
	global_load_lds_dwordx4 v[248:249], off
	v_lshl_add_u64 v[248:249], s[4:5], 0, v[130:131]
	s_mov_b32 m0, s45
	s_nop 0
	global_load_lds_dwordx4 v[248:249], off
	s_waitcnt vmcnt(8)
	s_waitcnt lgkmcnt(0)
	s_barrier
	s_setprio 1
	s_waitcnt lgkmcnt(0)
	v_mfma_f32_16x16x32_bf16 v[124:127], v[170:173], v[202:205], v[124:127]
	v_mfma_f32_16x16x32_bf16 v[124:127], v[174:177], v[206:209], v[124:127]
	v_mfma_f32_16x16x32_bf16 v[120:123], v[182:185], v[206:209], v[120:123]
	v_mfma_f32_16x16x32_bf16 v[120:123], v[178:181], v[202:205], v[120:123]
	v_mfma_f32_16x16x32_bf16 v[116:119], v[186:189], v[202:205], v[116:119]
	v_mfma_f32_16x16x32_bf16 v[116:119], v[190:193], v[206:209], v[116:119]
	v_mfma_f32_16x16x32_bf16 v[112:115], v[198:201], v[206:209], v[112:115]
	v_mfma_f32_16x16x32_bf16 v[112:115], v[194:197], v[202:205], v[112:115]
	v_mfma_f32_16x16x32_bf16 v[96:99], v[194:197], v[210:213], v[96:99]
	v_mfma_f32_16x16x32_bf16 v[96:99], v[198:201], v[214:217], v[96:99]
	v_mfma_f32_16x16x32_bf16 v[100:103], v[190:193], v[214:217], v[100:103]
	v_mfma_f32_16x16x32_bf16 v[100:103], v[186:189], v[210:213], v[100:103]
	v_mfma_f32_16x16x32_bf16 v[104:107], v[178:181], v[210:213], v[104:107]
	v_mfma_f32_16x16x32_bf16 v[104:107], v[182:185], v[214:217], v[104:107]
	v_mfma_f32_16x16x32_bf16 v[108:111], v[174:177], v[214:217], v[108:111]
	v_mfma_f32_16x16x32_bf16 v[108:111], v[170:173], v[210:213], v[108:111]
	v_mfma_f32_16x16x32_bf16 v[92:95], v[170:173], v[222:225], v[92:95]
	v_mfma_f32_16x16x32_bf16 v[92:95], v[174:177], v[226:229], v[92:95]
	v_mfma_f32_16x16x32_bf16 v[88:91], v[182:185], v[226:229], v[88:91]
	v_mfma_f32_16x16x32_bf16 v[88:91], v[178:181], v[222:225], v[88:91]
	v_mfma_f32_16x16x32_bf16 v[84:87], v[186:189], v[222:225], v[84:87]
	v_mfma_f32_16x16x32_bf16 v[84:87], v[190:193], v[226:229], v[84:87]
	v_mfma_f32_16x16x32_bf16 v[80:83], v[198:201], v[226:229], v[80:83]
	v_mfma_f32_16x16x32_bf16 v[80:83], v[194:197], v[222:225], v[80:83]
	v_mfma_f32_16x16x32_bf16 v[64:67], v[194:197], v[230:233], v[64:67]
	v_mfma_f32_16x16x32_bf16 v[64:67], v[198:201], v[234:237], v[64:67]
	v_mfma_f32_16x16x32_bf16 v[68:71], v[190:193], v[234:237], v[68:71]
	v_mfma_f32_16x16x32_bf16 v[68:71], v[186:189], v[230:233], v[68:71]
	v_mfma_f32_16x16x32_bf16 v[72:75], v[178:181], v[230:233], v[72:75]
	v_mfma_f32_16x16x32_bf16 v[72:75], v[182:185], v[234:237], v[72:75]
	v_mfma_f32_16x16x32_bf16 v[76:79], v[174:177], v[234:237], v[76:79]
	v_mfma_f32_16x16x32_bf16 v[76:79], v[170:173], v[230:233], v[76:79]
	s_setprio 0
	s_barrier
	s_add_i32 s4, s9, s39
	v_lshl_add_u64 v[218:219], v[218:219], 0, s[24:25]
	s_mov_b32 m0, s4
	ds_read_b128 v[202:205], v166 offset:49152
	ds_read_b128 v[206:209], v166 offset:50176
	ds_read_b128 v[210:213], v166 offset:51200
	ds_read_b128 v[214:217], v166 offset:52224
	ds_read_b128 v[222:225], v166 offset:53248
	ds_read_b128 v[226:229], v166 offset:54272
	ds_read_b128 v[230:233], v166 offset:55296
	ds_read_b128 v[234:237], v166 offset:56320
	global_load_lds_dwordx4 v[218:219], off
	v_lshl_add_u64 v[218:219], v[238:239], 0, s[24:25]
	s_add_i32 m0, s4, 0x2000
	s_add_i32 s4, s10, s39
	global_load_lds_dwordx4 v[218:219], off
	v_lshl_add_u64 v[218:219], v[240:241], 0, s[24:25]
	s_mov_b32 m0, s4
	s_nop 0
	global_load_lds_dwordx4 v[218:219], off
	v_lshl_add_u64 v[218:219], v[242:243], 0, s[24:25]
	s_add_i32 m0, s4, 0x2000
	s_nop 0
	global_load_lds_dwordx4 v[218:219], off
	v_lshl_add_u64 v[218:219], v[244:245], 0, s[24:25]
	s_mov_b32 m0, s49
	s_nop 0
	global_load_lds_dwordx4 v[218:219], off
	v_lshl_add_u64 v[218:219], v[246:247], 0, s[24:25]
	s_mov_b32 m0, s50
	s_nop 0
	global_load_lds_dwordx4 v[218:219], off
	s_waitcnt vmcnt(8)
	s_waitcnt lgkmcnt(0)
	s_barrier
	s_setprio 1
	s_waitcnt lgkmcnt(0)
	v_mfma_f32_16x16x32_bf16 v[60:63], v[170:173], v[202:205], v[60:63]
	v_mfma_f32_16x16x32_bf16 v[60:63], v[174:177], v[206:209], v[60:63]
	v_mfma_f32_16x16x32_bf16 v[56:59], v[182:185], v[206:209], v[56:59]
	v_mfma_f32_16x16x32_bf16 v[56:59], v[178:181], v[202:205], v[56:59]
	v_mfma_f32_16x16x32_bf16 v[52:55], v[186:189], v[202:205], v[52:55]
	v_mfma_f32_16x16x32_bf16 v[52:55], v[190:193], v[206:209], v[52:55]
	v_mfma_f32_16x16x32_bf16 v[48:51], v[198:201], v[206:209], v[48:51]
	v_mfma_f32_16x16x32_bf16 v[48:51], v[194:197], v[202:205], v[48:51]
	v_mfma_f32_16x16x32_bf16 v[32:35], v[194:197], v[210:213], v[32:35]
	v_mfma_f32_16x16x32_bf16 v[32:35], v[198:201], v[214:217], v[32:35]
	v_mfma_f32_16x16x32_bf16 v[36:39], v[190:193], v[214:217], v[36:39]
	v_mfma_f32_16x16x32_bf16 v[36:39], v[186:189], v[210:213], v[36:39]
	v_mfma_f32_16x16x32_bf16 v[40:43], v[178:181], v[210:213], v[40:43]
	v_mfma_f32_16x16x32_bf16 v[40:43], v[182:185], v[214:217], v[40:43]
	v_mfma_f32_16x16x32_bf16 v[44:47], v[174:177], v[214:217], v[44:47]
	v_mfma_f32_16x16x32_bf16 v[44:47], v[170:173], v[210:213], v[44:47]
	v_mfma_f32_16x16x32_bf16 v[28:31], v[170:173], v[222:225], v[28:31]
	v_mfma_f32_16x16x32_bf16 v[28:31], v[174:177], v[226:229], v[28:31]
	v_mfma_f32_16x16x32_bf16 v[24:27], v[182:185], v[226:229], v[24:27]
	v_mfma_f32_16x16x32_bf16 v[24:27], v[178:181], v[222:225], v[24:27]
	v_mfma_f32_16x16x32_bf16 v[20:23], v[186:189], v[222:225], v[20:23]
	v_mfma_f32_16x16x32_bf16 v[20:23], v[190:193], v[226:229], v[20:23]
	v_mfma_f32_16x16x32_bf16 v[16:19], v[198:201], v[226:229], v[16:19]
	v_mfma_f32_16x16x32_bf16 v[16:19], v[194:197], v[222:225], v[16:19]
	v_mfma_f32_16x16x32_bf16 v[0:3], v[194:197], v[230:233], v[0:3]
	v_mfma_f32_16x16x32_bf16 v[0:3], v[198:201], v[234:237], v[0:3]
	v_mfma_f32_16x16x32_bf16 v[4:7], v[190:193], v[234:237], v[4:7]
	v_mfma_f32_16x16x32_bf16 v[4:7], v[186:189], v[230:233], v[4:7]
	v_mfma_f32_16x16x32_bf16 v[8:11], v[178:181], v[230:233], v[8:11]
	v_mfma_f32_16x16x32_bf16 v[8:11], v[182:185], v[234:237], v[8:11]
	v_mfma_f32_16x16x32_bf16 v[12:15], v[174:177], v[234:237], v[12:15]
	v_mfma_f32_16x16x32_bf16 v[12:15], v[170:173], v[230:233], v[12:15]
	s_setprio 0
	s_barrier
	s_add_u32 s2, s2, 0x100
	s_addc_u32 s3, s3, 0
	s_add_u32 s6, s6, 0x100
	s_addc_u32 s7, s7, 0
	s_cmp_ge_i32 s8, s51
	s_mov_b32 s4, s8
	s_cbranch_scc0 .LBB0_970

.LBB0_1056:
	ds_read_b128 v[140:143], v222
	ds_read_b128 v[144:147], v222 offset:1024
	ds_read_b128 v[148:151], v222 offset:2048
	ds_read_b128 v[152:155], v222 offset:3072
	ds_read_b128 v[156:159], v223
	ds_read_b128 v[160:163], v223 offset:1024
	ds_read_b128 v[164:167], v223 offset:2048
	ds_read_b128 v[168:171], v223 offset:3072
	s_add_i32 s62, s26, 2
	s_add_u32 s27, s24, 0x4000
	s_addc_u32 s28, s25, 0
	s_cmp_eq_u32 s46, s26
	s_cselect_b32 s30, s0, s27
	s_cselect_b32 s31, s1, s28
	s_cselect_b32 s28, s22, s60
	s_cselect_b32 s29, s23, s61
	s_add_u32 s26, s30, 0x8000
	s_addc_u32 s27, s31, 0
	v_lshl_add_u64 v[204:205], s[24:25], 0, v[132:133]
	s_add_i32 m0, s38, 0xc000
	ds_read_b128 v[172:175], v224
	ds_read_b128 v[176:179], v224 offset:1024
	ds_read_b128 v[180:183], v224 offset:2048
	ds_read_b128 v[184:187], v224 offset:3072
	ds_read_b128 v[188:191], v224 offset:4096
	ds_read_b128 v[192:195], v224 offset:5120
	ds_read_b128 v[196:199], v224 offset:6144
	ds_read_b128 v[200:203], v224 offset:7168
	global_load_lds_dwordx4 v[204:205], off
	v_lshl_add_u64 v[204:205], s[24:25], 0, v[134:135]
	s_add_i32 m0, s38, 0xe000
	s_nop 0
	global_load_lds_dwordx4 v[204:205], off
	s_waitcnt vmcnt(8)
	s_waitcnt lgkmcnt(0)
	s_barrier
	s_setprio 1
	s_waitcnt lgkmcnt(0)
	v_mfma_f32_16x16x32_bf16 v[124:127], v[140:143], v[172:175], v[124:127]
	v_mfma_f32_16x16x32_bf16 v[124:127], v[144:147], v[176:179], v[124:127]
	v_mfma_f32_16x16x32_bf16 v[120:123], v[152:155], v[176:179], v[120:123]
	v_mfma_f32_16x16x32_bf16 v[120:123], v[148:151], v[172:175], v[120:123]
	v_mfma_f32_16x16x32_bf16 v[108:111], v[156:159], v[172:175], v[108:111]
	v_mfma_f32_16x16x32_bf16 v[108:111], v[160:163], v[176:179], v[108:111]
	v_mfma_f32_16x16x32_bf16 v[100:103], v[168:171], v[176:179], v[100:103]
	v_mfma_f32_16x16x32_bf16 v[100:103], v[164:167], v[172:175], v[100:103]
	v_mfma_f32_16x16x32_bf16 v[84:87], v[164:167], v[180:183], v[84:87]
	v_mfma_f32_16x16x32_bf16 v[84:87], v[168:171], v[184:187], v[84:87]
	v_mfma_f32_16x16x32_bf16 v[92:95], v[160:163], v[184:187], v[92:95]
	v_mfma_f32_16x16x32_bf16 v[92:95], v[156:159], v[180:183], v[92:95]
	v_mfma_f32_16x16x32_bf16 v[112:115], v[148:151], v[180:183], v[112:115]
	v_mfma_f32_16x16x32_bf16 v[112:115], v[152:155], v[184:187], v[112:115]
	v_mfma_f32_16x16x32_bf16 v[116:119], v[144:147], v[184:187], v[116:119]
	v_mfma_f32_16x16x32_bf16 v[116:119], v[140:143], v[180:183], v[116:119]
	v_mfma_f32_16x16x32_bf16 v[104:107], v[140:143], v[188:191], v[104:107]
	v_mfma_f32_16x16x32_bf16 v[104:107], v[144:147], v[192:195], v[104:107]
	v_mfma_f32_16x16x32_bf16 v[96:99], v[152:155], v[192:195], v[96:99]
	v_mfma_f32_16x16x32_bf16 v[96:99], v[148:151], v[188:191], v[96:99]
	v_mfma_f32_16x16x32_bf16 v[76:79], v[156:159], v[188:191], v[76:79]
	v_mfma_f32_16x16x32_bf16 v[76:79], v[160:163], v[192:195], v[76:79]
	v_mfma_f32_16x16x32_bf16 v[72:75], v[168:171], v[192:195], v[72:75]
	v_mfma_f32_16x16x32_bf16 v[72:75], v[164:167], v[188:191], v[72:75]
	v_mfma_f32_16x16x32_bf16 v[64:67], v[164:167], v[196:199], v[64:67]
	v_mfma_f32_16x16x32_bf16 v[64:67], v[168:171], v[200:203], v[64:67]
	v_mfma_f32_16x16x32_bf16 v[68:71], v[160:163], v[200:203], v[68:71]
	v_mfma_f32_16x16x32_bf16 v[68:71], v[156:159], v[196:199], v[68:71]
	v_mfma_f32_16x16x32_bf16 v[80:83], v[148:151], v[196:199], v[80:83]
	v_mfma_f32_16x16x32_bf16 v[80:83], v[152:155], v[200:203], v[80:83]
	v_mfma_f32_16x16x32_bf16 v[88:91], v[144:147], v[200:203], v[88:91]
	v_mfma_f32_16x16x32_bf16 v[88:91], v[140:143], v[196:199], v[88:91]
	s_setprio 0
	s_barrier
	s_add_i32 s63, s50, s37
	v_lshl_add_u64 v[204:205], s[28:29], 0, v[128:129]
	s_mov_b32 m0, s63
	ds_read_b128 v[172:175], v224 offset:16384
	ds_read_b128 v[176:179], v224 offset:17408
	ds_read_b128 v[180:183], v224 offset:18432
	ds_read_b128 v[184:187], v224 offset:19456
	ds_read_b128 v[188:191], v224 offset:20480
	ds_read_b128 v[192:195], v224 offset:21504
	ds_read_b128 v[196:199], v224 offset:22528
	ds_read_b128 v[200:203], v224 offset:23552
	global_load_lds_dwordx4 v[204:205], off
	s_add_i32 m0, s63, 0x2000
	s_add_u32 s64, s28, 0x4000
	v_lshl_add_u64 v[204:205], s[28:29], 0, v[130:131]
	s_addc_u32 s65, s29, 0
	s_add_i32 s63, s51, s37
	global_load_lds_dwordx4 v[204:205], off
	v_lshl_add_u64 v[204:205], s[64:65], 0, v[128:129]
	s_mov_b32 m0, s63
	s_nop 0
	global_load_lds_dwordx4 v[204:205], off
	v_lshl_add_u64 v[204:205], s[64:65], 0, v[130:131]
	s_add_i32 m0, s63, 0x2000
	s_nop 0
	global_load_lds_dwordx4 v[204:205], off
	v_lshl_add_u64 v[204:205], s[30:31], 0, v[128:129]
	s_mov_b32 m0, s38
	s_nop 0
	global_load_lds_dwordx4 v[204:205], off
	v_lshl_add_u64 v[204:205], s[30:31], 0, v[130:131]
	s_mov_b32 m0, s39
	s_nop 0
	global_load_lds_dwordx4 v[204:205], off
	s_waitcnt vmcnt(8)
	s_waitcnt lgkmcnt(0)
	s_barrier
	s_setprio 1
	s_waitcnt lgkmcnt(0)
	v_mfma_f32_16x16x32_bf16 v[60:63], v[140:143], v[172:175], v[60:63]
	v_mfma_f32_16x16x32_bf16 v[60:63], v[144:147], v[176:179], v[60:63]
	v_mfma_f32_16x16x32_bf16 v[56:59], v[152:155], v[176:179], v[56:59]
	v_mfma_f32_16x16x32_bf16 v[56:59], v[148:151], v[172:175], v[56:59]
	v_mfma_f32_16x16x32_bf16 v[44:47], v[156:159], v[172:175], v[44:47]
	v_mfma_f32_16x16x32_bf16 v[44:47], v[160:163], v[176:179], v[44:47]
	v_mfma_f32_16x16x32_bf16 v[36:39], v[168:171], v[176:179], v[36:39]
	v_mfma_f32_16x16x32_bf16 v[36:39], v[164:167], v[172:175], v[36:39]
	v_mfma_f32_16x16x32_bf16 v[20:23], v[164:167], v[180:183], v[20:23]
	v_mfma_f32_16x16x32_bf16 v[20:23], v[168:171], v[184:187], v[20:23]
	v_mfma_f32_16x16x32_bf16 v[28:31], v[160:163], v[184:187], v[28:31]
	v_mfma_f32_16x16x32_bf16 v[28:31], v[156:159], v[180:183], v[28:31]
	v_mfma_f32_16x16x32_bf16 v[48:51], v[148:151], v[180:183], v[48:51]
	v_mfma_f32_16x16x32_bf16 v[48:51], v[152:155], v[184:187], v[48:51]
	v_mfma_f32_16x16x32_bf16 v[52:55], v[144:147], v[184:187], v[52:55]
	v_mfma_f32_16x16x32_bf16 v[52:55], v[140:143], v[180:183], v[52:55]
	v_mfma_f32_16x16x32_bf16 v[40:43], v[140:143], v[188:191], v[40:43]
	v_mfma_f32_16x16x32_bf16 v[40:43], v[144:147], v[192:195], v[40:43]
	v_mfma_f32_16x16x32_bf16 v[32:35], v[152:155], v[192:195], v[32:35]
	v_mfma_f32_16x16x32_bf16 v[32:35], v[148:151], v[188:191], v[32:35]
	v_mfma_f32_16x16x32_bf16 v[12:15], v[156:159], v[188:191], v[12:15]
	v_mfma_f32_16x16x32_bf16 v[12:15], v[160:163], v[192:195], v[12:15]
	v_mfma_f32_16x16x32_bf16 v[8:11], v[168:171], v[192:195], v[8:11]
	v_mfma_f32_16x16x32_bf16 v[8:11], v[164:167], v[188:191], v[8:11]
	v_mfma_f32_16x16x32_bf16 v[0:3], v[164:167], v[196:199], v[0:3]
	v_mfma_f32_16x16x32_bf16 v[0:3], v[168:171], v[200:203], v[0:3]
	v_mfma_f32_16x16x32_bf16 v[4:7], v[160:163], v[200:203], v[4:7]
	v_mfma_f32_16x16x32_bf16 v[4:7], v[156:159], v[196:199], v[4:7]
	v_mfma_f32_16x16x32_bf16 v[16:19], v[148:151], v[196:199], v[16:19]
	v_mfma_f32_16x16x32_bf16 v[16:19], v[152:155], v[200:203], v[16:19]
	v_mfma_f32_16x16x32_bf16 v[24:27], v[144:147], v[200:203], v[24:27]
	v_mfma_f32_16x16x32_bf16 v[24:27], v[140:143], v[196:199], v[24:27]
	s_setprio 0
	s_barrier
	s_add_i32 s63, 0, 0x18000
	s_add_i32 s64, 0, 0x1c000
	v_add_u32_e32 v152, s63, v219
	v_add_u32_e32 v168, s64, v219
	ds_read_b128 v[140:143], v152
	ds_read_b128 v[144:147], v152 offset:1024
	ds_read_b128 v[148:151], v152 offset:2048
	ds_read_b128 v[152:155], v152 offset:3072
	ds_read_b128 v[156:159], v168
	ds_read_b128 v[160:163], v168 offset:1024
	ds_read_b128 v[164:167], v168 offset:2048
	ds_read_b128 v[168:171], v168 offset:3072
	s_add_u32 s30, s30, 0x4000
	s_addc_u32 s31, s31, 0
	s_mov_b32 m0, s40
	v_lshl_add_u64 v[204:205], s[30:31], 0, v[128:129]
	ds_read_b128 v[172:175], v224 offset:32768
	ds_read_b128 v[176:179], v224 offset:33792
	ds_read_b128 v[180:183], v224 offset:34816
	ds_read_b128 v[184:187], v224 offset:35840
	ds_read_b128 v[188:191], v224 offset:36864
	ds_read_b128 v[192:195], v224 offset:37888
	ds_read_b128 v[196:199], v224 offset:38912
	ds_read_b128 v[200:203], v224 offset:39936
	global_load_lds_dwordx4 v[204:205], off
	v_lshl_add_u64 v[204:205], s[30:31], 0, v[130:131]
	s_mov_b32 m0, s41
	s_nop 0
	global_load_lds_dwordx4 v[204:205], off
	s_waitcnt vmcnt(8)
	s_waitcnt lgkmcnt(0)
	s_barrier
	s_setprio 1
	s_waitcnt lgkmcnt(0)
	v_mfma_f32_16x16x32_bf16 v[124:127], v[140:143], v[172:175], v[124:127]
	v_mfma_f32_16x16x32_bf16 v[124:127], v[144:147], v[176:179], v[124:127]
	v_mfma_f32_16x16x32_bf16 v[120:123], v[152:155], v[176:179], v[120:123]
	v_mfma_f32_16x16x32_bf16 v[120:123], v[148:151], v[172:175], v[120:123]
	v_mfma_f32_16x16x32_bf16 v[108:111], v[156:159], v[172:175], v[108:111]
	v_mfma_f32_16x16x32_bf16 v[108:111], v[160:163], v[176:179], v[108:111]
	v_mfma_f32_16x16x32_bf16 v[100:103], v[168:171], v[176:179], v[100:103]
	v_mfma_f32_16x16x32_bf16 v[100:103], v[164:167], v[172:175], v[100:103]
	v_mfma_f32_16x16x32_bf16 v[84:87], v[164:167], v[180:183], v[84:87]
	v_mfma_f32_16x16x32_bf16 v[84:87], v[168:171], v[184:187], v[84:87]
	v_mfma_f32_16x16x32_bf16 v[92:95], v[160:163], v[184:187], v[92:95]
	v_mfma_f32_16x16x32_bf16 v[92:95], v[156:159], v[180:183], v[92:95]
	v_mfma_f32_16x16x32_bf16 v[112:115], v[148:151], v[180:183], v[112:115]
	v_mfma_f32_16x16x32_bf16 v[112:115], v[152:155], v[184:187], v[112:115]
	v_mfma_f32_16x16x32_bf16 v[116:119], v[144:147], v[184:187], v[116:119]
	v_mfma_f32_16x16x32_bf16 v[116:119], v[140:143], v[180:183], v[116:119]
	v_mfma_f32_16x16x32_bf16 v[104:107], v[140:143], v[188:191], v[104:107]
	v_mfma_f32_16x16x32_bf16 v[104:107], v[144:147], v[192:195], v[104:107]
	v_mfma_f32_16x16x32_bf16 v[96:99], v[152:155], v[192:195], v[96:99]
	v_mfma_f32_16x16x32_bf16 v[96:99], v[148:151], v[188:191], v[96:99]
	v_mfma_f32_16x16x32_bf16 v[76:79], v[156:159], v[188:191], v[76:79]
	v_mfma_f32_16x16x32_bf16 v[76:79], v[160:163], v[192:195], v[76:79]
	v_mfma_f32_16x16x32_bf16 v[72:75], v[168:171], v[192:195], v[72:75]
	v_mfma_f32_16x16x32_bf16 v[72:75], v[164:167], v[188:191], v[72:75]
	v_mfma_f32_16x16x32_bf16 v[64:67], v[164:167], v[196:199], v[64:67]
	v_mfma_f32_16x16x32_bf16 v[64:67], v[168:171], v[200:203], v[64:67]
	v_mfma_f32_16x16x32_bf16 v[68:71], v[160:163], v[200:203], v[68:71]
	v_mfma_f32_16x16x32_bf16 v[68:71], v[156:159], v[196:199], v[68:71]
	v_mfma_f32_16x16x32_bf16 v[80:83], v[148:151], v[196:199], v[80:83]
	v_mfma_f32_16x16x32_bf16 v[80:83], v[152:155], v[200:203], v[80:83]
	v_mfma_f32_16x16x32_bf16 v[88:91], v[144:147], v[200:203], v[88:91]
	v_mfma_f32_16x16x32_bf16 v[88:91], v[140:143], v[196:199], v[88:91]
	s_setprio 0
	s_barrier
	s_add_u32 s30, s28, 0x8000
	s_addc_u32 s31, s29, 0
	s_add_i32 s63, s63, s37
	v_lshl_add_u64 v[204:205], s[30:31], 0, v[128:129]
	s_mov_b32 m0, s63
	ds_read_b128 v[172:175], v224 offset:49152
	ds_read_b128 v[176:179], v224 offset:50176
	ds_read_b128 v[180:183], v224 offset:51200
	ds_read_b128 v[184:187], v224 offset:52224
	ds_read_b128 v[188:191], v224 offset:53248
	ds_read_b128 v[192:195], v224 offset:54272
	ds_read_b128 v[196:199], v224 offset:55296
	ds_read_b128 v[200:203], v224 offset:56320
	global_load_lds_dwordx4 v[204:205], off
	s_add_i32 m0, s63, 0x2000
	s_add_u32 s28, s28, 0xc000
	v_lshl_add_u64 v[204:205], s[30:31], 0, v[130:131]
	s_addc_u32 s29, s29, 0
	s_add_i32 s30, s64, s37
	global_load_lds_dwordx4 v[204:205], off
	v_lshl_add_u64 v[204:205], s[28:29], 0, v[128:129]
	s_mov_b32 m0, s30
	s_nop 0
	global_load_lds_dwordx4 v[204:205], off
	v_lshl_add_u64 v[204:205], s[28:29], 0, v[130:131]
	s_add_i32 m0, s30, 0x2000
	s_nop 0
	global_load_lds_dwordx4 v[204:205], off
	v_lshl_add_u64 v[204:205], s[26:27], 0, v[128:129]
	s_mov_b32 m0, s44
	s_nop 0
	global_load_lds_dwordx4 v[204:205], off
	v_lshl_add_u64 v[204:205], s[26:27], 0, v[130:131]
	s_mov_b32 m0, s45
	s_nop 0
	global_load_lds_dwordx4 v[204:205], off
	s_waitcnt vmcnt(8)
	s_waitcnt lgkmcnt(0)
	s_barrier
	s_setprio 1
	s_waitcnt lgkmcnt(0)
	v_mfma_f32_16x16x32_bf16 v[60:63], v[140:143], v[172:175], v[60:63]
	v_mfma_f32_16x16x32_bf16 v[60:63], v[144:147], v[176:179], v[60:63]
	v_mfma_f32_16x16x32_bf16 v[56:59], v[152:155], v[176:179], v[56:59]
	v_mfma_f32_16x16x32_bf16 v[56:59], v[148:151], v[172:175], v[56:59]
	v_mfma_f32_16x16x32_bf16 v[44:47], v[156:159], v[172:175], v[44:47]
	v_mfma_f32_16x16x32_bf16 v[44:47], v[160:163], v[176:179], v[44:47]
	v_mfma_f32_16x16x32_bf16 v[36:39], v[168:171], v[176:179], v[36:39]
	v_mfma_f32_16x16x32_bf16 v[36:39], v[164:167], v[172:175], v[36:39]
	v_mfma_f32_16x16x32_bf16 v[20:23], v[164:167], v[180:183], v[20:23]
	v_mfma_f32_16x16x32_bf16 v[20:23], v[168:171], v[184:187], v[20:23]
	v_mfma_f32_16x16x32_bf16 v[28:31], v[160:163], v[184:187], v[28:31]
	v_mfma_f32_16x16x32_bf16 v[28:31], v[156:159], v[180:183], v[28:31]
	v_mfma_f32_16x16x32_bf16 v[48:51], v[148:151], v[180:183], v[48:51]
	v_mfma_f32_16x16x32_bf16 v[48:51], v[152:155], v[184:187], v[48:51]
	v_mfma_f32_16x16x32_bf16 v[52:55], v[144:147], v[184:187], v[52:55]
	v_mfma_f32_16x16x32_bf16 v[52:55], v[140:143], v[180:183], v[52:55]
	v_mfma_f32_16x16x32_bf16 v[40:43], v[140:143], v[188:191], v[40:43]
	v_mfma_f32_16x16x32_bf16 v[40:43], v[144:147], v[192:195], v[40:43]
	v_mfma_f32_16x16x32_bf16 v[32:35], v[152:155], v[192:195], v[32:35]
	v_mfma_f32_16x16x32_bf16 v[32:35], v[148:151], v[188:191], v[32:35]
	v_mfma_f32_16x16x32_bf16 v[12:15], v[156:159], v[188:191], v[12:15]
	v_mfma_f32_16x16x32_bf16 v[12:15], v[160:163], v[192:195], v[12:15]
	v_mfma_f32_16x16x32_bf16 v[8:11], v[168:171], v[192:195], v[8:11]
	v_mfma_f32_16x16x32_bf16 v[8:11], v[164:167], v[188:191], v[8:11]
	v_mfma_f32_16x16x32_bf16 v[0:3], v[164:167], v[196:199], v[0:3]
	v_mfma_f32_16x16x32_bf16 v[0:3], v[168:171], v[200:203], v[0:3]
	v_mfma_f32_16x16x32_bf16 v[4:7], v[160:163], v[200:203], v[4:7]
	v_mfma_f32_16x16x32_bf16 v[4:7], v[156:159], v[196:199], v[4:7]
	v_mfma_f32_16x16x32_bf16 v[16:19], v[148:151], v[196:199], v[16:19]
	v_mfma_f32_16x16x32_bf16 v[16:19], v[152:155], v[200:203], v[16:19]
	v_mfma_f32_16x16x32_bf16 v[24:27], v[144:147], v[200:203], v[24:27]
	v_mfma_f32_16x16x32_bf16 v[24:27], v[140:143], v[196:199], v[24:27]
	s_setprio 0
	s_barrier
	s_add_u32 s24, s24, 0x10000
	s_addc_u32 s25, s25, 0
	s_add_u32 s60, s60, 0x10000
	s_addc_u32 s61, s61, 0
	s_cmp_ge_i32 s62, s43
	s_mov_b32 s26, s62
	s_cbranch_scc0 .LBB0_1056
	v_pk_mul_f32 v[198:199], v[126:127], 0.5 op_sel_hi:[1,0]
	v_pk_mul_f32 v[200:201], v[124:125], 0.5 op_sel_hi:[1,0]
	v_pk_mul_f32 v[202:203], v[122:123], 0.5 op_sel_hi:[1,0]
	v_pk_mul_f32 v[204:205], v[120:121], 0.5 op_sel_hi:[1,0]
	v_pk_mul_f32 v[208:209], v[110:111], 0.5 op_sel_hi:[1,0]
	v_pk_mul_f32 v[206:207], v[108:109], 0.5 op_sel_hi:[1,0]
	v_pk_mul_f32 v[196:197], v[102:103], 0.5 op_sel_hi:[1,0]
	v_pk_mul_f32 v[194:195], v[100:101], 0.5 op_sel_hi:[1,0]
	v_pk_mul_f32 v[192:193], v[118:119], 0.5 op_sel_hi:[1,0]
	v_pk_mul_f32 v[190:191], v[116:117], 0.5 op_sel_hi:[1,0]
	v_pk_mul_f32 v[188:189], v[114:115], 0.5 op_sel_hi:[1,0]
	v_pk_mul_f32 v[186:187], v[112:113], 0.5 op_sel_hi:[1,0]
	v_pk_mul_f32 v[184:185], v[94:95], 0.5 op_sel_hi:[1,0]
	v_pk_mul_f32 v[182:183], v[92:93], 0.5 op_sel_hi:[1,0]
	v_pk_mul_f32 v[180:181], v[86:87], 0.5 op_sel_hi:[1,0]
	v_pk_mul_f32 v[178:179], v[84:85], 0.5 op_sel_hi:[1,0]
	v_pk_mul_f32 v[176:177], v[106:107], 0.5 op_sel_hi:[1,0]
	v_pk_mul_f32 v[174:175], v[104:105], 0.5 op_sel_hi:[1,0]
	v_pk_mul_f32 v[172:173], v[98:99], 0.5 op_sel_hi:[1,0]
	v_pk_mul_f32 v[170:171], v[96:97], 0.5 op_sel_hi:[1,0]
	v_pk_mul_f32 v[168:169], v[78:79], 0.5 op_sel_hi:[1,0]
	v_pk_mul_f32 v[166:167], v[76:77], 0.5 op_sel_hi:[1,0]
	v_pk_mul_f32 v[164:165], v[74:75], 0.5 op_sel_hi:[1,0]
	v_pk_mul_f32 v[162:163], v[72:73], 0.5 op_sel_hi:[1,0]
	v_pk_mul_f32 v[160:161], v[90:91], 0.5 op_sel_hi:[1,0]
	v_pk_mul_f32 v[158:159], v[88:89], 0.5 op_sel_hi:[1,0]
	v_pk_mul_f32 v[156:157], v[82:83], 0.5 op_sel_hi:[1,0]
	v_pk_mul_f32 v[154:155], v[80:81], 0.5 op_sel_hi:[1,0]
	v_pk_mul_f32 v[152:153], v[70:71], 0.5 op_sel_hi:[1,0]
	v_pk_mul_f32 v[150:151], v[68:69], 0.5 op_sel_hi:[1,0]
	v_pk_mul_f32 v[148:149], v[66:67], 0.5 op_sel_hi:[1,0]
	v_pk_mul_f32 v[146:147], v[64:65], 0.5 op_sel_hi:[1,0]
	v_pk_mul_f32 v[142:143], v[62:63], 0.5 op_sel_hi:[1,0]
	v_pk_mul_f32 v[140:141], v[60:61], 0.5 op_sel_hi:[1,0]
	v_pk_mul_f32 v[126:127], v[58:59], 0.5 op_sel_hi:[1,0]
	v_pk_mul_f32 v[124:125], v[56:57], 0.5 op_sel_hi:[1,0]
	v_pk_mul_f32 v[122:123], v[46:47], 0.5 op_sel_hi:[1,0]
	v_pk_mul_f32 v[120:121], v[44:45], 0.5 op_sel_hi:[1,0]
	v_pk_mul_f32 v[118:119], v[38:39], 0.5 op_sel_hi:[1,0]
	v_pk_mul_f32 v[116:117], v[36:37], 0.5 op_sel_hi:[1,0]
	v_pk_mul_f32 v[114:115], v[54:55], 0.5 op_sel_hi:[1,0]
	v_pk_mul_f32 v[112:113], v[52:53], 0.5 op_sel_hi:[1,0]
	v_pk_mul_f32 v[110:111], v[50:51], 0.5 op_sel_hi:[1,0]
	v_pk_mul_f32 v[108:109], v[48:49], 0.5 op_sel_hi:[1,0]
	v_pk_mul_f32 v[106:107], v[30:31], 0.5 op_sel_hi:[1,0]
	v_pk_mul_f32 v[104:105], v[28:29], 0.5 op_sel_hi:[1,0]
	v_pk_mul_f32 v[102:103], v[22:23], 0.5 op_sel_hi:[1,0]
	v_pk_mul_f32 v[100:101], v[20:21], 0.5 op_sel_hi:[1,0]
	v_pk_mul_f32 v[98:99], v[42:43], 0.5 op_sel_hi:[1,0]
	v_pk_mul_f32 v[96:97], v[40:41], 0.5 op_sel_hi:[1,0]
	v_pk_mul_f32 v[94:95], v[34:35], 0.5 op_sel_hi:[1,0]
	v_pk_mul_f32 v[92:93], v[32:33], 0.5 op_sel_hi:[1,0]
	v_pk_mul_f32 v[90:91], v[14:15], 0.5 op_sel_hi:[1,0]
	v_pk_mul_f32 v[88:89], v[12:13], 0.5 op_sel_hi:[1,0]
	v_pk_mul_f32 v[86:87], v[10:11], 0.5 op_sel_hi:[1,0]
	v_pk_mul_f32 v[84:85], v[8:9], 0.5 op_sel_hi:[1,0]
	v_pk_mul_f32 v[82:83], v[26:27], 0.5 op_sel_hi:[1,0]
	v_pk_mul_f32 v[80:81], v[24:25], 0.5 op_sel_hi:[1,0]
	v_pk_mul_f32 v[78:79], v[18:19], 0.5 op_sel_hi:[1,0]
	v_pk_mul_f32 v[76:77], v[16:17], 0.5 op_sel_hi:[1,0]
	v_pk_mul_f32 v[74:75], v[6:7], 0.5 op_sel_hi:[1,0]
	v_pk_mul_f32 v[72:73], v[4:5], 0.5 op_sel_hi:[1,0]
	v_pk_mul_f32 v[70:71], v[2:3], 0.5 op_sel_hi:[1,0]
	v_pk_mul_f32 v[68:69], v[0:1], 0.5 op_sel_hi:[1,0]

.LBB0_1159:
	ds_read_b128 v[128:131], v205
	ds_read_b128 v[132:135], v205 offset:1024
	ds_read_b128 v[136:139], v205 offset:2048
	ds_read_b128 v[140:143], v205 offset:3072
	ds_read_b128 v[144:147], v206
	ds_read_b128 v[160:163], v206 offset:1024
	ds_read_b128 v[164:167], v206 offset:2048
	ds_read_b128 v[168:171], v206 offset:3072
	s_add_i32 s41, s6, 2
	s_add_u32 s68, s0, 0x80
	s_addc_u32 s7, s1, 0
	s_cmp_eq_u32 s57, s6
	s_cselect_b32 s6, s34, s68
	s_cselect_b32 s7, s35, s7
	s_cselect_b32 s69, s37, s39
	s_cselect_b32 s68, s36, s38
	v_lshl_add_u64 v[200:201], s[0:1], 0, v[152:153]
	s_add_i32 m0, s47, 0xc000
	ds_read_b128 v[172:175], v207
	ds_read_b128 v[176:179], v207 offset:1024
	ds_read_b128 v[180:183], v207 offset:2048
	ds_read_b128 v[184:187], v207 offset:3072
	ds_read_b128 v[188:191], v207 offset:4096
	ds_read_b128 v[192:195], v207 offset:5120
	ds_read_b128 v[196:199], v207 offset:6144
	ds_read_b128 v[212:215], v207 offset:7168
	global_load_lds_dwordx4 v[200:201], off
	v_lshl_add_u64 v[200:201], s[0:1], 0, v[154:155]
	s_add_i32 m0, s47, 0xe000
	s_nop 0
	global_load_lds_dwordx4 v[200:201], off
	s_waitcnt vmcnt(8)
	s_waitcnt lgkmcnt(0)
	s_barrier
	s_setprio 1
	s_waitcnt lgkmcnt(0)
	v_mfma_f32_16x16x32_bf16 v[124:127], v[128:131], v[172:175], v[124:127]
	v_mfma_f32_16x16x32_bf16 v[124:127], v[132:135], v[176:179], v[124:127]
	v_mfma_f32_16x16x32_bf16 v[120:123], v[140:143], v[176:179], v[120:123]
	v_mfma_f32_16x16x32_bf16 v[120:123], v[136:139], v[172:175], v[120:123]
	v_mfma_f32_16x16x32_bf16 v[116:119], v[144:147], v[172:175], v[116:119]
	v_mfma_f32_16x16x32_bf16 v[116:119], v[160:163], v[176:179], v[116:119]
	v_mfma_f32_16x16x32_bf16 v[112:115], v[168:171], v[176:179], v[112:115]
	v_mfma_f32_16x16x32_bf16 v[112:115], v[164:167], v[172:175], v[112:115]
	v_mfma_f32_16x16x32_bf16 v[96:99], v[164:167], v[180:183], v[96:99]
	v_mfma_f32_16x16x32_bf16 v[96:99], v[168:171], v[184:187], v[96:99]
	v_mfma_f32_16x16x32_bf16 v[100:103], v[160:163], v[184:187], v[100:103]
	v_mfma_f32_16x16x32_bf16 v[100:103], v[144:147], v[180:183], v[100:103]
	v_mfma_f32_16x16x32_bf16 v[104:107], v[136:139], v[180:183], v[104:107]
	v_mfma_f32_16x16x32_bf16 v[104:107], v[140:143], v[184:187], v[104:107]
	v_mfma_f32_16x16x32_bf16 v[108:111], v[132:135], v[184:187], v[108:111]
	v_mfma_f32_16x16x32_bf16 v[108:111], v[128:131], v[180:183], v[108:111]
	v_mfma_f32_16x16x32_bf16 v[92:95], v[128:131], v[188:191], v[92:95]
	v_mfma_f32_16x16x32_bf16 v[92:95], v[132:135], v[192:195], v[92:95]
	v_mfma_f32_16x16x32_bf16 v[88:91], v[140:143], v[192:195], v[88:91]
	v_mfma_f32_16x16x32_bf16 v[88:91], v[136:139], v[188:191], v[88:91]
	v_mfma_f32_16x16x32_bf16 v[84:87], v[144:147], v[188:191], v[84:87]
	v_mfma_f32_16x16x32_bf16 v[84:87], v[160:163], v[192:195], v[84:87]
	v_mfma_f32_16x16x32_bf16 v[80:83], v[168:171], v[192:195], v[80:83]
	v_mfma_f32_16x16x32_bf16 v[80:83], v[164:167], v[188:191], v[80:83]
	v_mfma_f32_16x16x32_bf16 v[64:67], v[164:167], v[196:199], v[64:67]
	v_mfma_f32_16x16x32_bf16 v[64:67], v[168:171], v[212:215], v[64:67]
	v_mfma_f32_16x16x32_bf16 v[68:71], v[160:163], v[212:215], v[68:71]
	v_mfma_f32_16x16x32_bf16 v[68:71], v[144:147], v[196:199], v[68:71]
	v_mfma_f32_16x16x32_bf16 v[72:75], v[136:139], v[196:199], v[72:75]
	v_mfma_f32_16x16x32_bf16 v[72:75], v[140:143], v[212:215], v[72:75]
	v_mfma_f32_16x16x32_bf16 v[76:79], v[132:135], v[212:215], v[76:79]
	v_mfma_f32_16x16x32_bf16 v[76:79], v[128:131], v[196:199], v[76:79]
	s_setprio 0
	s_barrier
	s_add_i32 s70, s60, s46
	v_lshl_add_u64 v[200:201], s[68:69], 0, v[148:149]
	s_mov_b32 m0, s70
	ds_read_b128 v[172:175], v207 offset:16384
	ds_read_b128 v[176:179], v207 offset:17408
	ds_read_b128 v[180:183], v207 offset:18432
	ds_read_b128 v[184:187], v207 offset:19456
	ds_read_b128 v[188:191], v207 offset:20480
	ds_read_b128 v[192:195], v207 offset:21504
	ds_read_b128 v[196:199], v207 offset:22528
	ds_read_b128 v[212:215], v207 offset:23552
	global_load_lds_dwordx4 v[200:201], off
	s_add_i32 m0, s70, 0x2000
	v_lshl_add_u64 v[216:217], s[68:69], 0, v[150:151]
	s_add_u32 s68, s68, s10
	s_addc_u32 s69, s69, s11
	s_add_i32 s70, s61, s46
	global_load_lds_dwordx4 v[216:217], off
	v_lshl_add_u64 v[218:219], s[68:69], 0, v[148:149]
	s_mov_b32 m0, s70
	v_lshl_add_u64 v[220:221], s[68:69], 0, v[150:151]
	global_load_lds_dwordx4 v[218:219], off
	s_add_i32 m0, s70, 0x2000
	v_lshl_add_u64 v[222:223], s[6:7], 0, v[148:149]
	global_load_lds_dwordx4 v[220:221], off
	s_mov_b32 m0, s47
	v_lshl_add_u64 v[224:225], s[6:7], 0, v[150:151]
	global_load_lds_dwordx4 v[222:223], off
	s_mov_b32 m0, s48
	s_nop 0
	global_load_lds_dwordx4 v[224:225], off
	s_waitcnt vmcnt(8)
	s_waitcnt lgkmcnt(0)
	s_barrier
	s_setprio 1
	s_waitcnt lgkmcnt(0)
	v_mfma_f32_16x16x32_bf16 v[60:63], v[128:131], v[172:175], v[60:63]
	v_mfma_f32_16x16x32_bf16 v[60:63], v[132:135], v[176:179], v[60:63]
	v_mfma_f32_16x16x32_bf16 v[56:59], v[140:143], v[176:179], v[56:59]
	v_mfma_f32_16x16x32_bf16 v[56:59], v[136:139], v[172:175], v[56:59]
	v_mfma_f32_16x16x32_bf16 v[52:55], v[144:147], v[172:175], v[52:55]
	v_mfma_f32_16x16x32_bf16 v[52:55], v[160:163], v[176:179], v[52:55]
	v_mfma_f32_16x16x32_bf16 v[48:51], v[168:171], v[176:179], v[48:51]
	v_mfma_f32_16x16x32_bf16 v[48:51], v[164:167], v[172:175], v[48:51]
	v_mfma_f32_16x16x32_bf16 v[32:35], v[164:167], v[180:183], v[32:35]
	v_mfma_f32_16x16x32_bf16 v[32:35], v[168:171], v[184:187], v[32:35]
	v_mfma_f32_16x16x32_bf16 v[36:39], v[160:163], v[184:187], v[36:39]
	v_mfma_f32_16x16x32_bf16 v[36:39], v[144:147], v[180:183], v[36:39]
	v_mfma_f32_16x16x32_bf16 v[40:43], v[136:139], v[180:183], v[40:43]
	v_mfma_f32_16x16x32_bf16 v[40:43], v[140:143], v[184:187], v[40:43]
	v_mfma_f32_16x16x32_bf16 v[44:47], v[132:135], v[184:187], v[44:47]
	v_mfma_f32_16x16x32_bf16 v[44:47], v[128:131], v[180:183], v[44:47]
	v_mfma_f32_16x16x32_bf16 v[28:31], v[128:131], v[188:191], v[28:31]
	v_mfma_f32_16x16x32_bf16 v[28:31], v[132:135], v[192:195], v[28:31]
	v_mfma_f32_16x16x32_bf16 v[24:27], v[140:143], v[192:195], v[24:27]
	v_mfma_f32_16x16x32_bf16 v[24:27], v[136:139], v[188:191], v[24:27]
	v_mfma_f32_16x16x32_bf16 v[20:23], v[144:147], v[188:191], v[20:23]
	v_mfma_f32_16x16x32_bf16 v[20:23], v[160:163], v[192:195], v[20:23]
	v_mfma_f32_16x16x32_bf16 v[16:19], v[168:171], v[192:195], v[16:19]
	v_mfma_f32_16x16x32_bf16 v[16:19], v[164:167], v[188:191], v[16:19]
	v_mfma_f32_16x16x32_bf16 v[0:3], v[164:167], v[196:199], v[0:3]
	v_mfma_f32_16x16x32_bf16 v[0:3], v[168:171], v[212:215], v[0:3]
	v_mfma_f32_16x16x32_bf16 v[4:7], v[160:163], v[212:215], v[4:7]
	v_mfma_f32_16x16x32_bf16 v[4:7], v[144:147], v[196:199], v[4:7]
	v_mfma_f32_16x16x32_bf16 v[8:11], v[136:139], v[196:199], v[8:11]
	v_mfma_f32_16x16x32_bf16 v[8:11], v[140:143], v[212:215], v[8:11]
	v_mfma_f32_16x16x32_bf16 v[12:15], v[132:135], v[212:215], v[12:15]
	v_mfma_f32_16x16x32_bf16 v[12:15], v[128:131], v[196:199], v[12:15]
	s_setprio 0
	s_barrier
	s_add_i32 s68, 0, 0x18000
	s_add_i32 s69, 0, 0x1c000
	v_add_u32_e32 v140, s68, v203
	v_add_u32_e32 v168, s69, v203
	ds_read_b128 v[128:131], v140
	ds_read_b128 v[132:135], v140 offset:1024
	ds_read_b128 v[136:139], v140 offset:2048
	ds_read_b128 v[140:143], v140 offset:3072
	ds_read_b128 v[144:147], v168
	ds_read_b128 v[160:163], v168 offset:1024
	ds_read_b128 v[164:167], v168 offset:2048
	ds_read_b128 v[168:171], v168 offset:3072
	s_add_u32 s6, s6, s10
	s_addc_u32 s7, s7, s11
	s_mov_b32 m0, s49
	v_lshl_add_u64 v[226:227], s[6:7], 0, v[148:149]
	ds_read_b128 v[172:175], v207 offset:32768
	ds_read_b128 v[176:179], v207 offset:33792
	ds_read_b128 v[180:183], v207 offset:34816
	ds_read_b128 v[184:187], v207 offset:35840
	ds_read_b128 v[188:191], v207 offset:36864
	ds_read_b128 v[192:195], v207 offset:37888
	ds_read_b128 v[196:199], v207 offset:38912
	ds_read_b128 v[212:215], v207 offset:39936
	global_load_lds_dwordx4 v[226:227], off
	v_lshl_add_u64 v[226:227], s[6:7], 0, v[150:151]
	s_mov_b32 m0, s50
	s_nop 0
	global_load_lds_dwordx4 v[226:227], off
	s_waitcnt vmcnt(8)
	s_waitcnt lgkmcnt(0)
	s_barrier
	s_setprio 1
	s_waitcnt lgkmcnt(0)
	v_mfma_f32_16x16x32_bf16 v[124:127], v[128:131], v[172:175], v[124:127]
	v_mfma_f32_16x16x32_bf16 v[124:127], v[132:135], v[176:179], v[124:127]
	v_mfma_f32_16x16x32_bf16 v[120:123], v[140:143], v[176:179], v[120:123]
	v_mfma_f32_16x16x32_bf16 v[120:123], v[136:139], v[172:175], v[120:123]
	v_mfma_f32_16x16x32_bf16 v[116:119], v[144:147], v[172:175], v[116:119]
	v_mfma_f32_16x16x32_bf16 v[116:119], v[160:163], v[176:179], v[116:119]
	v_mfma_f32_16x16x32_bf16 v[112:115], v[168:171], v[176:179], v[112:115]
	v_mfma_f32_16x16x32_bf16 v[112:115], v[164:167], v[172:175], v[112:115]
	v_mfma_f32_16x16x32_bf16 v[96:99], v[164:167], v[180:183], v[96:99]
	v_mfma_f32_16x16x32_bf16 v[96:99], v[168:171], v[184:187], v[96:99]
	v_mfma_f32_16x16x32_bf16 v[100:103], v[160:163], v[184:187], v[100:103]
	v_mfma_f32_16x16x32_bf16 v[100:103], v[144:147], v[180:183], v[100:103]
	v_mfma_f32_16x16x32_bf16 v[104:107], v[136:139], v[180:183], v[104:107]
	v_mfma_f32_16x16x32_bf16 v[104:107], v[140:143], v[184:187], v[104:107]
	v_mfma_f32_16x16x32_bf16 v[108:111], v[132:135], v[184:187], v[108:111]
	v_mfma_f32_16x16x32_bf16 v[108:111], v[128:131], v[180:183], v[108:111]
	v_mfma_f32_16x16x32_bf16 v[92:95], v[128:131], v[188:191], v[92:95]
	v_mfma_f32_16x16x32_bf16 v[92:95], v[132:135], v[192:195], v[92:95]
	v_mfma_f32_16x16x32_bf16 v[88:91], v[140:143], v[192:195], v[88:91]
	v_mfma_f32_16x16x32_bf16 v[88:91], v[136:139], v[188:191], v[88:91]
	v_mfma_f32_16x16x32_bf16 v[84:87], v[144:147], v[188:191], v[84:87]
	v_mfma_f32_16x16x32_bf16 v[84:87], v[160:163], v[192:195], v[84:87]
	v_mfma_f32_16x16x32_bf16 v[80:83], v[168:171], v[192:195], v[80:83]
	v_mfma_f32_16x16x32_bf16 v[80:83], v[164:167], v[188:191], v[80:83]
	v_mfma_f32_16x16x32_bf16 v[64:67], v[164:167], v[196:199], v[64:67]
	v_mfma_f32_16x16x32_bf16 v[64:67], v[168:171], v[212:215], v[64:67]
	v_mfma_f32_16x16x32_bf16 v[68:71], v[160:163], v[212:215], v[68:71]
	v_mfma_f32_16x16x32_bf16 v[68:71], v[144:147], v[196:199], v[68:71]
	v_mfma_f32_16x16x32_bf16 v[72:75], v[136:139], v[196:199], v[72:75]
	v_mfma_f32_16x16x32_bf16 v[72:75], v[140:143], v[212:215], v[72:75]
	v_mfma_f32_16x16x32_bf16 v[76:79], v[132:135], v[212:215], v[76:79]
	v_mfma_f32_16x16x32_bf16 v[76:79], v[128:131], v[196:199], v[76:79]
	s_setprio 0
	s_barrier
	s_add_i32 s6, s68, s46
	v_lshl_add_u64 v[200:201], v[200:201], 0, s[20:21]
	s_mov_b32 m0, s6
	ds_read_b128 v[172:175], v207 offset:49152
	ds_read_b128 v[176:179], v207 offset:50176
	ds_read_b128 v[180:183], v207 offset:51200
	ds_read_b128 v[184:187], v207 offset:52224
	ds_read_b128 v[188:191], v207 offset:53248
	ds_read_b128 v[192:195], v207 offset:54272
	ds_read_b128 v[196:199], v207 offset:55296
	ds_read_b128 v[212:215], v207 offset:56320
	global_load_lds_dwordx4 v[200:201], off
	v_lshl_add_u64 v[200:201], v[216:217], 0, s[20:21]
	s_add_i32 m0, s6, 0x2000
	s_add_i32 s6, s69, s46
	global_load_lds_dwordx4 v[200:201], off
	v_lshl_add_u64 v[200:201], v[218:219], 0, s[20:21]
	s_mov_b32 m0, s6
	s_nop 0
	global_load_lds_dwordx4 v[200:201], off
	v_lshl_add_u64 v[200:201], v[220:221], 0, s[20:21]
	s_add_i32 m0, s6, 0x2000
	s_nop 0
	global_load_lds_dwordx4 v[200:201], off
	v_lshl_add_u64 v[200:201], v[222:223], 0, s[20:21]
	s_mov_b32 m0, s54
	s_nop 0
	global_load_lds_dwordx4 v[200:201], off
	v_lshl_add_u64 v[200:201], v[224:225], 0, s[20:21]
	s_mov_b32 m0, s55
	s_nop 0
	global_load_lds_dwordx4 v[200:201], off
	s_waitcnt vmcnt(8)
	s_waitcnt lgkmcnt(0)
	s_barrier
	s_setprio 1
	s_waitcnt lgkmcnt(0)
	v_mfma_f32_16x16x32_bf16 v[60:63], v[128:131], v[172:175], v[60:63]
	v_mfma_f32_16x16x32_bf16 v[60:63], v[132:135], v[176:179], v[60:63]
	v_mfma_f32_16x16x32_bf16 v[56:59], v[140:143], v[176:179], v[56:59]
	v_mfma_f32_16x16x32_bf16 v[56:59], v[136:139], v[172:175], v[56:59]
	v_mfma_f32_16x16x32_bf16 v[52:55], v[144:147], v[172:175], v[52:55]
	v_mfma_f32_16x16x32_bf16 v[52:55], v[160:163], v[176:179], v[52:55]
	v_mfma_f32_16x16x32_bf16 v[48:51], v[168:171], v[176:179], v[48:51]
	v_mfma_f32_16x16x32_bf16 v[48:51], v[164:167], v[172:175], v[48:51]
	v_mfma_f32_16x16x32_bf16 v[32:35], v[164:167], v[180:183], v[32:35]
	v_mfma_f32_16x16x32_bf16 v[32:35], v[168:171], v[184:187], v[32:35]
	v_mfma_f32_16x16x32_bf16 v[36:39], v[160:163], v[184:187], v[36:39]
	v_mfma_f32_16x16x32_bf16 v[36:39], v[144:147], v[180:183], v[36:39]
	v_mfma_f32_16x16x32_bf16 v[40:43], v[136:139], v[180:183], v[40:43]
	v_mfma_f32_16x16x32_bf16 v[40:43], v[140:143], v[184:187], v[40:43]
	v_mfma_f32_16x16x32_bf16 v[44:47], v[132:135], v[184:187], v[44:47]
	v_mfma_f32_16x16x32_bf16 v[44:47], v[128:131], v[180:183], v[44:47]
	v_mfma_f32_16x16x32_bf16 v[28:31], v[128:131], v[188:191], v[28:31]
	v_mfma_f32_16x16x32_bf16 v[28:31], v[132:135], v[192:195], v[28:31]
	v_mfma_f32_16x16x32_bf16 v[24:27], v[140:143], v[192:195], v[24:27]
	v_mfma_f32_16x16x32_bf16 v[24:27], v[136:139], v[188:191], v[24:27]
	v_mfma_f32_16x16x32_bf16 v[20:23], v[144:147], v[188:191], v[20:23]
	v_mfma_f32_16x16x32_bf16 v[20:23], v[160:163], v[192:195], v[20:23]
	v_mfma_f32_16x16x32_bf16 v[16:19], v[168:171], v[192:195], v[16:19]
	v_mfma_f32_16x16x32_bf16 v[16:19], v[164:167], v[188:191], v[16:19]
	v_mfma_f32_16x16x32_bf16 v[0:3], v[164:167], v[196:199], v[0:3]
	v_mfma_f32_16x16x32_bf16 v[0:3], v[168:171], v[212:215], v[0:3]
	v_mfma_f32_16x16x32_bf16 v[4:7], v[160:163], v[212:215], v[4:7]
	v_mfma_f32_16x16x32_bf16 v[4:7], v[144:147], v[196:199], v[4:7]
	v_mfma_f32_16x16x32_bf16 v[8:11], v[136:139], v[196:199], v[8:11]
	v_mfma_f32_16x16x32_bf16 v[8:11], v[140:143], v[212:215], v[8:11]
	v_mfma_f32_16x16x32_bf16 v[12:15], v[132:135], v[212:215], v[12:15]
	v_mfma_f32_16x16x32_bf16 v[12:15], v[128:131], v[196:199], v[12:15]
	s_setprio 0
	s_barrier
	s_add_u32 s0, s0, 0x100
	s_addc_u32 s1, s1, 0
	s_add_u32 s38, s38, 0x100
	s_addc_u32 s39, s39, 0
	s_cmp_ge_i32 s41, s56
	s_mov_b32 s6, s41
	s_cbranch_scc0 .LBB0_1159
